# all K-loops: the two MFMAs of each accumulator (k=0,1 of a K-tile) issued back to back, B fragment held across the 4 row blocks
# speedup vs baseline: 1.0166x; 1.0156x over previous
; #define PG8_STAGE(bufoff, gbase, voff) do { _Pragma("unroll") for (int _i = 0; _i < 2; ++_i) \
;         __builtin_amdgcn_global_load_lds((const unsigned*)((const char*)(gbase) + (voff)[_i]), (PG8_LAS unsigned*)(lds + (bufoff) + ldsw + _i * 8192), 16, 0, 0); } while (0)
; #define PG8_LDA(dst, b, h) do { _Pragma("unroll") for (int m = 0; m < 4; ++m) _Pragma("unroll") for (int k = 0; k < 2; ++k) dst[m][k] = *(const PG8_LAS bf16x8*)(lds + PG8_SA(b, h) + aoff + m * 2048 + k * 1024); } while (0)
; #define PG8_LDB(dst, b, h) do { _Pragma("unroll") for (int n = 0; n < 2; ++n) _Pragma("unroll") for (int k = 0; k < 2; ++k) dst[n][k] = *(const PG8_LAS bf16x8*)(lds + PG8_SB(b, h) + boff + n * 2048 + k * 1024); } while (0)
; #define PG8_MMA(ai, bj, At, Bt) do { __builtin_amdgcn_s_setprio(1); _Pragma("unroll") for (int m = 0; m < 4; ++m) _Pragma("unroll") for (int n = 0; n < 2; ++n) _Pragma("unroll") for (int k = 0; k < 2; ++k) \
;         acc[ai][bj][m][n] = __builtin_amdgcn_mfma_f32_16x16x32_bf16(Bt[n][k], At[m][k], acc[ai][bj][m][n], 0, 0, 0); __builtin_amdgcn_s_setprio(0); } while (0)
; #define PG8_WAIT_V(n) asm volatile("s_waitcnt vmcnt(" #n ")" ::: "memory")
; #define PG8_WAIT_L(n) asm volatile("s_waitcnt lgkmcnt(" #n ")" ::: "memory")
;     ...
;         const char* nA = has_next ? (const char*)gA + (size_t)nxt.pm * tstepA + (size_t)nxt.pn * acolB : cA; const char* nB = has_next ? (const char*)gB + (size_t)nxt.pn * tstepB : cB;
;         for (int t = 0; t < nt; t += 2) {
;             const bool last = (t == nt - 2);
;             const char* a1 = cA + (size_t)(t + 1) * kstep;
;             const char* a2 = last ? nA : cA + (size_t)(t + 2) * kstep; const char* b2 = last ? nB : cB + (size_t)(t + 2) * kstep;
;             const char* a3 = a2 + kstep; const char* b3 = b2 + kstep;
;             if (last && has_next) S.a_ready(nxt);
;             if constexpr (SP2) {
;             PG8_LDB(B0, 0, 0); PG8_LDB(B1, 0, 1); PG8_SCHED; PG8_LDA(At, 0, 0); PG8_STAGE(PG8_SA(1, 1), a1 + hstepA, voffA);
;             PG8_WAIT_V(8); PG8_WAIT_L(0); PG8_BAR; PG8_MMA(0, 0, At, B0); PG8_MMA(0, 1, At, B1); PG8_BAR; PG8_SCHED;
;             PG8_LDA(At, 0, 1); PG8_STAGE(PG8_SB(0, 0), b2, voffB); PG8_STAGE(PG8_SB(0, 1), b2 + hstepB, voffB); PG8_STAGE(PG8_SA(0, 0), a2, voffA);
;             PG8_WAIT_V(8); PG8_WAIT_L(0); PG8_BAR; PG8_MMA(1, 0, At, B0); PG8_MMA(1, 1, At, B1); PG8_BAR; PG8_SCHED;
.LBB0_127:
	s_ashr_i32 s91, s90, 31
	s_lshl_b64 s[10:11], s[90:91], 19
	s_add_u32 s22, s44, s10
	s_addc_u32 s23, s45, s11
	s_lshl_b64 s[10:11], s[88:89], 9
	s_add_u32 s94, s22, s10
	s_addc_u32 s95, s23, s11
	s_andn2_b64 vcc, exec, s[72:73]
	s_cbranch_vccnz .LBB0_130
	s_and_b64 s[10:11], s[40:41], exec
	s_cselect_b32 s10, s95, s9
	s_cselect_b32 s11, s94, s8
	s_add_u32 s22, s6, 0x100
	s_addc_u32 s23, s7, 0
	s_add_u32 s6, s8, 0x40080
	s_addc_u32 s7, s9, 0
	s_mov_b32 s8, 0
	s_add_i32 s24, s8, 2
	s_add_u32 s25, s6, 0xfffc0080
	s_addc_u32 s9, s7, -1
	s_add_i32 s27, 0, 0x10000
	s_cmp_eq_u32 s18, s8
	s_cselect_b32 s9, s10, s9
	s_cselect_b32 s8, s11, s25
	v_add_u32_e32 v152, s27, v159
	s_cselect_b32 s35, s93, s23
	s_cselect_b32 s34, s92, s22
	s_add_i32 s25, 0, 0x14000
	ds_read_b128 v[144:147], v152
	ds_read_b128 v[148:151], v152 offset:1024
	ds_read_b128 v[154:157], v152 offset:2048
	ds_read_b128 v[160:163], v152 offset:3072
	v_add_u32_e32 v152, s25, v159
	ds_read_b128 v[172:175], v152
	ds_read_b128 v[180:183], v152 offset:1024
	ds_read_b128 v[184:187], v152 offset:2048
	ds_read_b128 v[188:191], v152 offset:3072
	v_lshl_add_u64 v[164:165], s[6:7], 0, v[142:143]
	s_add_i32 m0, s2, 0xc000
	ds_read_b128 v[192:195], v179
	ds_read_b128 v[196:199], v179 offset:1024
	ds_read_b128 v[200:203], v179 offset:2048
	ds_read_b128 v[204:207], v179 offset:3072
	ds_read_b128 v[208:211], v179 offset:4096
	ds_read_b128 v[212:215], v179 offset:5120
	ds_read_b128 v[216:219], v179 offset:6144
	ds_read_b128 v[220:223], v179 offset:7168
	global_load_lds_dwordx4 v[164:165], off
	v_lshl_add_u64 v[164:165], s[6:7], 0, v[140:141]
	s_add_i32 m0, s2, 0xe000
	s_nop 0
	global_load_lds_dwordx4 v[164:165], off
	s_waitcnt vmcnt(8)
	s_waitcnt lgkmcnt(0)
	s_barrier
	s_waitcnt lgkmcnt(0)
	v_mfma_f32_16x16x32_bf16 v[126:129], v[144:147], v[192:195], 0
	v_mfma_f32_16x16x32_bf16 v[126:129], v[148:151], v[196:199], v[126:129]
	v_mfma_f32_16x16x32_bf16 v[110:113], v[144:147], v[200:203], 0
	v_mfma_f32_16x16x32_bf16 v[110:113], v[148:151], v[204:207], v[110:113]
	v_mfma_f32_16x16x32_bf16 v[94:97], v[144:147], v[208:211], 0
	v_mfma_f32_16x16x32_bf16 v[94:97], v[148:151], v[212:215], v[94:97]
	v_mfma_f32_16x16x32_bf16 v[78:81], v[144:147], v[216:219], 0
	v_mfma_f32_16x16x32_bf16 v[78:81], v[148:151], v[220:223], v[78:81]
	v_mfma_f32_16x16x32_bf16 v[122:125], v[154:157], v[192:195], 0
	v_mfma_f32_16x16x32_bf16 v[122:125], v[160:163], v[196:199], v[122:125]
	v_mfma_f32_16x16x32_bf16 v[106:109], v[154:157], v[200:203], 0
	v_mfma_f32_16x16x32_bf16 v[106:109], v[160:163], v[204:207], v[106:109]
	v_mfma_f32_16x16x32_bf16 v[90:93], v[154:157], v[208:211], 0
	v_mfma_f32_16x16x32_bf16 v[90:93], v[160:163], v[212:215], v[90:93]
	v_mfma_f32_16x16x32_bf16 v[74:77], v[154:157], v[216:219], 0
	v_mfma_f32_16x16x32_bf16 v[74:77], v[160:163], v[220:223], v[74:77]
	s_barrier
	s_add_i32 s27, s27, s0
	v_lshl_add_u64 v[164:165], s[34:35], 0, v[134:135]
	s_mov_b32 m0, s27
	ds_read_b128 v[192:195], v179 offset:16384
	ds_read_b128 v[196:199], v179 offset:17408
	ds_read_b128 v[200:203], v179 offset:18432
	ds_read_b128 v[204:207], v179 offset:19456
	ds_read_b128 v[208:211], v179 offset:20480
	ds_read_b128 v[212:215], v179 offset:21504
	ds_read_b128 v[216:219], v179 offset:22528
	ds_read_b128 v[220:223], v179 offset:23552
	global_load_lds_dwordx4 v[164:165], off
	s_add_i32 m0, s27, 0x2000
	v_lshl_add_u64 v[168:169], s[34:35], 0, v[130:131]
	s_add_u32 s34, s34, s42
	s_addc_u32 s35, s35, s43
	s_add_i32 s25, s25, s0
	global_load_lds_dwordx4 v[168:169], off
	v_lshl_add_u64 v[170:171], s[34:35], 0, v[134:135]
	s_mov_b32 m0, s25
	v_lshl_add_u64 v[176:177], s[34:35], 0, v[130:131]
	global_load_lds_dwordx4 v[170:171], off
	s_add_i32 m0, s25, 0x2000
	v_lshl_add_u64 v[224:225], s[8:9], 0, v[136:137]
	global_load_lds_dwordx4 v[176:177], off
	s_mov_b32 m0, s2
	v_lshl_add_u64 v[226:227], s[8:9], 0, v[132:133]
	global_load_lds_dwordx4 v[224:225], off
	s_mov_b32 m0, s3
	s_nop 0
	global_load_lds_dwordx4 v[226:227], off
	s_waitcnt vmcnt(8)
	s_waitcnt lgkmcnt(0)
	s_barrier
	s_waitcnt lgkmcnt(0)
	v_mfma_f32_16x16x32_bf16 v[62:65], v[144:147], v[192:195], 0
	v_mfma_f32_16x16x32_bf16 v[62:65], v[148:151], v[196:199], v[62:65]
	v_mfma_f32_16x16x32_bf16 v[46:49], v[144:147], v[200:203], 0
	v_mfma_f32_16x16x32_bf16 v[46:49], v[148:151], v[204:207], v[46:49]
	v_mfma_f32_16x16x32_bf16 v[30:33], v[144:147], v[208:211], 0
	v_mfma_f32_16x16x32_bf16 v[30:33], v[148:151], v[212:215], v[30:33]
	v_mfma_f32_16x16x32_bf16 v[14:17], v[144:147], v[216:219], 0
	v_mfma_f32_16x16x32_bf16 v[14:17], v[148:151], v[220:223], v[14:17]
	v_mfma_f32_16x16x32_bf16 v[58:61], v[154:157], v[192:195], 0
	v_mfma_f32_16x16x32_bf16 v[58:61], v[160:163], v[196:199], v[58:61]
	v_mfma_f32_16x16x32_bf16 v[42:45], v[154:157], v[200:203], 0
	v_mfma_f32_16x16x32_bf16 v[42:45], v[160:163], v[204:207], v[42:45]
	v_mfma_f32_16x16x32_bf16 v[26:29], v[154:157], v[208:211], 0
	v_mfma_f32_16x16x32_bf16 v[26:29], v[160:163], v[212:215], v[26:29]
	v_mfma_f32_16x16x32_bf16 v[10:13], v[154:157], v[216:219], 0
	v_mfma_f32_16x16x32_bf16 v[10:13], v[160:163], v[220:223], v[10:13]
	s_barrier
; #define PG8_STAGE(bufoff, gbase, voff) do { _Pragma("unroll") for (int _i = 0; _i < 2; ++_i) \
;         __builtin_amdgcn_global_load_lds((const unsigned*)((const char*)(gbase) + (voff)[_i]), (PG8_LAS unsigned*)(lds + (bufoff) + ldsw + _i * 8192), 16, 0, 0); } while (0)
; #define PG8_LDA(dst, b, h) do { _Pragma("unroll") for (int m = 0; m < 4; ++m) _Pragma("unroll") for (int k = 0; k < 2; ++k) dst[m][k] = *(const PG8_LAS bf16x8*)(lds + PG8_SA(b, h) + aoff + m * 2048 + k * 1024); } while (0)
; #define PG8_LDB(dst, b, h) do { _Pragma("unroll") for (int n = 0; n < 2; ++n) _Pragma("unroll") for (int k = 0; k < 2; ++k) dst[n][k] = *(const PG8_LAS bf16x8*)(lds + PG8_SB(b, h) + boff + n * 2048 + k * 1024); } while (0)
; #define PG8_MMA(ai, bj, At, Bt) do { __builtin_amdgcn_s_setprio(1); _Pragma("unroll") for (int m = 0; m < 4; ++m) _Pragma("unroll") for (int n = 0; n < 2; ++n) _Pragma("unroll") for (int k = 0; k < 2; ++k) \
;         acc[ai][bj][m][n] = __builtin_amdgcn_mfma_f32_16x16x32_bf16(Bt[n][k], At[m][k], acc[ai][bj][m][n], 0, 0, 0); __builtin_amdgcn_s_setprio(0); } while (0)
; #define PG8_WAIT_V(n) asm volatile("s_waitcnt vmcnt(" #n ")" ::: "memory")
; #define PG8_WAIT_L(n) asm volatile("s_waitcnt lgkmcnt(" #n ")" ::: "memory")
; #define PG8_BAR __builtin_amdgcn_s_barrier()
; #define PG8_SCHED __builtin_amdgcn_sched_barrier(0)
;     ...
;             PG8_LDB(B0, 1, 0); PG8_LDB(B1, 1, 1); PG8_SCHED; PG8_LDA(At, 1, 0); PG8_STAGE(PG8_SA(0, 1), a2 + hstepA, voffA);
;             PG8_WAIT_V(8); PG8_WAIT_L(0); PG8_BAR; PG8_MMA(0, 0, At, B0); PG8_MMA(0, 1, At, B1); PG8_BAR; PG8_SCHED;
;             PG8_LDA(At, 1, 1); PG8_STAGE(PG8_SB(1, 0), b3, voffB); PG8_STAGE(PG8_SB(1, 1), b3 + hstepB, voffB); PG8_STAGE(PG8_SA(1, 0), a3, voffA);
;             PG8_WAIT_V(8); PG8_WAIT_L(0); PG8_BAR; PG8_MMA(1, 0, At, B0); PG8_MMA(1, 1, At, B1); PG8_BAR; PG8_SCHED;
	s_add_i32 s25, 0, 0x18000
	v_add_u32_e32 v152, s25, v159
	s_add_i32 s27, 0, 0x1c000
	ds_read_b128 v[144:147], v152
	ds_read_b128 v[148:151], v152 offset:1024
	ds_read_b128 v[154:157], v152 offset:2048
	ds_read_b128 v[160:163], v152 offset:3072
	v_add_u32_e32 v152, s27, v159
	ds_read_b128 v[172:175], v152
	ds_read_b128 v[180:183], v152 offset:1024
	ds_read_b128 v[184:187], v152 offset:2048
	ds_read_b128 v[188:191], v152 offset:3072
	s_add_u32 s8, s8, 0x40000
	s_addc_u32 s9, s9, 0
	s_mov_b32 m0, s12
	v_lshl_add_u64 v[228:229], s[8:9], 0, v[136:137]
	ds_read_b128 v[192:195], v179 offset:32768
	ds_read_b128 v[196:199], v179 offset:33792
	ds_read_b128 v[200:203], v179 offset:34816
	ds_read_b128 v[204:207], v179 offset:35840
	ds_read_b128 v[208:211], v179 offset:36864
	ds_read_b128 v[212:215], v179 offset:37888
	ds_read_b128 v[216:219], v179 offset:38912
	ds_read_b128 v[220:223], v179 offset:39936
	global_load_lds_dwordx4 v[228:229], off
	v_lshl_add_u64 v[228:229], s[8:9], 0, v[132:133]
	s_mov_b32 m0, s13
	s_nop 0
	global_load_lds_dwordx4 v[228:229], off
	s_waitcnt vmcnt(8)
	s_waitcnt lgkmcnt(0)
	s_barrier
	s_waitcnt lgkmcnt(0)
	v_mfma_f32_16x16x32_bf16 v[126:129], v[144:147], v[192:195], v[126:129]
	v_mfma_f32_16x16x32_bf16 v[126:129], v[148:151], v[196:199], v[126:129]
	v_mfma_f32_16x16x32_bf16 v[110:113], v[144:147], v[200:203], v[110:113]
	v_mfma_f32_16x16x32_bf16 v[110:113], v[148:151], v[204:207], v[110:113]
	v_mfma_f32_16x16x32_bf16 v[94:97], v[144:147], v[208:211], v[94:97]
	v_mfma_f32_16x16x32_bf16 v[94:97], v[148:151], v[212:215], v[94:97]
	v_mfma_f32_16x16x32_bf16 v[78:81], v[144:147], v[216:219], v[78:81]
	v_mfma_f32_16x16x32_bf16 v[78:81], v[148:151], v[220:223], v[78:81]
	v_mfma_f32_16x16x32_bf16 v[122:125], v[154:157], v[192:195], v[122:125]
	v_mfma_f32_16x16x32_bf16 v[122:125], v[160:163], v[196:199], v[122:125]
	v_mfma_f32_16x16x32_bf16 v[106:109], v[154:157], v[200:203], v[106:109]
	v_mfma_f32_16x16x32_bf16 v[106:109], v[160:163], v[204:207], v[106:109]
	v_mfma_f32_16x16x32_bf16 v[90:93], v[154:157], v[208:211], v[90:93]
	v_mfma_f32_16x16x32_bf16 v[90:93], v[160:163], v[212:215], v[90:93]
	v_mfma_f32_16x16x32_bf16 v[74:77], v[154:157], v[216:219], v[74:77]
	v_mfma_f32_16x16x32_bf16 v[74:77], v[160:163], v[220:223], v[74:77]
	s_barrier
	s_add_i32 s8, s25, s0
	v_lshl_add_u64 v[164:165], v[164:165], 0, s[62:63]
	s_mov_b32 m0, s8
	ds_read_b128 v[192:195], v179 offset:49152
	ds_read_b128 v[196:199], v179 offset:50176
	ds_read_b128 v[200:203], v179 offset:51200
	ds_read_b128 v[204:207], v179 offset:52224
	ds_read_b128 v[208:211], v179 offset:53248
	ds_read_b128 v[212:215], v179 offset:54272
	ds_read_b128 v[216:219], v179 offset:55296
	ds_read_b128 v[220:223], v179 offset:56320
	global_load_lds_dwordx4 v[164:165], off
	v_lshl_add_u64 v[164:165], v[168:169], 0, s[62:63]
	s_add_i32 m0, s8, 0x2000
	s_add_i32 s8, s27, s0
	global_load_lds_dwordx4 v[164:165], off
	v_lshl_add_u64 v[164:165], v[170:171], 0, s[62:63]
	s_mov_b32 m0, s8
	s_nop 0
	global_load_lds_dwordx4 v[164:165], off
	v_lshl_add_u64 v[164:165], v[176:177], 0, s[62:63]
	s_add_i32 m0, s8, 0x2000
	s_nop 0
	global_load_lds_dwordx4 v[164:165], off
	v_lshl_add_u64 v[164:165], v[224:225], 0, s[62:63]
	s_mov_b32 m0, s16
	s_nop 0
	global_load_lds_dwordx4 v[164:165], off
	v_lshl_add_u64 v[164:165], v[226:227], 0, s[62:63]
	s_mov_b32 m0, s17
	s_nop 0
	global_load_lds_dwordx4 v[164:165], off
	s_waitcnt vmcnt(8)
	s_waitcnt lgkmcnt(0)
	s_barrier
	s_waitcnt lgkmcnt(0)
	v_mfma_f32_16x16x32_bf16 v[62:65], v[144:147], v[192:195], v[62:65]
	v_mfma_f32_16x16x32_bf16 v[62:65], v[148:151], v[196:199], v[62:65]
	v_mfma_f32_16x16x32_bf16 v[46:49], v[144:147], v[200:203], v[46:49]
	v_mfma_f32_16x16x32_bf16 v[46:49], v[148:151], v[204:207], v[46:49]
	v_mfma_f32_16x16x32_bf16 v[30:33], v[144:147], v[208:211], v[30:33]
	v_mfma_f32_16x16x32_bf16 v[30:33], v[148:151], v[212:215], v[30:33]
	v_mfma_f32_16x16x32_bf16 v[14:17], v[144:147], v[216:219], v[14:17]
	v_mfma_f32_16x16x32_bf16 v[14:17], v[148:151], v[220:223], v[14:17]
	v_mfma_f32_16x16x32_bf16 v[58:61], v[154:157], v[192:195], v[58:61]
	v_mfma_f32_16x16x32_bf16 v[58:61], v[160:163], v[196:199], v[58:61]
	v_mfma_f32_16x16x32_bf16 v[42:45], v[154:157], v[200:203], v[42:45]
	v_mfma_f32_16x16x32_bf16 v[42:45], v[160:163], v[204:207], v[42:45]
	v_mfma_f32_16x16x32_bf16 v[26:29], v[154:157], v[208:211], v[26:29]
	v_mfma_f32_16x16x32_bf16 v[26:29], v[160:163], v[212:215], v[26:29]
	v_mfma_f32_16x16x32_bf16 v[10:13], v[154:157], v[216:219], v[10:13]
	v_mfma_f32_16x16x32_bf16 v[10:13], v[160:163], v[220:223], v[10:13]
	s_barrier
	s_add_u32 s22, s22, 0x100
	s_addc_u32 s23, s23, 0
	s_add_u32 s6, s6, 0x100
	s_addc_u32 s7, s7, 0
	s_cmp_ge_i32 s24, s14
	s_mov_b32 s8, s24
	s_cbranch_scc1 .LBB0_130
; #define PG8_STAGE(bufoff, gbase, voff) do { _Pragma("unroll") for (int _i = 0; _i < 2; ++_i) \
;         __builtin_amdgcn_global_load_lds((const unsigned*)((const char*)(gbase) + (voff)[_i]), (PG8_LAS unsigned*)(lds + (bufoff) + ldsw + _i * 8192), 16, 0, 0); } while (0)
; #define PG8_LDA(dst, b, h) do { _Pragma("unroll") for (int m = 0; m < 4; ++m) _Pragma("unroll") for (int k = 0; k < 2; ++k) dst[m][k] = *(const PG8_LAS bf16x8*)(lds + PG8_SA(b, h) + aoff + m * 2048 + k * 1024); } while (0)
; #define PG8_LDB(dst, b, h) do { _Pragma("unroll") for (int n = 0; n < 2; ++n) _Pragma("unroll") for (int k = 0; k < 2; ++k) dst[n][k] = *(const PG8_LAS bf16x8*)(lds + PG8_SB(b, h) + boff + n * 2048 + k * 1024); } while (0)
; #define PG8_MMA(ai, bj, At, Bt) do { __builtin_amdgcn_s_setprio(1); _Pragma("unroll") for (int m = 0; m < 4; ++m) _Pragma("unroll") for (int n = 0; n < 2; ++n) _Pragma("unroll") for (int k = 0; k < 2; ++k) \
;         acc[ai][bj][m][n] = __builtin_amdgcn_mfma_f32_16x16x32_bf16(Bt[n][k], At[m][k], acc[ai][bj][m][n], 0, 0, 0); __builtin_amdgcn_s_setprio(0); } while (0)
; #define PG8_WAIT_V(n) asm volatile("s_waitcnt vmcnt(" #n ")" ::: "memory")
; #define PG8_WAIT_L(n) asm volatile("s_waitcnt lgkmcnt(" #n ")" ::: "memory")
; #define PG8_BAR __builtin_amdgcn_s_barrier()
; #define PG8_SCHED __builtin_amdgcn_sched_barrier(0)
;     ...
;             const char* a1 = cA + (size_t)(t + 1) * kstep;
;             const char* a2 = last ? nA : cA + (size_t)(t + 2) * kstep; const char* b2 = last ? nB : cB + (size_t)(t + 2) * kstep;
;             const char* a3 = a2 + kstep; const char* b3 = b2 + kstep;
;             if (last && has_next) S.a_ready(nxt);
;             if constexpr (SP2) {
;             PG8_LDB(B0, 0, 0); PG8_LDB(B1, 0, 1); PG8_SCHED; PG8_LDA(At, 0, 0); PG8_STAGE(PG8_SA(1, 1), a1 + hstepA, voffA);
;             PG8_WAIT_V(8); PG8_WAIT_L(0); PG8_BAR; PG8_MMA(0, 0, At, B0); PG8_MMA(0, 1, At, B1); PG8_BAR; PG8_SCHED;
;             PG8_LDA(At, 0, 1); PG8_STAGE(PG8_SB(0, 0), b2, voffB); PG8_STAGE(PG8_SB(0, 1), b2 + hstepB, voffB); PG8_STAGE(PG8_SA(0, 0), a2, voffA);
;             PG8_WAIT_V(8); PG8_WAIT_L(0); PG8_BAR; PG8_MMA(1, 0, At, B0); PG8_MMA(1, 1, At, B1); PG8_BAR; PG8_SCHED;
.LBB0_129:
	s_add_i32 s24, s8, 2
	s_add_u32 s25, s6, 0xfffc0080
	s_addc_u32 s9, s7, -1
	s_add_i32 s27, 0, 0x10000
	s_cmp_eq_u32 s18, s8
	s_cselect_b32 s9, s10, s9
	s_cselect_b32 s8, s11, s25
	v_add_u32_e32 v152, s27, v159
	s_cselect_b32 s35, s93, s23
	s_cselect_b32 s34, s92, s22
	s_add_i32 s25, 0, 0x14000
	ds_read_b128 v[144:147], v152
	ds_read_b128 v[148:151], v152 offset:1024
	ds_read_b128 v[154:157], v152 offset:2048
	ds_read_b128 v[160:163], v152 offset:3072
	v_add_u32_e32 v152, s25, v159
	ds_read_b128 v[172:175], v152
	ds_read_b128 v[180:183], v152 offset:1024
	ds_read_b128 v[184:187], v152 offset:2048
	ds_read_b128 v[188:191], v152 offset:3072
	v_lshl_add_u64 v[164:165], s[6:7], 0, v[142:143]
	s_add_i32 m0, s2, 0xc000
	ds_read_b128 v[192:195], v179
	ds_read_b128 v[196:199], v179 offset:1024
	ds_read_b128 v[200:203], v179 offset:2048
	ds_read_b128 v[204:207], v179 offset:3072
	ds_read_b128 v[208:211], v179 offset:4096
	ds_read_b128 v[212:215], v179 offset:5120
	ds_read_b128 v[216:219], v179 offset:6144
	ds_read_b128 v[220:223], v179 offset:7168
	global_load_lds_dwordx4 v[164:165], off
	v_lshl_add_u64 v[164:165], s[6:7], 0, v[140:141]
	s_add_i32 m0, s2, 0xe000
	s_nop 0
	global_load_lds_dwordx4 v[164:165], off
	s_waitcnt vmcnt(8)
	s_waitcnt lgkmcnt(0)
	s_barrier
	s_waitcnt lgkmcnt(0)
	v_mfma_f32_16x16x32_bf16 v[118:121], v[172:175], v[192:195], 0
	v_mfma_f32_16x16x32_bf16 v[118:121], v[180:183], v[196:199], v[118:121]
	v_mfma_f32_16x16x32_bf16 v[102:105], v[172:175], v[200:203], 0
	v_mfma_f32_16x16x32_bf16 v[102:105], v[180:183], v[204:207], v[102:105]
	v_mfma_f32_16x16x32_bf16 v[86:89], v[172:175], v[208:211], 0
	v_mfma_f32_16x16x32_bf16 v[86:89], v[180:183], v[212:215], v[86:89]
	v_mfma_f32_16x16x32_bf16 v[70:73], v[172:175], v[216:219], 0
	v_mfma_f32_16x16x32_bf16 v[70:73], v[180:183], v[220:223], v[70:73]
	v_mfma_f32_16x16x32_bf16 v[114:117], v[184:187], v[192:195], 0
	v_mfma_f32_16x16x32_bf16 v[114:117], v[188:191], v[196:199], v[114:117]
	v_mfma_f32_16x16x32_bf16 v[98:101], v[184:187], v[200:203], 0
	v_mfma_f32_16x16x32_bf16 v[98:101], v[188:191], v[204:207], v[98:101]
	v_mfma_f32_16x16x32_bf16 v[82:85], v[184:187], v[208:211], 0
	v_mfma_f32_16x16x32_bf16 v[82:85], v[188:191], v[212:215], v[82:85]
	v_mfma_f32_16x16x32_bf16 v[66:69], v[184:187], v[216:219], 0
	v_mfma_f32_16x16x32_bf16 v[66:69], v[188:191], v[220:223], v[66:69]
	s_barrier
	s_add_i32 s27, s27, s0
	v_lshl_add_u64 v[164:165], s[34:35], 0, v[134:135]
	s_mov_b32 m0, s27
	ds_read_b128 v[192:195], v179 offset:16384
	ds_read_b128 v[196:199], v179 offset:17408
	ds_read_b128 v[200:203], v179 offset:18432
	ds_read_b128 v[204:207], v179 offset:19456
	ds_read_b128 v[208:211], v179 offset:20480
	ds_read_b128 v[212:215], v179 offset:21504
	ds_read_b128 v[216:219], v179 offset:22528
	ds_read_b128 v[220:223], v179 offset:23552
	global_load_lds_dwordx4 v[164:165], off
	s_add_i32 m0, s27, 0x2000
	v_lshl_add_u64 v[168:169], s[34:35], 0, v[130:131]
	s_add_u32 s34, s34, s42
	s_addc_u32 s35, s35, s43
	s_add_i32 s25, s25, s0
	global_load_lds_dwordx4 v[168:169], off
	v_lshl_add_u64 v[170:171], s[34:35], 0, v[134:135]
	s_mov_b32 m0, s25
	v_lshl_add_u64 v[176:177], s[34:35], 0, v[130:131]
	global_load_lds_dwordx4 v[170:171], off
	s_add_i32 m0, s25, 0x2000
	v_lshl_add_u64 v[224:225], s[8:9], 0, v[136:137]
	global_load_lds_dwordx4 v[176:177], off
	s_mov_b32 m0, s2
	v_lshl_add_u64 v[226:227], s[8:9], 0, v[132:133]
	global_load_lds_dwordx4 v[224:225], off
	s_mov_b32 m0, s3
	s_nop 0
	global_load_lds_dwordx4 v[226:227], off
	s_waitcnt vmcnt(8)
	s_waitcnt lgkmcnt(0)
	s_barrier
	s_waitcnt lgkmcnt(0)
	v_mfma_f32_16x16x32_bf16 v[54:57], v[172:175], v[192:195], 0
	v_mfma_f32_16x16x32_bf16 v[54:57], v[180:183], v[196:199], v[54:57]
	v_mfma_f32_16x16x32_bf16 v[38:41], v[172:175], v[200:203], 0
	v_mfma_f32_16x16x32_bf16 v[38:41], v[180:183], v[204:207], v[38:41]
	v_mfma_f32_16x16x32_bf16 v[22:25], v[172:175], v[208:211], 0
	v_mfma_f32_16x16x32_bf16 v[22:25], v[180:183], v[212:215], v[22:25]
	v_mfma_f32_16x16x32_bf16 v[6:9], v[172:175], v[216:219], 0
	v_mfma_f32_16x16x32_bf16 v[6:9], v[180:183], v[220:223], v[6:9]
	v_mfma_f32_16x16x32_bf16 v[50:53], v[184:187], v[192:195], 0
	v_mfma_f32_16x16x32_bf16 v[50:53], v[188:191], v[196:199], v[50:53]
	v_mfma_f32_16x16x32_bf16 v[34:37], v[184:187], v[200:203], 0
	v_mfma_f32_16x16x32_bf16 v[34:37], v[188:191], v[204:207], v[34:37]
	v_mfma_f32_16x16x32_bf16 v[18:21], v[184:187], v[208:211], 0
	v_mfma_f32_16x16x32_bf16 v[18:21], v[188:191], v[212:215], v[18:21]
	v_mfma_f32_16x16x32_bf16 v[2:5], v[184:187], v[216:219], 0
	v_mfma_f32_16x16x32_bf16 v[2:5], v[188:191], v[220:223], v[2:5]
	s_barrier
; #define PG8_STAGE(bufoff, gbase, voff) do { _Pragma("unroll") for (int _i = 0; _i < 2; ++_i) \
;         __builtin_amdgcn_global_load_lds((const unsigned*)((const char*)(gbase) + (voff)[_i]), (PG8_LAS unsigned*)(lds + (bufoff) + ldsw + _i * 8192), 16, 0, 0); } while (0)
; #define PG8_LDA(dst, b, h) do { _Pragma("unroll") for (int m = 0; m < 4; ++m) _Pragma("unroll") for (int k = 0; k < 2; ++k) dst[m][k] = *(const PG8_LAS bf16x8*)(lds + PG8_SA(b, h) + aoff + m * 2048 + k * 1024); } while (0)
; #define PG8_LDB(dst, b, h) do { _Pragma("unroll") for (int n = 0; n < 2; ++n) _Pragma("unroll") for (int k = 0; k < 2; ++k) dst[n][k] = *(const PG8_LAS bf16x8*)(lds + PG8_SB(b, h) + boff + n * 2048 + k * 1024); } while (0)
; #define PG8_MMA(ai, bj, At, Bt) do { __builtin_amdgcn_s_setprio(1); _Pragma("unroll") for (int m = 0; m < 4; ++m) _Pragma("unroll") for (int n = 0; n < 2; ++n) _Pragma("unroll") for (int k = 0; k < 2; ++k) \
;         acc[ai][bj][m][n] = __builtin_amdgcn_mfma_f32_16x16x32_bf16(Bt[n][k], At[m][k], acc[ai][bj][m][n], 0, 0, 0); __builtin_amdgcn_s_setprio(0); } while (0)
; #define PG8_WAIT_V(n) asm volatile("s_waitcnt vmcnt(" #n ")" ::: "memory")
; #define PG8_WAIT_L(n) asm volatile("s_waitcnt lgkmcnt(" #n ")" ::: "memory")
; #define PG8_BAR __builtin_amdgcn_s_barrier()
; #define PG8_SCHED __builtin_amdgcn_sched_barrier(0)
;     ...
;         for (int t = 0; t < nt; t += 2) {
;     ...
;             PG8_LDB(B0, 1, 0); PG8_LDB(B1, 1, 1); PG8_SCHED; PG8_LDA(At, 1, 0); PG8_STAGE(PG8_SA(0, 1), a2 + hstepA, voffA);
;             PG8_WAIT_V(8); PG8_WAIT_L(0); PG8_BAR; PG8_MMA(0, 0, At, B0); PG8_MMA(0, 1, At, B1); PG8_BAR; PG8_SCHED;
;             PG8_LDA(At, 1, 1); PG8_STAGE(PG8_SB(1, 0), b3, voffB); PG8_STAGE(PG8_SB(1, 1), b3 + hstepB, voffB); PG8_STAGE(PG8_SA(1, 0), a3, voffA);
;             PG8_WAIT_V(8); PG8_WAIT_L(0); PG8_BAR; PG8_MMA(1, 0, At, B0); PG8_MMA(1, 1, At, B1); PG8_BAR; PG8_SCHED;
	s_add_i32 s25, 0, 0x18000
	v_add_u32_e32 v152, s25, v159
	s_add_i32 s27, 0, 0x1c000
	ds_read_b128 v[144:147], v152
	ds_read_b128 v[148:151], v152 offset:1024
	ds_read_b128 v[154:157], v152 offset:2048
	ds_read_b128 v[160:163], v152 offset:3072
	v_add_u32_e32 v152, s27, v159
	ds_read_b128 v[172:175], v152
	ds_read_b128 v[180:183], v152 offset:1024
	ds_read_b128 v[184:187], v152 offset:2048
	ds_read_b128 v[188:191], v152 offset:3072
	s_add_u32 s8, s8, 0x40000
	s_addc_u32 s9, s9, 0
	s_mov_b32 m0, s12
	v_lshl_add_u64 v[228:229], s[8:9], 0, v[136:137]
	ds_read_b128 v[192:195], v179 offset:32768
	ds_read_b128 v[196:199], v179 offset:33792
	ds_read_b128 v[200:203], v179 offset:34816
	ds_read_b128 v[204:207], v179 offset:35840
	ds_read_b128 v[208:211], v179 offset:36864
	ds_read_b128 v[212:215], v179 offset:37888
	ds_read_b128 v[216:219], v179 offset:38912
	ds_read_b128 v[220:223], v179 offset:39936
	global_load_lds_dwordx4 v[228:229], off
	v_lshl_add_u64 v[228:229], s[8:9], 0, v[132:133]
	s_mov_b32 m0, s13
	s_nop 0
	global_load_lds_dwordx4 v[228:229], off
	s_waitcnt vmcnt(8)
	s_waitcnt lgkmcnt(0)
	s_barrier
	s_waitcnt lgkmcnt(0)
	v_mfma_f32_16x16x32_bf16 v[118:121], v[172:175], v[192:195], v[118:121]
	v_mfma_f32_16x16x32_bf16 v[118:121], v[180:183], v[196:199], v[118:121]
	v_mfma_f32_16x16x32_bf16 v[102:105], v[172:175], v[200:203], v[102:105]
	v_mfma_f32_16x16x32_bf16 v[102:105], v[180:183], v[204:207], v[102:105]
	v_mfma_f32_16x16x32_bf16 v[86:89], v[172:175], v[208:211], v[86:89]
	v_mfma_f32_16x16x32_bf16 v[86:89], v[180:183], v[212:215], v[86:89]
	v_mfma_f32_16x16x32_bf16 v[70:73], v[172:175], v[216:219], v[70:73]
	v_mfma_f32_16x16x32_bf16 v[70:73], v[180:183], v[220:223], v[70:73]
	v_mfma_f32_16x16x32_bf16 v[114:117], v[184:187], v[192:195], v[114:117]
	v_mfma_f32_16x16x32_bf16 v[114:117], v[188:191], v[196:199], v[114:117]
	v_mfma_f32_16x16x32_bf16 v[98:101], v[184:187], v[200:203], v[98:101]
	v_mfma_f32_16x16x32_bf16 v[98:101], v[188:191], v[204:207], v[98:101]
	v_mfma_f32_16x16x32_bf16 v[82:85], v[184:187], v[208:211], v[82:85]
	v_mfma_f32_16x16x32_bf16 v[82:85], v[188:191], v[212:215], v[82:85]
	v_mfma_f32_16x16x32_bf16 v[66:69], v[184:187], v[216:219], v[66:69]
	v_mfma_f32_16x16x32_bf16 v[66:69], v[188:191], v[220:223], v[66:69]
	s_barrier
	s_add_i32 s8, s25, s0
	v_lshl_add_u64 v[164:165], v[164:165], 0, s[62:63]
	s_mov_b32 m0, s8
	ds_read_b128 v[192:195], v179 offset:49152
	ds_read_b128 v[196:199], v179 offset:50176
	ds_read_b128 v[200:203], v179 offset:51200
	ds_read_b128 v[204:207], v179 offset:52224
	ds_read_b128 v[208:211], v179 offset:53248
	ds_read_b128 v[212:215], v179 offset:54272
	ds_read_b128 v[216:219], v179 offset:55296
	ds_read_b128 v[220:223], v179 offset:56320
	global_load_lds_dwordx4 v[164:165], off
	v_lshl_add_u64 v[164:165], v[168:169], 0, s[62:63]
	s_add_i32 m0, s8, 0x2000
	s_add_i32 s8, s27, s0
	global_load_lds_dwordx4 v[164:165], off
	v_lshl_add_u64 v[164:165], v[170:171], 0, s[62:63]
	s_mov_b32 m0, s8
	s_nop 0
	global_load_lds_dwordx4 v[164:165], off
	v_lshl_add_u64 v[164:165], v[176:177], 0, s[62:63]
	s_add_i32 m0, s8, 0x2000
	s_nop 0
	global_load_lds_dwordx4 v[164:165], off
	v_lshl_add_u64 v[164:165], v[224:225], 0, s[62:63]
	s_mov_b32 m0, s16
	s_nop 0
	global_load_lds_dwordx4 v[164:165], off
	v_lshl_add_u64 v[164:165], v[226:227], 0, s[62:63]
	s_mov_b32 m0, s17
	s_nop 0
	global_load_lds_dwordx4 v[164:165], off
	s_waitcnt vmcnt(8)
	s_waitcnt lgkmcnt(0)
	s_barrier
	s_waitcnt lgkmcnt(0)
	v_mfma_f32_16x16x32_bf16 v[54:57], v[172:175], v[192:195], v[54:57]
	v_mfma_f32_16x16x32_bf16 v[54:57], v[180:183], v[196:199], v[54:57]
	v_mfma_f32_16x16x32_bf16 v[38:41], v[172:175], v[200:203], v[38:41]
	v_mfma_f32_16x16x32_bf16 v[38:41], v[180:183], v[204:207], v[38:41]
	v_mfma_f32_16x16x32_bf16 v[22:25], v[172:175], v[208:211], v[22:25]
	v_mfma_f32_16x16x32_bf16 v[22:25], v[180:183], v[212:215], v[22:25]
	v_mfma_f32_16x16x32_bf16 v[6:9], v[172:175], v[216:219], v[6:9]
	v_mfma_f32_16x16x32_bf16 v[6:9], v[180:183], v[220:223], v[6:9]
	v_mfma_f32_16x16x32_bf16 v[50:53], v[184:187], v[192:195], v[50:53]
	v_mfma_f32_16x16x32_bf16 v[50:53], v[188:191], v[196:199], v[50:53]
	v_mfma_f32_16x16x32_bf16 v[34:37], v[184:187], v[200:203], v[34:37]
	v_mfma_f32_16x16x32_bf16 v[34:37], v[188:191], v[204:207], v[34:37]
	v_mfma_f32_16x16x32_bf16 v[18:21], v[184:187], v[208:211], v[18:21]
	v_mfma_f32_16x16x32_bf16 v[18:21], v[188:191], v[212:215], v[18:21]
	v_mfma_f32_16x16x32_bf16 v[2:5], v[184:187], v[216:219], v[2:5]
	v_mfma_f32_16x16x32_bf16 v[2:5], v[188:191], v[220:223], v[2:5]
	s_barrier
	s_add_u32 s22, s22, 0x100
	s_addc_u32 s23, s23, 0
	s_add_u32 s6, s6, 0x100
	s_addc_u32 s7, s7, 0
	s_cmp_ge_i32 s24, s14
	s_mov_b32 s8, s24
	s_cbranch_scc0 .LBB0_129

; #define PG8_STAGE(bufoff, gbase, voff) do { _Pragma("unroll") for (int _i = 0; _i < 2; ++_i) \
;         __builtin_amdgcn_global_load_lds((const unsigned*)((const char*)(gbase) + (voff)[_i]), (PG8_LAS unsigned*)(lds + (bufoff) + ldsw + _i * 8192), 16, 0, 0); } while (0)
; #define PG8_LDA(dst, b, h) do { _Pragma("unroll") for (int m = 0; m < 4; ++m) _Pragma("unroll") for (int k = 0; k < 2; ++k) dst[m][k] = *(const PG8_LAS bf16x8*)(lds + PG8_SA(b, h) + aoff + m * 2048 + k * 1024); } while (0)
; #define PG8_LDB(dst, b, h) do { _Pragma("unroll") for (int n = 0; n < 2; ++n) _Pragma("unroll") for (int k = 0; k < 2; ++k) dst[n][k] = *(const PG8_LAS bf16x8*)(lds + PG8_SB(b, h) + boff + n * 2048 + k * 1024); } while (0)
; #define PG8_MMA(ai, bj, At, Bt) do { __builtin_amdgcn_s_setprio(1); _Pragma("unroll") for (int m = 0; m < 4; ++m) _Pragma("unroll") for (int n = 0; n < 2; ++n) _Pragma("unroll") for (int k = 0; k < 2; ++k) \
;         acc[ai][bj][m][n] = __builtin_amdgcn_mfma_f32_16x16x32_bf16(Bt[n][k], At[m][k], acc[ai][bj][m][n], 0, 0, 0); __builtin_amdgcn_s_setprio(0); } while (0)
; #define PG8_WAIT_V(n) asm volatile("s_waitcnt vmcnt(" #n ")" ::: "memory")
; #define PG8_WAIT_L(n) asm volatile("s_waitcnt lgkmcnt(" #n ")" ::: "memory")
; #define PG8_BAR __builtin_amdgcn_s_barrier()
; #define PG8_SCHED __builtin_amdgcn_sched_barrier(0)
;     ...
;             const char* a1 = cA + (size_t)(t + 1) * kstep;
;             const char* a2 = last ? nA : cA + (size_t)(t + 2) * kstep; const char* b2 = last ? nB : cB + (size_t)(t + 2) * kstep;
;             const char* a3 = a2 + kstep; const char* b3 = b2 + kstep;
;             if (last && has_next) S.a_ready(nxt);
;             if constexpr (SP2) {
;             PG8_LDB(B0, 0, 0); PG8_LDB(B1, 0, 1); PG8_SCHED; PG8_LDA(At, 0, 0); PG8_STAGE(PG8_SA(1, 1), a1 + hstepA, voffA);
;             PG8_WAIT_V(8); PG8_WAIT_L(0); PG8_BAR; PG8_MMA(0, 0, At, B0); PG8_MMA(0, 1, At, B1); PG8_BAR; PG8_SCHED;
;             PG8_LDA(At, 0, 1); PG8_STAGE(PG8_SB(0, 0), b2, voffB); PG8_STAGE(PG8_SB(0, 1), b2 + hstepB, voffB); PG8_STAGE(PG8_SA(0, 0), a2, voffA);
.LBB0_286:
	v_readlane_b32 s10, v255, 5
	v_readlane_b32 s11, v255, 6
	s_andn2_b64 vcc, exec, s[10:11]
	s_cbranch_vccnz .LBB0_289
	s_add_u32 s10, s6, 0x100
	s_addc_u32 s11, s7, 0
	s_add_u32 s6, s8, 0x80
	s_addc_u32 s7, s9, 0
	s_mov_b32 s8, 0
	s_add_i32 s12, s8, 2
	s_add_u32 s13, s6, 0x80
	s_addc_u32 s9, s7, 0
	s_add_i32 s16, 0, 0x10000
	s_cmp_eq_u32 s69, s8
	s_cselect_b32 s9, s41, s9
	s_cselect_b32 s8, s40, s13
	s_cselect_b32 s15, s5, s11
	s_cselect_b32 s14, s4, s10
	s_add_i32 s13, 0, 0x14000
	v_add_u32_e32 v142, s16, v249
	v_add_u32_e32 v158, s13, v249
	ds_read_b128 v[130:133], v142
	ds_read_b128 v[134:137], v142 offset:1024
	ds_read_b128 v[138:141], v142 offset:2048
	ds_read_b128 v[142:145], v142 offset:3072
	ds_read_b128 v[146:149], v158
	ds_read_b128 v[150:153], v158 offset:1024
	ds_read_b128 v[154:157], v158 offset:2048
	ds_read_b128 v[158:161], v158 offset:3072
	v_lshl_add_u64 v[212:213], s[6:7], 0, v[182:183]
	s_add_i32 m0, s27, 0xc000
	ds_read_b128 v[162:165], v251
	ds_read_b128 v[184:187], v251 offset:1024
	ds_read_b128 v[188:191], v251 offset:2048
	ds_read_b128 v[192:195], v251 offset:3072
	ds_read_b128 v[196:199], v251 offset:4096
	ds_read_b128 v[200:203], v251 offset:5120
	ds_read_b128 v[204:207], v251 offset:6144
	ds_read_b128 v[208:211], v251 offset:7168
	global_load_lds_dwordx4 v[212:213], off
	v_lshl_add_u64 v[212:213], s[6:7], 0, v[180:181]
	s_add_i32 m0, s27, 0xe000
	s_nop 0
	global_load_lds_dwordx4 v[212:213], off
	s_waitcnt vmcnt(8)
	s_waitcnt lgkmcnt(0)
	s_barrier
	s_waitcnt lgkmcnt(0)
	v_mfma_f32_16x16x32_bf16 v[122:125], v[130:133], v[162:165], 0
	v_mfma_f32_16x16x32_bf16 v[122:125], v[134:137], v[184:187], v[122:125]
	v_mfma_f32_16x16x32_bf16 v[110:113], v[130:133], v[188:191], 0
	v_mfma_f32_16x16x32_bf16 v[110:113], v[134:137], v[192:195], v[110:113]
	v_mfma_f32_16x16x32_bf16 v[94:97], v[130:133], v[196:199], 0
	v_mfma_f32_16x16x32_bf16 v[94:97], v[134:137], v[200:203], v[94:97]
	v_mfma_f32_16x16x32_bf16 v[78:81], v[130:133], v[204:207], 0
	v_mfma_f32_16x16x32_bf16 v[78:81], v[134:137], v[208:211], v[78:81]
	v_mfma_f32_16x16x32_bf16 v[118:121], v[138:141], v[162:165], 0
	v_mfma_f32_16x16x32_bf16 v[118:121], v[142:145], v[184:187], v[118:121]
	v_mfma_f32_16x16x32_bf16 v[102:105], v[138:141], v[188:191], 0
	v_mfma_f32_16x16x32_bf16 v[102:105], v[142:145], v[192:195], v[102:105]
	v_mfma_f32_16x16x32_bf16 v[86:89], v[138:141], v[196:199], 0
	v_mfma_f32_16x16x32_bf16 v[86:89], v[142:145], v[200:203], v[86:89]
	v_mfma_f32_16x16x32_bf16 v[70:73], v[138:141], v[204:207], 0
	v_mfma_f32_16x16x32_bf16 v[70:73], v[142:145], v[208:211], v[70:73]
	v_mfma_f32_16x16x32_bf16 v[126:129], v[146:149], v[162:165], 0
	v_mfma_f32_16x16x32_bf16 v[126:129], v[150:153], v[184:187], v[126:129]
	v_mfma_f32_16x16x32_bf16 v[106:109], v[146:149], v[188:191], 0
	v_mfma_f32_16x16x32_bf16 v[106:109], v[150:153], v[192:195], v[106:109]
	v_mfma_f32_16x16x32_bf16 v[90:93], v[146:149], v[196:199], 0
	v_mfma_f32_16x16x32_bf16 v[90:93], v[150:153], v[200:203], v[90:93]
	v_mfma_f32_16x16x32_bf16 v[74:77], v[146:149], v[204:207], 0
	v_mfma_f32_16x16x32_bf16 v[74:77], v[150:153], v[208:211], v[74:77]
	v_mfma_f32_16x16x32_bf16 v[114:117], v[154:157], v[162:165], 0
	v_mfma_f32_16x16x32_bf16 v[114:117], v[158:161], v[184:187], v[114:117]
	v_mfma_f32_16x16x32_bf16 v[98:101], v[154:157], v[188:191], 0
	v_mfma_f32_16x16x32_bf16 v[98:101], v[158:161], v[192:195], v[98:101]
	v_mfma_f32_16x16x32_bf16 v[82:85], v[154:157], v[196:199], 0
	v_mfma_f32_16x16x32_bf16 v[82:85], v[158:161], v[200:203], v[82:85]
	v_mfma_f32_16x16x32_bf16 v[66:69], v[154:157], v[204:207], 0
	v_mfma_f32_16x16x32_bf16 v[66:69], v[158:161], v[208:211], v[66:69]
	s_barrier
	s_add_i32 s16, s16, s0
	v_lshl_add_u64 v[212:213], s[14:15], 0, v[166:167]
	s_mov_b32 m0, s16
	ds_read_b128 v[162:165], v251 offset:16384
	ds_read_b128 v[184:187], v251 offset:17408
	ds_read_b128 v[188:191], v251 offset:18432
	ds_read_b128 v[192:195], v251 offset:19456
	ds_read_b128 v[196:199], v251 offset:20480
	ds_read_b128 v[200:203], v251 offset:21504
	ds_read_b128 v[204:207], v251 offset:22528
	ds_read_b128 v[208:211], v251 offset:23552
	global_load_lds_dwordx4 v[212:213], off
	s_add_i32 m0, s16, 0x2000
	v_lshl_add_u64 v[214:215], s[14:15], 0, v[172:173]
	s_add_u32 s14, s14, s58
	s_addc_u32 s15, s15, s59
	s_add_i32 s13, s13, s0
	global_load_lds_dwordx4 v[214:215], off
	v_lshl_add_u64 v[216:217], s[14:15], 0, v[166:167]
	s_mov_b32 m0, s13
	v_lshl_add_u64 v[218:219], s[14:15], 0, v[172:173]
	global_load_lds_dwordx4 v[216:217], off
	s_add_i32 m0, s13, 0x2000
	v_lshl_add_u64 v[220:221], s[8:9], 0, v[176:177]
	global_load_lds_dwordx4 v[218:219], off
	s_mov_b32 m0, s27
	v_lshl_add_u64 v[222:223], s[8:9], 0, v[174:175]
	global_load_lds_dwordx4 v[220:221], off
	s_mov_b32 m0, s31
	s_nop 0
	global_load_lds_dwordx4 v[222:223], off
	s_waitcnt vmcnt(8)
	s_waitcnt lgkmcnt(0)
	s_barrier
; #define PG8_STAGE(bufoff, gbase, voff) do { _Pragma("unroll") for (int _i = 0; _i < 2; ++_i) \
;         __builtin_amdgcn_global_load_lds((const unsigned*)((const char*)(gbase) + (voff)[_i]), (PG8_LAS unsigned*)(lds + (bufoff) + ldsw + _i * 8192), 16, 0, 0); } while (0)
; #define PG8_LDA(dst, b, h) do { _Pragma("unroll") for (int m = 0; m < 4; ++m) _Pragma("unroll") for (int k = 0; k < 2; ++k) dst[m][k] = *(const PG8_LAS bf16x8*)(lds + PG8_SA(b, h) + aoff + m * 2048 + k * 1024); } while (0)
; #define PG8_LDB(dst, b, h) do { _Pragma("unroll") for (int n = 0; n < 2; ++n) _Pragma("unroll") for (int k = 0; k < 2; ++k) dst[n][k] = *(const PG8_LAS bf16x8*)(lds + PG8_SB(b, h) + boff + n * 2048 + k * 1024); } while (0)
; #define PG8_MMA(ai, bj, At, Bt) do { __builtin_amdgcn_s_setprio(1); _Pragma("unroll") for (int m = 0; m < 4; ++m) _Pragma("unroll") for (int n = 0; n < 2; ++n) _Pragma("unroll") for (int k = 0; k < 2; ++k) \
;         acc[ai][bj][m][n] = __builtin_amdgcn_mfma_f32_16x16x32_bf16(Bt[n][k], At[m][k], acc[ai][bj][m][n], 0, 0, 0); __builtin_amdgcn_s_setprio(0); } while (0)
; #define PG8_WAIT_V(n) asm volatile("s_waitcnt vmcnt(" #n ")" ::: "memory")
; #define PG8_WAIT_L(n) asm volatile("s_waitcnt lgkmcnt(" #n ")" ::: "memory")
; #define PG8_BAR __builtin_amdgcn_s_barrier()
; #define PG8_SCHED __builtin_amdgcn_sched_barrier(0)
;     ...
;             PG8_WAIT_V(8); PG8_WAIT_L(0); PG8_BAR; PG8_MMA(1, 0, At, B0); PG8_MMA(1, 1, At, B1); PG8_BAR; PG8_SCHED;
;             PG8_LDB(B0, 1, 0); PG8_LDB(B1, 1, 1); PG8_SCHED; PG8_LDA(At, 1, 0); PG8_STAGE(PG8_SA(0, 1), a2 + hstepA, voffA);
;             PG8_WAIT_V(8); PG8_WAIT_L(0); PG8_BAR; PG8_MMA(0, 0, At, B0); PG8_MMA(0, 1, At, B1); PG8_BAR; PG8_SCHED;
	s_waitcnt lgkmcnt(0)
	v_mfma_f32_16x16x32_bf16 v[62:65], v[130:133], v[162:165], 0
	v_mfma_f32_16x16x32_bf16 v[62:65], v[134:137], v[184:187], v[62:65]
	v_mfma_f32_16x16x32_bf16 v[46:49], v[130:133], v[188:191], 0
	v_mfma_f32_16x16x32_bf16 v[46:49], v[134:137], v[192:195], v[46:49]
	v_mfma_f32_16x16x32_bf16 v[30:33], v[130:133], v[196:199], 0
	v_mfma_f32_16x16x32_bf16 v[30:33], v[134:137], v[200:203], v[30:33]
	v_mfma_f32_16x16x32_bf16 v[14:17], v[130:133], v[204:207], 0
	v_mfma_f32_16x16x32_bf16 v[14:17], v[134:137], v[208:211], v[14:17]
	v_mfma_f32_16x16x32_bf16 v[54:57], v[138:141], v[162:165], 0
	v_mfma_f32_16x16x32_bf16 v[54:57], v[142:145], v[184:187], v[54:57]
	v_mfma_f32_16x16x32_bf16 v[38:41], v[138:141], v[188:191], 0
	v_mfma_f32_16x16x32_bf16 v[38:41], v[142:145], v[192:195], v[38:41]
	v_mfma_f32_16x16x32_bf16 v[22:25], v[138:141], v[196:199], 0
	v_mfma_f32_16x16x32_bf16 v[22:25], v[142:145], v[200:203], v[22:25]
	v_mfma_f32_16x16x32_bf16 v[6:9], v[138:141], v[204:207], 0
	v_mfma_f32_16x16x32_bf16 v[6:9], v[142:145], v[208:211], v[6:9]
	v_mfma_f32_16x16x32_bf16 v[58:61], v[146:149], v[162:165], 0
	v_mfma_f32_16x16x32_bf16 v[58:61], v[150:153], v[184:187], v[58:61]
	v_mfma_f32_16x16x32_bf16 v[42:45], v[146:149], v[188:191], 0
	v_mfma_f32_16x16x32_bf16 v[42:45], v[150:153], v[192:195], v[42:45]
	v_mfma_f32_16x16x32_bf16 v[26:29], v[146:149], v[196:199], 0
	v_mfma_f32_16x16x32_bf16 v[26:29], v[150:153], v[200:203], v[26:29]
	v_mfma_f32_16x16x32_bf16 v[10:13], v[146:149], v[204:207], 0
	v_mfma_f32_16x16x32_bf16 v[10:13], v[150:153], v[208:211], v[10:13]
	v_mfma_f32_16x16x32_bf16 v[50:53], v[154:157], v[162:165], 0
	v_mfma_f32_16x16x32_bf16 v[50:53], v[158:161], v[184:187], v[50:53]
	v_mfma_f32_16x16x32_bf16 v[34:37], v[154:157], v[188:191], 0
	v_mfma_f32_16x16x32_bf16 v[34:37], v[158:161], v[192:195], v[34:37]
	v_mfma_f32_16x16x32_bf16 v[18:21], v[154:157], v[196:199], 0
	v_mfma_f32_16x16x32_bf16 v[18:21], v[158:161], v[200:203], v[18:21]
	v_mfma_f32_16x16x32_bf16 v[2:5], v[154:157], v[204:207], 0
	v_mfma_f32_16x16x32_bf16 v[2:5], v[158:161], v[208:211], v[2:5]
	s_barrier
	s_add_i32 s13, 0, 0x18000
	s_add_i32 s14, 0, 0x1c000
	v_add_u32_e32 v142, s13, v249
	v_add_u32_e32 v158, s14, v249
	ds_read_b128 v[130:133], v142
	ds_read_b128 v[134:137], v142 offset:1024
	ds_read_b128 v[138:141], v142 offset:2048
	ds_read_b128 v[142:145], v142 offset:3072
	ds_read_b128 v[146:149], v158
	ds_read_b128 v[150:153], v158 offset:1024
	ds_read_b128 v[154:157], v158 offset:2048
	ds_read_b128 v[158:161], v158 offset:3072
	s_add_u32 s8, s8, s58
	s_addc_u32 s9, s9, s59
	s_mov_b32 m0, s47
	v_lshl_add_u64 v[224:225], s[8:9], 0, v[176:177]
	ds_read_b128 v[162:165], v251 offset:32768
	ds_read_b128 v[184:187], v251 offset:33792
	ds_read_b128 v[188:191], v251 offset:34816
	ds_read_b128 v[192:195], v251 offset:35840
	ds_read_b128 v[196:199], v251 offset:36864
	ds_read_b128 v[200:203], v251 offset:37888
	ds_read_b128 v[204:207], v251 offset:38912
	ds_read_b128 v[208:211], v251 offset:39936
	global_load_lds_dwordx4 v[224:225], off
	v_lshl_add_u64 v[224:225], s[8:9], 0, v[174:175]
	s_mov_b32 m0, s49
	s_nop 0
	global_load_lds_dwordx4 v[224:225], off
	s_waitcnt vmcnt(8)
	s_waitcnt lgkmcnt(0)
	s_barrier
	s_waitcnt lgkmcnt(0)
	v_mfma_f32_16x16x32_bf16 v[122:125], v[130:133], v[162:165], v[122:125]
	v_mfma_f32_16x16x32_bf16 v[122:125], v[134:137], v[184:187], v[122:125]
	v_mfma_f32_16x16x32_bf16 v[110:113], v[130:133], v[188:191], v[110:113]
	v_mfma_f32_16x16x32_bf16 v[110:113], v[134:137], v[192:195], v[110:113]
	v_mfma_f32_16x16x32_bf16 v[94:97], v[130:133], v[196:199], v[94:97]
	v_mfma_f32_16x16x32_bf16 v[94:97], v[134:137], v[200:203], v[94:97]
	v_mfma_f32_16x16x32_bf16 v[78:81], v[130:133], v[204:207], v[78:81]
	v_mfma_f32_16x16x32_bf16 v[78:81], v[134:137], v[208:211], v[78:81]
	v_mfma_f32_16x16x32_bf16 v[118:121], v[138:141], v[162:165], v[118:121]
	v_mfma_f32_16x16x32_bf16 v[118:121], v[142:145], v[184:187], v[118:121]
	v_mfma_f32_16x16x32_bf16 v[102:105], v[138:141], v[188:191], v[102:105]
	v_mfma_f32_16x16x32_bf16 v[102:105], v[142:145], v[192:195], v[102:105]
	v_mfma_f32_16x16x32_bf16 v[86:89], v[138:141], v[196:199], v[86:89]
	v_mfma_f32_16x16x32_bf16 v[86:89], v[142:145], v[200:203], v[86:89]
	v_mfma_f32_16x16x32_bf16 v[70:73], v[138:141], v[204:207], v[70:73]
	v_mfma_f32_16x16x32_bf16 v[70:73], v[142:145], v[208:211], v[70:73]
	v_mfma_f32_16x16x32_bf16 v[126:129], v[146:149], v[162:165], v[126:129]
	v_mfma_f32_16x16x32_bf16 v[126:129], v[150:153], v[184:187], v[126:129]
	v_mfma_f32_16x16x32_bf16 v[106:109], v[146:149], v[188:191], v[106:109]
	v_mfma_f32_16x16x32_bf16 v[106:109], v[150:153], v[192:195], v[106:109]
	v_mfma_f32_16x16x32_bf16 v[90:93], v[146:149], v[196:199], v[90:93]
	v_mfma_f32_16x16x32_bf16 v[90:93], v[150:153], v[200:203], v[90:93]
	v_mfma_f32_16x16x32_bf16 v[74:77], v[146:149], v[204:207], v[74:77]
	v_mfma_f32_16x16x32_bf16 v[74:77], v[150:153], v[208:211], v[74:77]
	v_mfma_f32_16x16x32_bf16 v[114:117], v[154:157], v[162:165], v[114:117]
	v_mfma_f32_16x16x32_bf16 v[114:117], v[158:161], v[184:187], v[114:117]
	v_mfma_f32_16x16x32_bf16 v[98:101], v[154:157], v[188:191], v[98:101]
	v_mfma_f32_16x16x32_bf16 v[98:101], v[158:161], v[192:195], v[98:101]
	v_mfma_f32_16x16x32_bf16 v[82:85], v[154:157], v[196:199], v[82:85]
	v_mfma_f32_16x16x32_bf16 v[82:85], v[158:161], v[200:203], v[82:85]
	v_mfma_f32_16x16x32_bf16 v[66:69], v[154:157], v[204:207], v[66:69]
	v_mfma_f32_16x16x32_bf16 v[66:69], v[158:161], v[208:211], v[66:69]
	s_barrier
; #define PG8_STAGE(bufoff, gbase, voff) do { _Pragma("unroll") for (int _i = 0; _i < 2; ++_i) \
;         __builtin_amdgcn_global_load_lds((const unsigned*)((const char*)(gbase) + (voff)[_i]), (PG8_LAS unsigned*)(lds + (bufoff) + ldsw + _i * 8192), 16, 0, 0); } while (0)
; #define PG8_LDA(dst, b, h) do { _Pragma("unroll") for (int m = 0; m < 4; ++m) _Pragma("unroll") for (int k = 0; k < 2; ++k) dst[m][k] = *(const PG8_LAS bf16x8*)(lds + PG8_SA(b, h) + aoff + m * 2048 + k * 1024); } while (0)
; #define PG8_LDB(dst, b, h) do { _Pragma("unroll") for (int n = 0; n < 2; ++n) _Pragma("unroll") for (int k = 0; k < 2; ++k) dst[n][k] = *(const PG8_LAS bf16x8*)(lds + PG8_SB(b, h) + boff + n * 2048 + k * 1024); } while (0)
; #define PG8_MMA(ai, bj, At, Bt) do { __builtin_amdgcn_s_setprio(1); _Pragma("unroll") for (int m = 0; m < 4; ++m) _Pragma("unroll") for (int n = 0; n < 2; ++n) _Pragma("unroll") for (int k = 0; k < 2; ++k) \
;         acc[ai][bj][m][n] = __builtin_amdgcn_mfma_f32_16x16x32_bf16(Bt[n][k], At[m][k], acc[ai][bj][m][n], 0, 0, 0); __builtin_amdgcn_s_setprio(0); } while (0)
; #define PG8_WAIT_V(n) asm volatile("s_waitcnt vmcnt(" #n ")" ::: "memory")
; #define PG8_WAIT_L(n) asm volatile("s_waitcnt lgkmcnt(" #n ")" ::: "memory")
; #define PG8_BAR __builtin_amdgcn_s_barrier()
; #define PG8_SCHED __builtin_amdgcn_sched_barrier(0)
;     ...
;             const char* a1 = cA + (size_t)(t + 1) * kstep;
;             const char* a2 = last ? nA : cA + (size_t)(t + 2) * kstep; const char* b2 = last ? nB : cB + (size_t)(t + 2) * kstep;
;             const char* a3 = a2 + kstep; const char* b3 = b2 + kstep;
;             if (last && has_next) S.a_ready(nxt);
;             if constexpr (SP2) {
;             PG8_LDB(B0, 0, 0); PG8_LDB(B1, 0, 1); PG8_SCHED; PG8_LDA(At, 0, 0); PG8_STAGE(PG8_SA(1, 1), a1 + hstepA, voffA);
;             PG8_WAIT_V(8); PG8_WAIT_L(0); PG8_BAR; PG8_MMA(0, 0, At, B0); PG8_MMA(0, 1, At, B1); PG8_BAR; PG8_SCHED;
;     ...
;             PG8_LDA(At, 1, 1); PG8_STAGE(PG8_SB(1, 0), b3, voffB); PG8_STAGE(PG8_SB(1, 1), b3 + hstepB, voffB); PG8_STAGE(PG8_SA(1, 0), a3, voffA);
;             PG8_WAIT_V(8); PG8_WAIT_L(0); PG8_BAR; PG8_MMA(1, 0, At, B0); PG8_MMA(1, 1, At, B1); PG8_BAR; PG8_SCHED;
	s_add_i32 s8, s13, s0
	v_lshl_add_u64 v[212:213], v[212:213], 0, s[62:63]
	s_mov_b32 m0, s8
	ds_read_b128 v[162:165], v251 offset:49152
	ds_read_b128 v[184:187], v251 offset:50176
	ds_read_b128 v[188:191], v251 offset:51200
	ds_read_b128 v[192:195], v251 offset:52224
	ds_read_b128 v[196:199], v251 offset:53248
	ds_read_b128 v[200:203], v251 offset:54272
	ds_read_b128 v[204:207], v251 offset:55296
	ds_read_b128 v[208:211], v251 offset:56320
	global_load_lds_dwordx4 v[212:213], off
	v_lshl_add_u64 v[212:213], v[214:215], 0, s[62:63]
	s_add_i32 m0, s8, 0x2000
	s_add_i32 s8, s14, s0
	global_load_lds_dwordx4 v[212:213], off
	v_lshl_add_u64 v[212:213], v[216:217], 0, s[62:63]
	s_mov_b32 m0, s8
	s_nop 0
	global_load_lds_dwordx4 v[212:213], off
	v_lshl_add_u64 v[212:213], v[218:219], 0, s[62:63]
	s_add_i32 m0, s8, 0x2000
	s_nop 0
	global_load_lds_dwordx4 v[212:213], off
	v_lshl_add_u64 v[212:213], v[220:221], 0, s[62:63]
	s_mov_b32 m0, s51
	s_nop 0
	global_load_lds_dwordx4 v[212:213], off
	v_lshl_add_u64 v[212:213], v[222:223], 0, s[62:63]
	s_mov_b32 m0, s53
	s_nop 0
	global_load_lds_dwordx4 v[212:213], off
	s_waitcnt vmcnt(8)
	s_waitcnt lgkmcnt(0)
	s_barrier
	s_waitcnt lgkmcnt(0)
	v_mfma_f32_16x16x32_bf16 v[62:65], v[130:133], v[162:165], v[62:65]
	v_mfma_f32_16x16x32_bf16 v[62:65], v[134:137], v[184:187], v[62:65]
	v_mfma_f32_16x16x32_bf16 v[46:49], v[130:133], v[188:191], v[46:49]
	v_mfma_f32_16x16x32_bf16 v[46:49], v[134:137], v[192:195], v[46:49]
	v_mfma_f32_16x16x32_bf16 v[30:33], v[130:133], v[196:199], v[30:33]
	v_mfma_f32_16x16x32_bf16 v[30:33], v[134:137], v[200:203], v[30:33]
	v_mfma_f32_16x16x32_bf16 v[14:17], v[130:133], v[204:207], v[14:17]
	v_mfma_f32_16x16x32_bf16 v[14:17], v[134:137], v[208:211], v[14:17]
	v_mfma_f32_16x16x32_bf16 v[54:57], v[138:141], v[162:165], v[54:57]
	v_mfma_f32_16x16x32_bf16 v[54:57], v[142:145], v[184:187], v[54:57]
	v_mfma_f32_16x16x32_bf16 v[38:41], v[138:141], v[188:191], v[38:41]
	v_mfma_f32_16x16x32_bf16 v[38:41], v[142:145], v[192:195], v[38:41]
	v_mfma_f32_16x16x32_bf16 v[22:25], v[138:141], v[196:199], v[22:25]
	v_mfma_f32_16x16x32_bf16 v[22:25], v[142:145], v[200:203], v[22:25]
	v_mfma_f32_16x16x32_bf16 v[6:9], v[138:141], v[204:207], v[6:9]
	v_mfma_f32_16x16x32_bf16 v[6:9], v[142:145], v[208:211], v[6:9]
	v_mfma_f32_16x16x32_bf16 v[58:61], v[146:149], v[162:165], v[58:61]
	v_mfma_f32_16x16x32_bf16 v[58:61], v[150:153], v[184:187], v[58:61]
	v_mfma_f32_16x16x32_bf16 v[42:45], v[146:149], v[188:191], v[42:45]
	v_mfma_f32_16x16x32_bf16 v[42:45], v[150:153], v[192:195], v[42:45]
	v_mfma_f32_16x16x32_bf16 v[26:29], v[146:149], v[196:199], v[26:29]
	v_mfma_f32_16x16x32_bf16 v[26:29], v[150:153], v[200:203], v[26:29]
	v_mfma_f32_16x16x32_bf16 v[10:13], v[146:149], v[204:207], v[10:13]
	v_mfma_f32_16x16x32_bf16 v[10:13], v[150:153], v[208:211], v[10:13]
	v_mfma_f32_16x16x32_bf16 v[50:53], v[154:157], v[162:165], v[50:53]
	v_mfma_f32_16x16x32_bf16 v[50:53], v[158:161], v[184:187], v[50:53]
	v_mfma_f32_16x16x32_bf16 v[34:37], v[154:157], v[188:191], v[34:37]
	v_mfma_f32_16x16x32_bf16 v[34:37], v[158:161], v[192:195], v[34:37]
	v_mfma_f32_16x16x32_bf16 v[18:21], v[154:157], v[196:199], v[18:21]
	v_mfma_f32_16x16x32_bf16 v[18:21], v[158:161], v[200:203], v[18:21]
	v_mfma_f32_16x16x32_bf16 v[2:5], v[154:157], v[204:207], v[2:5]
	v_mfma_f32_16x16x32_bf16 v[2:5], v[158:161], v[208:211], v[2:5]
	s_barrier
	s_add_u32 s10, s10, 0x100
	s_addc_u32 s11, s11, 0
	s_add_u32 s6, s6, 0x100
	s_addc_u32 s7, s7, 0
	s_cmp_ge_i32 s12, s55
	s_mov_b32 s8, s12
	s_cbranch_scc1 .LBB0_289
.LBB0_288:
	s_add_i32 s12, s8, 2
	s_add_u32 s13, s6, 0x80
	s_addc_u32 s9, s7, 0
	s_add_i32 s16, 0, 0x10000
	s_cmp_eq_u32 s69, s8
	s_cselect_b32 s9, s41, s9
	s_cselect_b32 s8, s40, s13
	s_cselect_b32 s15, s5, s11
	s_cselect_b32 s14, s4, s10
	s_add_i32 s13, 0, 0x14000
	v_add_u32_e32 v142, s16, v249
	v_add_u32_e32 v158, s13, v249
	ds_read_b128 v[130:133], v142
	ds_read_b128 v[134:137], v142 offset:1024
	ds_read_b128 v[138:141], v142 offset:2048
	ds_read_b128 v[142:145], v142 offset:3072
	ds_read_b128 v[146:149], v158
	ds_read_b128 v[150:153], v158 offset:1024
	ds_read_b128 v[154:157], v158 offset:2048
	ds_read_b128 v[158:161], v158 offset:3072
	v_lshl_add_u64 v[212:213], s[6:7], 0, v[182:183]
	s_add_i32 m0, s27, 0xc000
	ds_read_b128 v[162:165], v251
	ds_read_b128 v[184:187], v251 offset:1024
	ds_read_b128 v[188:191], v251 offset:2048
	ds_read_b128 v[192:195], v251 offset:3072
	ds_read_b128 v[196:199], v251 offset:4096
	ds_read_b128 v[200:203], v251 offset:5120
	ds_read_b128 v[204:207], v251 offset:6144
	ds_read_b128 v[208:211], v251 offset:7168
	global_load_lds_dwordx4 v[212:213], off
	v_lshl_add_u64 v[212:213], s[6:7], 0, v[180:181]
	s_add_i32 m0, s27, 0xe000
	s_nop 0
	global_load_lds_dwordx4 v[212:213], off
	s_waitcnt vmcnt(8)
	s_waitcnt lgkmcnt(0)
	s_barrier
; #define PG8_STAGE(bufoff, gbase, voff) do { _Pragma("unroll") for (int _i = 0; _i < 2; ++_i) \
;         __builtin_amdgcn_global_load_lds((const unsigned*)((const char*)(gbase) + (voff)[_i]), (PG8_LAS unsigned*)(lds + (bufoff) + ldsw + _i * 8192), 16, 0, 0); } while (0)
; #define PG8_LDA(dst, b, h) do { _Pragma("unroll") for (int m = 0; m < 4; ++m) _Pragma("unroll") for (int k = 0; k < 2; ++k) dst[m][k] = *(const PG8_LAS bf16x8*)(lds + PG8_SA(b, h) + aoff + m * 2048 + k * 1024); } while (0)
; #define PG8_MMA(ai, bj, At, Bt) do { __builtin_amdgcn_s_setprio(1); _Pragma("unroll") for (int m = 0; m < 4; ++m) _Pragma("unroll") for (int n = 0; n < 2; ++n) _Pragma("unroll") for (int k = 0; k < 2; ++k) \
;         acc[ai][bj][m][n] = __builtin_amdgcn_mfma_f32_16x16x32_bf16(Bt[n][k], At[m][k], acc[ai][bj][m][n], 0, 0, 0); __builtin_amdgcn_s_setprio(0); } while (0)
; #define PG8_WAIT_V(n) asm volatile("s_waitcnt vmcnt(" #n ")" ::: "memory")
; #define PG8_WAIT_L(n) asm volatile("s_waitcnt lgkmcnt(" #n ")" ::: "memory")
; #define PG8_BAR __builtin_amdgcn_s_barrier()
; #define PG8_SCHED __builtin_amdgcn_sched_barrier(0)
;     ...
;             PG8_WAIT_V(8); PG8_WAIT_L(0); PG8_BAR; PG8_MMA(0, 0, At, B0); PG8_MMA(0, 1, At, B1); PG8_BAR; PG8_SCHED;
;             PG8_LDA(At, 0, 1); PG8_STAGE(PG8_SB(0, 0), b2, voffB); PG8_STAGE(PG8_SB(0, 1), b2 + hstepB, voffB); PG8_STAGE(PG8_SA(0, 0), a2, voffA);
;             PG8_WAIT_V(8); PG8_WAIT_L(0); PG8_BAR; PG8_MMA(1, 0, At, B0); PG8_MMA(1, 1, At, B1); PG8_BAR; PG8_SCHED;
	s_waitcnt lgkmcnt(0)
	v_mfma_f32_16x16x32_bf16 v[122:125], v[130:133], v[162:165], v[122:125]
	v_mfma_f32_16x16x32_bf16 v[122:125], v[134:137], v[184:187], v[122:125]
	v_mfma_f32_16x16x32_bf16 v[110:113], v[130:133], v[188:191], v[110:113]
	v_mfma_f32_16x16x32_bf16 v[110:113], v[134:137], v[192:195], v[110:113]
	v_mfma_f32_16x16x32_bf16 v[94:97], v[130:133], v[196:199], v[94:97]
	v_mfma_f32_16x16x32_bf16 v[94:97], v[134:137], v[200:203], v[94:97]
	v_mfma_f32_16x16x32_bf16 v[78:81], v[130:133], v[204:207], v[78:81]
	v_mfma_f32_16x16x32_bf16 v[78:81], v[134:137], v[208:211], v[78:81]
	v_mfma_f32_16x16x32_bf16 v[118:121], v[138:141], v[162:165], v[118:121]
	v_mfma_f32_16x16x32_bf16 v[118:121], v[142:145], v[184:187], v[118:121]
	v_mfma_f32_16x16x32_bf16 v[102:105], v[138:141], v[188:191], v[102:105]
	v_mfma_f32_16x16x32_bf16 v[102:105], v[142:145], v[192:195], v[102:105]
	v_mfma_f32_16x16x32_bf16 v[86:89], v[138:141], v[196:199], v[86:89]
	v_mfma_f32_16x16x32_bf16 v[86:89], v[142:145], v[200:203], v[86:89]
	v_mfma_f32_16x16x32_bf16 v[70:73], v[138:141], v[204:207], v[70:73]
	v_mfma_f32_16x16x32_bf16 v[70:73], v[142:145], v[208:211], v[70:73]
	v_mfma_f32_16x16x32_bf16 v[126:129], v[146:149], v[162:165], v[126:129]
	v_mfma_f32_16x16x32_bf16 v[126:129], v[150:153], v[184:187], v[126:129]
	v_mfma_f32_16x16x32_bf16 v[106:109], v[146:149], v[188:191], v[106:109]
	v_mfma_f32_16x16x32_bf16 v[106:109], v[150:153], v[192:195], v[106:109]
	v_mfma_f32_16x16x32_bf16 v[90:93], v[146:149], v[196:199], v[90:93]
	v_mfma_f32_16x16x32_bf16 v[90:93], v[150:153], v[200:203], v[90:93]
	v_mfma_f32_16x16x32_bf16 v[74:77], v[146:149], v[204:207], v[74:77]
	v_mfma_f32_16x16x32_bf16 v[74:77], v[150:153], v[208:211], v[74:77]
	v_mfma_f32_16x16x32_bf16 v[114:117], v[154:157], v[162:165], v[114:117]
	v_mfma_f32_16x16x32_bf16 v[114:117], v[158:161], v[184:187], v[114:117]
	v_mfma_f32_16x16x32_bf16 v[98:101], v[154:157], v[188:191], v[98:101]
	v_mfma_f32_16x16x32_bf16 v[98:101], v[158:161], v[192:195], v[98:101]
	v_mfma_f32_16x16x32_bf16 v[82:85], v[154:157], v[196:199], v[82:85]
	v_mfma_f32_16x16x32_bf16 v[82:85], v[158:161], v[200:203], v[82:85]
	v_mfma_f32_16x16x32_bf16 v[66:69], v[154:157], v[204:207], v[66:69]
	v_mfma_f32_16x16x32_bf16 v[66:69], v[158:161], v[208:211], v[66:69]
	s_barrier
	s_add_i32 s16, s16, s0
	v_lshl_add_u64 v[212:213], s[14:15], 0, v[166:167]
	s_mov_b32 m0, s16
	ds_read_b128 v[162:165], v251 offset:16384
	ds_read_b128 v[184:187], v251 offset:17408
	ds_read_b128 v[188:191], v251 offset:18432
	ds_read_b128 v[192:195], v251 offset:19456
	ds_read_b128 v[196:199], v251 offset:20480
	ds_read_b128 v[200:203], v251 offset:21504
	ds_read_b128 v[204:207], v251 offset:22528
	ds_read_b128 v[208:211], v251 offset:23552
	global_load_lds_dwordx4 v[212:213], off
	s_add_i32 m0, s16, 0x2000
	v_lshl_add_u64 v[214:215], s[14:15], 0, v[172:173]
	s_add_u32 s14, s14, s58
	s_addc_u32 s15, s15, s59
	s_add_i32 s13, s13, s0
	global_load_lds_dwordx4 v[214:215], off
	v_lshl_add_u64 v[216:217], s[14:15], 0, v[166:167]
	s_mov_b32 m0, s13
	v_lshl_add_u64 v[218:219], s[14:15], 0, v[172:173]
	global_load_lds_dwordx4 v[216:217], off
	s_add_i32 m0, s13, 0x2000
	v_lshl_add_u64 v[220:221], s[8:9], 0, v[176:177]
	global_load_lds_dwordx4 v[218:219], off
	s_mov_b32 m0, s27
	v_lshl_add_u64 v[222:223], s[8:9], 0, v[174:175]
	global_load_lds_dwordx4 v[220:221], off
	s_mov_b32 m0, s31
	s_nop 0
	global_load_lds_dwordx4 v[222:223], off
	s_waitcnt vmcnt(8)
	s_waitcnt lgkmcnt(0)
	s_barrier
	s_waitcnt lgkmcnt(0)
	v_mfma_f32_16x16x32_bf16 v[62:65], v[130:133], v[162:165], v[62:65]
	v_mfma_f32_16x16x32_bf16 v[62:65], v[134:137], v[184:187], v[62:65]
	v_mfma_f32_16x16x32_bf16 v[46:49], v[130:133], v[188:191], v[46:49]
	v_mfma_f32_16x16x32_bf16 v[46:49], v[134:137], v[192:195], v[46:49]
	v_mfma_f32_16x16x32_bf16 v[30:33], v[130:133], v[196:199], v[30:33]
	v_mfma_f32_16x16x32_bf16 v[30:33], v[134:137], v[200:203], v[30:33]
	v_mfma_f32_16x16x32_bf16 v[14:17], v[130:133], v[204:207], v[14:17]
	v_mfma_f32_16x16x32_bf16 v[14:17], v[134:137], v[208:211], v[14:17]
	v_mfma_f32_16x16x32_bf16 v[54:57], v[138:141], v[162:165], v[54:57]
	v_mfma_f32_16x16x32_bf16 v[54:57], v[142:145], v[184:187], v[54:57]
	v_mfma_f32_16x16x32_bf16 v[38:41], v[138:141], v[188:191], v[38:41]
	v_mfma_f32_16x16x32_bf16 v[38:41], v[142:145], v[192:195], v[38:41]
	v_mfma_f32_16x16x32_bf16 v[22:25], v[138:141], v[196:199], v[22:25]
	v_mfma_f32_16x16x32_bf16 v[22:25], v[142:145], v[200:203], v[22:25]
	v_mfma_f32_16x16x32_bf16 v[6:9], v[138:141], v[204:207], v[6:9]
	v_mfma_f32_16x16x32_bf16 v[6:9], v[142:145], v[208:211], v[6:9]
	v_mfma_f32_16x16x32_bf16 v[58:61], v[146:149], v[162:165], v[58:61]
	v_mfma_f32_16x16x32_bf16 v[58:61], v[150:153], v[184:187], v[58:61]
	v_mfma_f32_16x16x32_bf16 v[42:45], v[146:149], v[188:191], v[42:45]
	v_mfma_f32_16x16x32_bf16 v[42:45], v[150:153], v[192:195], v[42:45]
	v_mfma_f32_16x16x32_bf16 v[26:29], v[146:149], v[196:199], v[26:29]
	v_mfma_f32_16x16x32_bf16 v[26:29], v[150:153], v[200:203], v[26:29]
	v_mfma_f32_16x16x32_bf16 v[10:13], v[146:149], v[204:207], v[10:13]
	v_mfma_f32_16x16x32_bf16 v[10:13], v[150:153], v[208:211], v[10:13]
	v_mfma_f32_16x16x32_bf16 v[50:53], v[154:157], v[162:165], v[50:53]
	v_mfma_f32_16x16x32_bf16 v[50:53], v[158:161], v[184:187], v[50:53]
	v_mfma_f32_16x16x32_bf16 v[34:37], v[154:157], v[188:191], v[34:37]
	v_mfma_f32_16x16x32_bf16 v[34:37], v[158:161], v[192:195], v[34:37]
	v_mfma_f32_16x16x32_bf16 v[18:21], v[154:157], v[196:199], v[18:21]
	v_mfma_f32_16x16x32_bf16 v[18:21], v[158:161], v[200:203], v[18:21]
	v_mfma_f32_16x16x32_bf16 v[2:5], v[154:157], v[204:207], v[2:5]
	v_mfma_f32_16x16x32_bf16 v[2:5], v[158:161], v[208:211], v[2:5]
	s_barrier
; #define PG8_STAGE(bufoff, gbase, voff) do { _Pragma("unroll") for (int _i = 0; _i < 2; ++_i) \
;         __builtin_amdgcn_global_load_lds((const unsigned*)((const char*)(gbase) + (voff)[_i]), (PG8_LAS unsigned*)(lds + (bufoff) + ldsw + _i * 8192), 16, 0, 0); } while (0)
; #define PG8_LDA(dst, b, h) do { _Pragma("unroll") for (int m = 0; m < 4; ++m) _Pragma("unroll") for (int k = 0; k < 2; ++k) dst[m][k] = *(const PG8_LAS bf16x8*)(lds + PG8_SA(b, h) + aoff + m * 2048 + k * 1024); } while (0)
; #define PG8_LDB(dst, b, h) do { _Pragma("unroll") for (int n = 0; n < 2; ++n) _Pragma("unroll") for (int k = 0; k < 2; ++k) dst[n][k] = *(const PG8_LAS bf16x8*)(lds + PG8_SB(b, h) + boff + n * 2048 + k * 1024); } while (0)
; #define PG8_MMA(ai, bj, At, Bt) do { __builtin_amdgcn_s_setprio(1); _Pragma("unroll") for (int m = 0; m < 4; ++m) _Pragma("unroll") for (int n = 0; n < 2; ++n) _Pragma("unroll") for (int k = 0; k < 2; ++k) \
;         acc[ai][bj][m][n] = __builtin_amdgcn_mfma_f32_16x16x32_bf16(Bt[n][k], At[m][k], acc[ai][bj][m][n], 0, 0, 0); __builtin_amdgcn_s_setprio(0); } while (0)
; #define PG8_WAIT_V(n) asm volatile("s_waitcnt vmcnt(" #n ")" ::: "memory")
; #define PG8_WAIT_L(n) asm volatile("s_waitcnt lgkmcnt(" #n ")" ::: "memory")
; #define PG8_BAR __builtin_amdgcn_s_barrier()
; #define PG8_SCHED __builtin_amdgcn_sched_barrier(0)
;     ...
;             PG8_LDB(B0, 1, 0); PG8_LDB(B1, 1, 1); PG8_SCHED; PG8_LDA(At, 1, 0); PG8_STAGE(PG8_SA(0, 1), a2 + hstepA, voffA);
;             PG8_WAIT_V(8); PG8_WAIT_L(0); PG8_BAR; PG8_MMA(0, 0, At, B0); PG8_MMA(0, 1, At, B1); PG8_BAR; PG8_SCHED;
;             PG8_LDA(At, 1, 1); PG8_STAGE(PG8_SB(1, 0), b3, voffB); PG8_STAGE(PG8_SB(1, 1), b3 + hstepB, voffB); PG8_STAGE(PG8_SA(1, 0), a3, voffA);
;             PG8_WAIT_V(8); PG8_WAIT_L(0); PG8_BAR; PG8_MMA(1, 0, At, B0); PG8_MMA(1, 1, At, B1); PG8_BAR; PG8_SCHED;
	s_add_i32 s13, 0, 0x18000
	s_add_i32 s14, 0, 0x1c000
	v_add_u32_e32 v142, s13, v249
	v_add_u32_e32 v158, s14, v249
	ds_read_b128 v[130:133], v142
	ds_read_b128 v[134:137], v142 offset:1024
	ds_read_b128 v[138:141], v142 offset:2048
	ds_read_b128 v[142:145], v142 offset:3072
	ds_read_b128 v[146:149], v158
	ds_read_b128 v[150:153], v158 offset:1024
	ds_read_b128 v[154:157], v158 offset:2048
	ds_read_b128 v[158:161], v158 offset:3072
	s_add_u32 s8, s8, s58
	s_addc_u32 s9, s9, s59
	s_mov_b32 m0, s47
	v_lshl_add_u64 v[224:225], s[8:9], 0, v[176:177]
	ds_read_b128 v[162:165], v251 offset:32768
	ds_read_b128 v[184:187], v251 offset:33792
	ds_read_b128 v[188:191], v251 offset:34816
	ds_read_b128 v[192:195], v251 offset:35840
	ds_read_b128 v[196:199], v251 offset:36864
	ds_read_b128 v[200:203], v251 offset:37888
	ds_read_b128 v[204:207], v251 offset:38912
	ds_read_b128 v[208:211], v251 offset:39936
	global_load_lds_dwordx4 v[224:225], off
	v_lshl_add_u64 v[224:225], s[8:9], 0, v[174:175]
	s_mov_b32 m0, s49
	s_nop 0
	global_load_lds_dwordx4 v[224:225], off
	s_waitcnt vmcnt(8)
	s_waitcnt lgkmcnt(0)
	s_barrier
	s_waitcnt lgkmcnt(0)
	v_mfma_f32_16x16x32_bf16 v[122:125], v[130:133], v[162:165], v[122:125]
	v_mfma_f32_16x16x32_bf16 v[122:125], v[134:137], v[184:187], v[122:125]
	v_mfma_f32_16x16x32_bf16 v[110:113], v[130:133], v[188:191], v[110:113]
	v_mfma_f32_16x16x32_bf16 v[110:113], v[134:137], v[192:195], v[110:113]
	v_mfma_f32_16x16x32_bf16 v[94:97], v[130:133], v[196:199], v[94:97]
	v_mfma_f32_16x16x32_bf16 v[94:97], v[134:137], v[200:203], v[94:97]
	v_mfma_f32_16x16x32_bf16 v[78:81], v[130:133], v[204:207], v[78:81]
	v_mfma_f32_16x16x32_bf16 v[78:81], v[134:137], v[208:211], v[78:81]
	v_mfma_f32_16x16x32_bf16 v[118:121], v[138:141], v[162:165], v[118:121]
	v_mfma_f32_16x16x32_bf16 v[118:121], v[142:145], v[184:187], v[118:121]
	v_mfma_f32_16x16x32_bf16 v[102:105], v[138:141], v[188:191], v[102:105]
	v_mfma_f32_16x16x32_bf16 v[102:105], v[142:145], v[192:195], v[102:105]
	v_mfma_f32_16x16x32_bf16 v[86:89], v[138:141], v[196:199], v[86:89]
	v_mfma_f32_16x16x32_bf16 v[86:89], v[142:145], v[200:203], v[86:89]
	v_mfma_f32_16x16x32_bf16 v[70:73], v[138:141], v[204:207], v[70:73]
	v_mfma_f32_16x16x32_bf16 v[70:73], v[142:145], v[208:211], v[70:73]
	v_mfma_f32_16x16x32_bf16 v[126:129], v[146:149], v[162:165], v[126:129]
	v_mfma_f32_16x16x32_bf16 v[126:129], v[150:153], v[184:187], v[126:129]
	v_mfma_f32_16x16x32_bf16 v[106:109], v[146:149], v[188:191], v[106:109]
	v_mfma_f32_16x16x32_bf16 v[106:109], v[150:153], v[192:195], v[106:109]
	v_mfma_f32_16x16x32_bf16 v[90:93], v[146:149], v[196:199], v[90:93]
	v_mfma_f32_16x16x32_bf16 v[90:93], v[150:153], v[200:203], v[90:93]
	v_mfma_f32_16x16x32_bf16 v[74:77], v[146:149], v[204:207], v[74:77]
	v_mfma_f32_16x16x32_bf16 v[74:77], v[150:153], v[208:211], v[74:77]
	v_mfma_f32_16x16x32_bf16 v[114:117], v[154:157], v[162:165], v[114:117]
	v_mfma_f32_16x16x32_bf16 v[114:117], v[158:161], v[184:187], v[114:117]
	v_mfma_f32_16x16x32_bf16 v[98:101], v[154:157], v[188:191], v[98:101]
	v_mfma_f32_16x16x32_bf16 v[98:101], v[158:161], v[192:195], v[98:101]
	v_mfma_f32_16x16x32_bf16 v[82:85], v[154:157], v[196:199], v[82:85]
	v_mfma_f32_16x16x32_bf16 v[82:85], v[158:161], v[200:203], v[82:85]
	v_mfma_f32_16x16x32_bf16 v[66:69], v[154:157], v[204:207], v[66:69]
	v_mfma_f32_16x16x32_bf16 v[66:69], v[158:161], v[208:211], v[66:69]
	s_barrier
	s_add_i32 s8, s13, s0
	v_lshl_add_u64 v[212:213], v[212:213], 0, s[62:63]
	s_mov_b32 m0, s8
	ds_read_b128 v[162:165], v251 offset:49152
	ds_read_b128 v[184:187], v251 offset:50176
	ds_read_b128 v[188:191], v251 offset:51200
	ds_read_b128 v[192:195], v251 offset:52224
	ds_read_b128 v[196:199], v251 offset:53248
	ds_read_b128 v[200:203], v251 offset:54272
	ds_read_b128 v[204:207], v251 offset:55296
	ds_read_b128 v[208:211], v251 offset:56320
	global_load_lds_dwordx4 v[212:213], off
	v_lshl_add_u64 v[212:213], v[214:215], 0, s[62:63]
	s_add_i32 m0, s8, 0x2000
	s_add_i32 s8, s14, s0
	global_load_lds_dwordx4 v[212:213], off
	v_lshl_add_u64 v[212:213], v[216:217], 0, s[62:63]
	s_mov_b32 m0, s8
	s_nop 0
	global_load_lds_dwordx4 v[212:213], off
	v_lshl_add_u64 v[212:213], v[218:219], 0, s[62:63]
	s_add_i32 m0, s8, 0x2000
	s_nop 0
	global_load_lds_dwordx4 v[212:213], off
	v_lshl_add_u64 v[212:213], v[220:221], 0, s[62:63]
	s_mov_b32 m0, s51
	s_nop 0
	global_load_lds_dwordx4 v[212:213], off
	v_lshl_add_u64 v[212:213], v[222:223], 0, s[62:63]
	s_mov_b32 m0, s53
	s_nop 0
	global_load_lds_dwordx4 v[212:213], off
	s_waitcnt vmcnt(8)
	s_waitcnt lgkmcnt(0)
	s_barrier
	s_waitcnt lgkmcnt(0)
	v_mfma_f32_16x16x32_bf16 v[62:65], v[130:133], v[162:165], v[62:65]
	v_mfma_f32_16x16x32_bf16 v[62:65], v[134:137], v[184:187], v[62:65]
	v_mfma_f32_16x16x32_bf16 v[46:49], v[130:133], v[188:191], v[46:49]
	v_mfma_f32_16x16x32_bf16 v[46:49], v[134:137], v[192:195], v[46:49]
	v_mfma_f32_16x16x32_bf16 v[30:33], v[130:133], v[196:199], v[30:33]
	v_mfma_f32_16x16x32_bf16 v[30:33], v[134:137], v[200:203], v[30:33]
	v_mfma_f32_16x16x32_bf16 v[14:17], v[130:133], v[204:207], v[14:17]
	v_mfma_f32_16x16x32_bf16 v[14:17], v[134:137], v[208:211], v[14:17]
	v_mfma_f32_16x16x32_bf16 v[54:57], v[138:141], v[162:165], v[54:57]
	v_mfma_f32_16x16x32_bf16 v[54:57], v[142:145], v[184:187], v[54:57]
	v_mfma_f32_16x16x32_bf16 v[38:41], v[138:141], v[188:191], v[38:41]
	v_mfma_f32_16x16x32_bf16 v[38:41], v[142:145], v[192:195], v[38:41]
	v_mfma_f32_16x16x32_bf16 v[22:25], v[138:141], v[196:199], v[22:25]
	v_mfma_f32_16x16x32_bf16 v[22:25], v[142:145], v[200:203], v[22:25]
	v_mfma_f32_16x16x32_bf16 v[6:9], v[138:141], v[204:207], v[6:9]
	v_mfma_f32_16x16x32_bf16 v[6:9], v[142:145], v[208:211], v[6:9]
	v_mfma_f32_16x16x32_bf16 v[58:61], v[146:149], v[162:165], v[58:61]
	v_mfma_f32_16x16x32_bf16 v[58:61], v[150:153], v[184:187], v[58:61]
	v_mfma_f32_16x16x32_bf16 v[42:45], v[146:149], v[188:191], v[42:45]
	v_mfma_f32_16x16x32_bf16 v[42:45], v[150:153], v[192:195], v[42:45]
	v_mfma_f32_16x16x32_bf16 v[26:29], v[146:149], v[196:199], v[26:29]
	v_mfma_f32_16x16x32_bf16 v[26:29], v[150:153], v[200:203], v[26:29]
	v_mfma_f32_16x16x32_bf16 v[10:13], v[146:149], v[204:207], v[10:13]
	v_mfma_f32_16x16x32_bf16 v[10:13], v[150:153], v[208:211], v[10:13]
	v_mfma_f32_16x16x32_bf16 v[50:53], v[154:157], v[162:165], v[50:53]
	v_mfma_f32_16x16x32_bf16 v[50:53], v[158:161], v[184:187], v[50:53]
	v_mfma_f32_16x16x32_bf16 v[34:37], v[154:157], v[188:191], v[34:37]
	v_mfma_f32_16x16x32_bf16 v[34:37], v[158:161], v[192:195], v[34:37]
	v_mfma_f32_16x16x32_bf16 v[18:21], v[154:157], v[196:199], v[18:21]
	v_mfma_f32_16x16x32_bf16 v[18:21], v[158:161], v[200:203], v[18:21]
	v_mfma_f32_16x16x32_bf16 v[2:5], v[154:157], v[204:207], v[2:5]
	v_mfma_f32_16x16x32_bf16 v[2:5], v[158:161], v[208:211], v[2:5]
	s_barrier
	s_add_u32 s10, s10, 0x100
	s_addc_u32 s11, s11, 0
	s_add_u32 s6, s6, 0x100
	s_addc_u32 s7, s7, 0
	s_cmp_ge_i32 s12, s55
	s_mov_b32 s8, s12
	s_cbranch_scc0 .LBB0_288

; #define PG8_STAGE(bufoff, gbase, voff) do { _Pragma("unroll") for (int _i = 0; _i < 2; ++_i) \
;         __builtin_amdgcn_global_load_lds((const unsigned*)((const char*)(gbase) + (voff)[_i]), (PG8_LAS unsigned*)(lds + (bufoff) + ldsw + _i * 8192), 16, 0, 0); } while (0)
; #define PG8_LDA(dst, b, h) do { _Pragma("unroll") for (int m = 0; m < 4; ++m) _Pragma("unroll") for (int k = 0; k < 2; ++k) dst[m][k] = *(const PG8_LAS bf16x8*)(lds + PG8_SA(b, h) + aoff + m * 2048 + k * 1024); } while (0)
; #define PG8_LDB(dst, b, h) do { _Pragma("unroll") for (int n = 0; n < 2; ++n) _Pragma("unroll") for (int k = 0; k < 2; ++k) dst[n][k] = *(const PG8_LAS bf16x8*)(lds + PG8_SB(b, h) + boff + n * 2048 + k * 1024); } while (0)
; #define PG8_MMA(ai, bj, At, Bt) do { __builtin_amdgcn_s_setprio(1); _Pragma("unroll") for (int m = 0; m < 4; ++m) _Pragma("unroll") for (int n = 0; n < 2; ++n) _Pragma("unroll") for (int k = 0; k < 2; ++k) \
;         acc[ai][bj][m][n] = __builtin_amdgcn_mfma_f32_16x16x32_bf16(Bt[n][k], At[m][k], acc[ai][bj][m][n], 0, 0, 0); __builtin_amdgcn_s_setprio(0); } while (0)
; #define PG8_WAIT_V(n) asm volatile("s_waitcnt vmcnt(" #n ")" ::: "memory")
; #define PG8_WAIT_L(n) asm volatile("s_waitcnt lgkmcnt(" #n ")" ::: "memory")
; #define PG8_BAR __builtin_amdgcn_s_barrier()
; #define PG8_SCHED __builtin_amdgcn_sched_barrier(0)
;     ...
;             const char* a1 = cA + (size_t)(t + 1) * kstep;
;             const char* a2 = last ? nA : cA + (size_t)(t + 2) * kstep; const char* b2 = last ? nB : cB + (size_t)(t + 2) * kstep;
;             const char* a3 = a2 + kstep; const char* b3 = b2 + kstep;
;             if (last && has_next) S.a_ready(nxt);
;             if constexpr (SP2) {
;             PG8_LDB(B0, 0, 0); PG8_LDB(B1, 0, 1); PG8_SCHED; PG8_LDA(At, 0, 0); PG8_STAGE(PG8_SA(1, 1), a1 + hstepA, voffA);
;             PG8_WAIT_V(8); PG8_WAIT_L(0); PG8_BAR; PG8_MMA(0, 0, At, B0); PG8_MMA(0, 1, At, B1); PG8_BAR; PG8_SCHED;
;             PG8_LDA(At, 0, 1); PG8_STAGE(PG8_SB(0, 0), b2, voffB); PG8_STAGE(PG8_SB(0, 1), b2 + hstepB, voffB); PG8_STAGE(PG8_SA(0, 0), a2, voffA);
.LBB0_518:
	s_andn2_b64 vcc, exec, s[88:89]
	s_waitcnt lgkmcnt(0)
	s_cbranch_vccnz .LBB0_521
	s_add_u32 s10, s6, 0x100
	s_addc_u32 s11, s7, 0
	v_readlane_b32 s6, v255, 40
	s_add_u32 s6, s8, s6
	s_addc_u32 s7, s9, 0
	s_mov_b32 s8, 0
	s_add_i32 s25, s8, 2
	v_readlane_b32 s27, v255, 40
	s_add_u32 s27, s6, s27
	s_addc_u32 s9, s7, 0
	s_add_i32 s31, 0, 0x10000
	s_cmp_eq_u32 s19, s8
	s_cselect_b32 s9, s43, s9
	s_cselect_b32 s8, s42, s27
	s_cselect_b32 s35, s93, s11
	s_cselect_b32 s34, s92, s10
	s_add_i32 s27, 0, 0x14000
	v_add_u32_e32 v148, s31, v229
	v_add_u32_e32 v164, s27, v229
	ds_read_b128 v[136:139], v148
	ds_read_b128 v[140:143], v148 offset:1024
	ds_read_b128 v[144:147], v148 offset:2048
	ds_read_b128 v[148:151], v148 offset:3072
	ds_read_b128 v[152:155], v164
	ds_read_b128 v[156:159], v164 offset:1024
	ds_read_b128 v[160:163], v164 offset:2048
	ds_read_b128 v[172:175], v164 offset:3072
	v_lshl_add_u64 v[164:165], s[6:7], 0, v[134:135]
	s_add_i32 m0, s2, 0xc000
	ds_read_b128 v[176:179], v231
	ds_read_b128 v[180:183], v231 offset:1024
	ds_read_b128 v[184:187], v231 offset:2048
	ds_read_b128 v[188:191], v231 offset:3072
	ds_read_b128 v[192:195], v231 offset:4096
	ds_read_b128 v[196:199], v231 offset:5120
	ds_read_b128 v[200:203], v231 offset:6144
	ds_read_b128 v[204:207], v231 offset:7168
	global_load_lds_dwordx4 v[164:165], off
	v_lshl_add_u64 v[164:165], s[6:7], 0, v[132:133]
	s_add_i32 m0, s2, 0xe000
	s_nop 0
	global_load_lds_dwordx4 v[164:165], off
	s_waitcnt vmcnt(8)
	s_waitcnt lgkmcnt(0)
	s_barrier
	s_waitcnt lgkmcnt(0)
	v_mfma_f32_16x16x32_bf16 v[126:129], v[136:139], v[176:179], 0
	v_mfma_f32_16x16x32_bf16 v[126:129], v[140:143], v[180:183], v[126:129]
	v_mfma_f32_16x16x32_bf16 v[110:113], v[136:139], v[184:187], 0
	v_mfma_f32_16x16x32_bf16 v[110:113], v[140:143], v[188:191], v[110:113]
	v_mfma_f32_16x16x32_bf16 v[94:97], v[136:139], v[192:195], 0
	v_mfma_f32_16x16x32_bf16 v[94:97], v[140:143], v[196:199], v[94:97]
	v_mfma_f32_16x16x32_bf16 v[78:81], v[136:139], v[200:203], 0
	v_mfma_f32_16x16x32_bf16 v[78:81], v[140:143], v[204:207], v[78:81]
	v_mfma_f32_16x16x32_bf16 v[122:125], v[144:147], v[176:179], 0
	v_mfma_f32_16x16x32_bf16 v[122:125], v[148:151], v[180:183], v[122:125]
	v_mfma_f32_16x16x32_bf16 v[106:109], v[144:147], v[184:187], 0
	v_mfma_f32_16x16x32_bf16 v[106:109], v[148:151], v[188:191], v[106:109]
	v_mfma_f32_16x16x32_bf16 v[90:93], v[144:147], v[192:195], 0
	v_mfma_f32_16x16x32_bf16 v[90:93], v[148:151], v[196:199], v[90:93]
	v_mfma_f32_16x16x32_bf16 v[74:77], v[144:147], v[200:203], 0
	v_mfma_f32_16x16x32_bf16 v[74:77], v[148:151], v[204:207], v[74:77]
	v_mfma_f32_16x16x32_bf16 v[118:121], v[152:155], v[176:179], 0
	v_mfma_f32_16x16x32_bf16 v[118:121], v[156:159], v[180:183], v[118:121]
	v_mfma_f32_16x16x32_bf16 v[102:105], v[152:155], v[184:187], 0
	v_mfma_f32_16x16x32_bf16 v[102:105], v[156:159], v[188:191], v[102:105]
	v_mfma_f32_16x16x32_bf16 v[86:89], v[152:155], v[192:195], 0
	v_mfma_f32_16x16x32_bf16 v[86:89], v[156:159], v[196:199], v[86:89]
	v_mfma_f32_16x16x32_bf16 v[70:73], v[152:155], v[200:203], 0
	v_mfma_f32_16x16x32_bf16 v[70:73], v[156:159], v[204:207], v[70:73]
	v_mfma_f32_16x16x32_bf16 v[114:117], v[160:163], v[176:179], 0
	v_mfma_f32_16x16x32_bf16 v[114:117], v[172:175], v[180:183], v[114:117]
	v_mfma_f32_16x16x32_bf16 v[98:101], v[160:163], v[184:187], 0
	v_mfma_f32_16x16x32_bf16 v[98:101], v[172:175], v[188:191], v[98:101]
	v_mfma_f32_16x16x32_bf16 v[82:85], v[160:163], v[192:195], 0
	v_mfma_f32_16x16x32_bf16 v[82:85], v[172:175], v[196:199], v[82:85]
	v_mfma_f32_16x16x32_bf16 v[66:69], v[160:163], v[200:203], 0
	v_mfma_f32_16x16x32_bf16 v[66:69], v[172:175], v[204:207], v[66:69]
	s_barrier
	s_add_i32 s31, s31, s0
	v_lshl_add_u64 v[164:165], s[34:35], 0, v[166:167]
	s_mov_b32 m0, s31
	ds_read_b128 v[176:179], v231 offset:16384
	ds_read_b128 v[180:183], v231 offset:17408
	ds_read_b128 v[184:187], v231 offset:18432
	ds_read_b128 v[188:191], v231 offset:19456
	ds_read_b128 v[192:195], v231 offset:20480
	ds_read_b128 v[196:199], v231 offset:21504
	ds_read_b128 v[200:203], v231 offset:22528
	ds_read_b128 v[204:207], v231 offset:23552
	global_load_lds_dwordx4 v[164:165], off
	s_add_i32 m0, s31, 0x2000
	v_lshl_add_u64 v[168:169], s[34:35], 0, v[130:131]
	s_add_u32 s34, s34, s60
	s_addc_u32 s35, s35, s61
	s_add_i32 s27, s27, s0
	global_load_lds_dwordx4 v[168:169], off
	v_lshl_add_u64 v[170:171], s[34:35], 0, v[166:167]
	s_mov_b32 m0, s27
	v_lshl_add_u64 v[208:209], s[34:35], 0, v[130:131]
	global_load_lds_dwordx4 v[170:171], off
	s_add_i32 m0, s27, 0x2000
	v_lshl_add_u64 v[210:211], s[8:9], 0, v[246:247]
	global_load_lds_dwordx4 v[208:209], off
	s_mov_b32 m0, s2
	v_lshl_add_u64 v[212:213], s[8:9], 0, v[248:249]
	global_load_lds_dwordx4 v[210:211], off
	s_mov_b32 m0, s3
	s_nop 0
	global_load_lds_dwordx4 v[212:213], off
	s_waitcnt vmcnt(8)
	s_waitcnt lgkmcnt(0)
	s_barrier
; #define PG8_STAGE(bufoff, gbase, voff) do { _Pragma("unroll") for (int _i = 0; _i < 2; ++_i) \
;         __builtin_amdgcn_global_load_lds((const unsigned*)((const char*)(gbase) + (voff)[_i]), (PG8_LAS unsigned*)(lds + (bufoff) + ldsw + _i * 8192), 16, 0, 0); } while (0)
; #define PG8_LDA(dst, b, h) do { _Pragma("unroll") for (int m = 0; m < 4; ++m) _Pragma("unroll") for (int k = 0; k < 2; ++k) dst[m][k] = *(const PG8_LAS bf16x8*)(lds + PG8_SA(b, h) + aoff + m * 2048 + k * 1024); } while (0)
; #define PG8_LDB(dst, b, h) do { _Pragma("unroll") for (int n = 0; n < 2; ++n) _Pragma("unroll") for (int k = 0; k < 2; ++k) dst[n][k] = *(const PG8_LAS bf16x8*)(lds + PG8_SB(b, h) + boff + n * 2048 + k * 1024); } while (0)
; #define PG8_MMA(ai, bj, At, Bt) do { __builtin_amdgcn_s_setprio(1); _Pragma("unroll") for (int m = 0; m < 4; ++m) _Pragma("unroll") for (int n = 0; n < 2; ++n) _Pragma("unroll") for (int k = 0; k < 2; ++k) \
;         acc[ai][bj][m][n] = __builtin_amdgcn_mfma_f32_16x16x32_bf16(Bt[n][k], At[m][k], acc[ai][bj][m][n], 0, 0, 0); __builtin_amdgcn_s_setprio(0); } while (0)
; #define PG8_WAIT_V(n) asm volatile("s_waitcnt vmcnt(" #n ")" ::: "memory")
; #define PG8_WAIT_L(n) asm volatile("s_waitcnt lgkmcnt(" #n ")" ::: "memory")
; #define PG8_BAR __builtin_amdgcn_s_barrier()
; #define PG8_SCHED __builtin_amdgcn_sched_barrier(0)
;     ...
;             PG8_WAIT_V(8); PG8_WAIT_L(0); PG8_BAR; PG8_MMA(1, 0, At, B0); PG8_MMA(1, 1, At, B1); PG8_BAR; PG8_SCHED;
;             PG8_LDB(B0, 1, 0); PG8_LDB(B1, 1, 1); PG8_SCHED; PG8_LDA(At, 1, 0); PG8_STAGE(PG8_SA(0, 1), a2 + hstepA, voffA);
;             PG8_WAIT_V(8); PG8_WAIT_L(0); PG8_BAR; PG8_MMA(0, 0, At, B0); PG8_MMA(0, 1, At, B1); PG8_BAR; PG8_SCHED;
	s_waitcnt lgkmcnt(0)
	v_mfma_f32_16x16x32_bf16 v[62:65], v[136:139], v[176:179], 0
	v_mfma_f32_16x16x32_bf16 v[62:65], v[140:143], v[180:183], v[62:65]
	v_mfma_f32_16x16x32_bf16 v[46:49], v[136:139], v[184:187], 0
	v_mfma_f32_16x16x32_bf16 v[46:49], v[140:143], v[188:191], v[46:49]
	v_mfma_f32_16x16x32_bf16 v[30:33], v[136:139], v[192:195], 0
	v_mfma_f32_16x16x32_bf16 v[30:33], v[140:143], v[196:199], v[30:33]
	v_mfma_f32_16x16x32_bf16 v[14:17], v[136:139], v[200:203], 0
	v_mfma_f32_16x16x32_bf16 v[14:17], v[140:143], v[204:207], v[14:17]
	v_mfma_f32_16x16x32_bf16 v[58:61], v[144:147], v[176:179], 0
	v_mfma_f32_16x16x32_bf16 v[58:61], v[148:151], v[180:183], v[58:61]
	v_mfma_f32_16x16x32_bf16 v[42:45], v[144:147], v[184:187], 0
	v_mfma_f32_16x16x32_bf16 v[42:45], v[148:151], v[188:191], v[42:45]
	v_mfma_f32_16x16x32_bf16 v[26:29], v[144:147], v[192:195], 0
	v_mfma_f32_16x16x32_bf16 v[26:29], v[148:151], v[196:199], v[26:29]
	v_mfma_f32_16x16x32_bf16 v[10:13], v[144:147], v[200:203], 0
	v_mfma_f32_16x16x32_bf16 v[10:13], v[148:151], v[204:207], v[10:13]
	v_mfma_f32_16x16x32_bf16 v[54:57], v[152:155], v[176:179], 0
	v_mfma_f32_16x16x32_bf16 v[54:57], v[156:159], v[180:183], v[54:57]
	v_mfma_f32_16x16x32_bf16 v[38:41], v[152:155], v[184:187], 0
	v_mfma_f32_16x16x32_bf16 v[38:41], v[156:159], v[188:191], v[38:41]
	v_mfma_f32_16x16x32_bf16 v[22:25], v[152:155], v[192:195], 0
	v_mfma_f32_16x16x32_bf16 v[22:25], v[156:159], v[196:199], v[22:25]
	v_mfma_f32_16x16x32_bf16 v[6:9], v[152:155], v[200:203], 0
	v_mfma_f32_16x16x32_bf16 v[6:9], v[156:159], v[204:207], v[6:9]
	v_mfma_f32_16x16x32_bf16 v[50:53], v[160:163], v[176:179], 0
	v_mfma_f32_16x16x32_bf16 v[50:53], v[172:175], v[180:183], v[50:53]
	v_mfma_f32_16x16x32_bf16 v[34:37], v[160:163], v[184:187], 0
	v_mfma_f32_16x16x32_bf16 v[34:37], v[172:175], v[188:191], v[34:37]
	v_mfma_f32_16x16x32_bf16 v[18:21], v[160:163], v[192:195], 0
	v_mfma_f32_16x16x32_bf16 v[18:21], v[172:175], v[196:199], v[18:21]
	v_mfma_f32_16x16x32_bf16 v[2:5], v[160:163], v[200:203], 0
	v_mfma_f32_16x16x32_bf16 v[2:5], v[172:175], v[204:207], v[2:5]
	s_barrier
	s_add_i32 s27, 0, 0x18000
	s_add_i32 s31, 0, 0x1c000
	v_add_u32_e32 v148, s27, v229
	v_add_u32_e32 v172, s31, v229
	ds_read_b128 v[136:139], v148
	ds_read_b128 v[140:143], v148 offset:1024
	ds_read_b128 v[144:147], v148 offset:2048
	ds_read_b128 v[148:151], v148 offset:3072
	ds_read_b128 v[152:155], v172
	ds_read_b128 v[156:159], v172 offset:1024
	ds_read_b128 v[160:163], v172 offset:2048
	ds_read_b128 v[172:175], v172 offset:3072
	s_add_u32 s8, s8, s101
	s_addc_u32 s9, s9, 0
	s_mov_b32 m0, s14
	v_lshl_add_u64 v[214:215], s[8:9], 0, v[246:247]
	ds_read_b128 v[176:179], v231 offset:32768
	ds_read_b128 v[180:183], v231 offset:33792
	ds_read_b128 v[184:187], v231 offset:34816
	ds_read_b128 v[188:191], v231 offset:35840
	ds_read_b128 v[192:195], v231 offset:36864
	ds_read_b128 v[196:199], v231 offset:37888
	ds_read_b128 v[200:203], v231 offset:38912
	ds_read_b128 v[204:207], v231 offset:39936
	global_load_lds_dwordx4 v[214:215], off
	v_lshl_add_u64 v[214:215], s[8:9], 0, v[248:249]
	s_mov_b32 m0, s15
	s_nop 0
	global_load_lds_dwordx4 v[214:215], off
	s_waitcnt vmcnt(8)
	s_waitcnt lgkmcnt(0)
	s_barrier
	s_waitcnt lgkmcnt(0)
	v_mfma_f32_16x16x32_bf16 v[126:129], v[136:139], v[176:179], v[126:129]
	v_mfma_f32_16x16x32_bf16 v[126:129], v[140:143], v[180:183], v[126:129]
	v_mfma_f32_16x16x32_bf16 v[110:113], v[136:139], v[184:187], v[110:113]
	v_mfma_f32_16x16x32_bf16 v[110:113], v[140:143], v[188:191], v[110:113]
	v_mfma_f32_16x16x32_bf16 v[94:97], v[136:139], v[192:195], v[94:97]
	v_mfma_f32_16x16x32_bf16 v[94:97], v[140:143], v[196:199], v[94:97]
	v_mfma_f32_16x16x32_bf16 v[78:81], v[136:139], v[200:203], v[78:81]
	v_mfma_f32_16x16x32_bf16 v[78:81], v[140:143], v[204:207], v[78:81]
	v_mfma_f32_16x16x32_bf16 v[122:125], v[144:147], v[176:179], v[122:125]
	v_mfma_f32_16x16x32_bf16 v[122:125], v[148:151], v[180:183], v[122:125]
	v_mfma_f32_16x16x32_bf16 v[106:109], v[144:147], v[184:187], v[106:109]
	v_mfma_f32_16x16x32_bf16 v[106:109], v[148:151], v[188:191], v[106:109]
	v_mfma_f32_16x16x32_bf16 v[90:93], v[144:147], v[192:195], v[90:93]
	v_mfma_f32_16x16x32_bf16 v[90:93], v[148:151], v[196:199], v[90:93]
	v_mfma_f32_16x16x32_bf16 v[74:77], v[144:147], v[200:203], v[74:77]
	v_mfma_f32_16x16x32_bf16 v[74:77], v[148:151], v[204:207], v[74:77]
	v_mfma_f32_16x16x32_bf16 v[118:121], v[152:155], v[176:179], v[118:121]
	v_mfma_f32_16x16x32_bf16 v[118:121], v[156:159], v[180:183], v[118:121]
	v_mfma_f32_16x16x32_bf16 v[102:105], v[152:155], v[184:187], v[102:105]
	v_mfma_f32_16x16x32_bf16 v[102:105], v[156:159], v[188:191], v[102:105]
	v_mfma_f32_16x16x32_bf16 v[86:89], v[152:155], v[192:195], v[86:89]
	v_mfma_f32_16x16x32_bf16 v[86:89], v[156:159], v[196:199], v[86:89]
	v_mfma_f32_16x16x32_bf16 v[70:73], v[152:155], v[200:203], v[70:73]
	v_mfma_f32_16x16x32_bf16 v[70:73], v[156:159], v[204:207], v[70:73]
	v_mfma_f32_16x16x32_bf16 v[114:117], v[160:163], v[176:179], v[114:117]
	v_mfma_f32_16x16x32_bf16 v[114:117], v[172:175], v[180:183], v[114:117]
	v_mfma_f32_16x16x32_bf16 v[98:101], v[160:163], v[184:187], v[98:101]
	v_mfma_f32_16x16x32_bf16 v[98:101], v[172:175], v[188:191], v[98:101]
	v_mfma_f32_16x16x32_bf16 v[82:85], v[160:163], v[192:195], v[82:85]
	v_mfma_f32_16x16x32_bf16 v[82:85], v[172:175], v[196:199], v[82:85]
	v_mfma_f32_16x16x32_bf16 v[66:69], v[160:163], v[200:203], v[66:69]
	v_mfma_f32_16x16x32_bf16 v[66:69], v[172:175], v[204:207], v[66:69]
	s_barrier
; #define PG8_STAGE(bufoff, gbase, voff) do { _Pragma("unroll") for (int _i = 0; _i < 2; ++_i) \
;         __builtin_amdgcn_global_load_lds((const unsigned*)((const char*)(gbase) + (voff)[_i]), (PG8_LAS unsigned*)(lds + (bufoff) + ldsw + _i * 8192), 16, 0, 0); } while (0)
; #define PG8_LDA(dst, b, h) do { _Pragma("unroll") for (int m = 0; m < 4; ++m) _Pragma("unroll") for (int k = 0; k < 2; ++k) dst[m][k] = *(const PG8_LAS bf16x8*)(lds + PG8_SA(b, h) + aoff + m * 2048 + k * 1024); } while (0)
; #define PG8_LDB(dst, b, h) do { _Pragma("unroll") for (int n = 0; n < 2; ++n) _Pragma("unroll") for (int k = 0; k < 2; ++k) dst[n][k] = *(const PG8_LAS bf16x8*)(lds + PG8_SB(b, h) + boff + n * 2048 + k * 1024); } while (0)
; #define PG8_MMA(ai, bj, At, Bt) do { __builtin_amdgcn_s_setprio(1); _Pragma("unroll") for (int m = 0; m < 4; ++m) _Pragma("unroll") for (int n = 0; n < 2; ++n) _Pragma("unroll") for (int k = 0; k < 2; ++k) \
;         acc[ai][bj][m][n] = __builtin_amdgcn_mfma_f32_16x16x32_bf16(Bt[n][k], At[m][k], acc[ai][bj][m][n], 0, 0, 0); __builtin_amdgcn_s_setprio(0); } while (0)
; #define PG8_WAIT_V(n) asm volatile("s_waitcnt vmcnt(" #n ")" ::: "memory")
; #define PG8_WAIT_L(n) asm volatile("s_waitcnt lgkmcnt(" #n ")" ::: "memory")
; #define PG8_BAR __builtin_amdgcn_s_barrier()
; #define PG8_SCHED __builtin_amdgcn_sched_barrier(0)
;     ...
;             const char* a1 = cA + (size_t)(t + 1) * kstep;
;             const char* a2 = last ? nA : cA + (size_t)(t + 2) * kstep; const char* b2 = last ? nB : cB + (size_t)(t + 2) * kstep;
;             const char* a3 = a2 + kstep; const char* b3 = b2 + kstep;
;             if (last && has_next) S.a_ready(nxt);
;             if constexpr (SP2) {
;             PG8_LDB(B0, 0, 0); PG8_LDB(B1, 0, 1); PG8_SCHED; PG8_LDA(At, 0, 0); PG8_STAGE(PG8_SA(1, 1), a1 + hstepA, voffA);
;             PG8_WAIT_V(8); PG8_WAIT_L(0); PG8_BAR; PG8_MMA(0, 0, At, B0); PG8_MMA(0, 1, At, B1); PG8_BAR; PG8_SCHED;
;     ...
;             PG8_LDA(At, 1, 1); PG8_STAGE(PG8_SB(1, 0), b3, voffB); PG8_STAGE(PG8_SB(1, 1), b3 + hstepB, voffB); PG8_STAGE(PG8_SA(1, 0), a3, voffA);
;             PG8_WAIT_V(8); PG8_WAIT_L(0); PG8_BAR; PG8_MMA(1, 0, At, B0); PG8_MMA(1, 1, At, B1); PG8_BAR; PG8_SCHED;
	s_add_i32 s8, s27, s0
	v_lshl_add_u64 v[164:165], v[164:165], 0, s[62:63]
	s_mov_b32 m0, s8
	ds_read_b128 v[176:179], v231 offset:49152
	ds_read_b128 v[180:183], v231 offset:50176
	ds_read_b128 v[184:187], v231 offset:51200
	ds_read_b128 v[188:191], v231 offset:52224
	ds_read_b128 v[192:195], v231 offset:53248
	ds_read_b128 v[196:199], v231 offset:54272
	ds_read_b128 v[200:203], v231 offset:55296
	ds_read_b128 v[204:207], v231 offset:56320
	global_load_lds_dwordx4 v[164:165], off
	v_lshl_add_u64 v[164:165], v[168:169], 0, s[62:63]
	s_add_i32 m0, s8, 0x2000
	s_add_i32 s8, s31, s0
	global_load_lds_dwordx4 v[164:165], off
	v_lshl_add_u64 v[164:165], v[170:171], 0, s[62:63]
	s_mov_b32 m0, s8
	s_nop 0
	global_load_lds_dwordx4 v[164:165], off
	v_lshl_add_u64 v[164:165], v[208:209], 0, s[62:63]
	s_add_i32 m0, s8, 0x2000
	s_nop 0
	global_load_lds_dwordx4 v[164:165], off
	v_lshl_add_u64 v[164:165], v[210:211], 0, v[244:245]
	s_mov_b32 m0, s17
	s_nop 0
	global_load_lds_dwordx4 v[164:165], off
	v_lshl_add_u64 v[164:165], v[212:213], 0, v[244:245]
	s_mov_b32 m0, s18
	s_nop 0
	global_load_lds_dwordx4 v[164:165], off
	s_waitcnt vmcnt(8)
	s_waitcnt lgkmcnt(0)
	s_barrier
	s_waitcnt lgkmcnt(0)
	v_mfma_f32_16x16x32_bf16 v[62:65], v[136:139], v[176:179], v[62:65]
	v_mfma_f32_16x16x32_bf16 v[62:65], v[140:143], v[180:183], v[62:65]
	v_mfma_f32_16x16x32_bf16 v[46:49], v[136:139], v[184:187], v[46:49]
	v_mfma_f32_16x16x32_bf16 v[46:49], v[140:143], v[188:191], v[46:49]
	v_mfma_f32_16x16x32_bf16 v[30:33], v[136:139], v[192:195], v[30:33]
	v_mfma_f32_16x16x32_bf16 v[30:33], v[140:143], v[196:199], v[30:33]
	v_mfma_f32_16x16x32_bf16 v[14:17], v[136:139], v[200:203], v[14:17]
	v_mfma_f32_16x16x32_bf16 v[14:17], v[140:143], v[204:207], v[14:17]
	v_mfma_f32_16x16x32_bf16 v[58:61], v[144:147], v[176:179], v[58:61]
	v_mfma_f32_16x16x32_bf16 v[58:61], v[148:151], v[180:183], v[58:61]
	v_mfma_f32_16x16x32_bf16 v[42:45], v[144:147], v[184:187], v[42:45]
	v_mfma_f32_16x16x32_bf16 v[42:45], v[148:151], v[188:191], v[42:45]
	v_mfma_f32_16x16x32_bf16 v[26:29], v[144:147], v[192:195], v[26:29]
	v_mfma_f32_16x16x32_bf16 v[26:29], v[148:151], v[196:199], v[26:29]
	v_mfma_f32_16x16x32_bf16 v[10:13], v[144:147], v[200:203], v[10:13]
	v_mfma_f32_16x16x32_bf16 v[10:13], v[148:151], v[204:207], v[10:13]
	v_mfma_f32_16x16x32_bf16 v[54:57], v[152:155], v[176:179], v[54:57]
	v_mfma_f32_16x16x32_bf16 v[54:57], v[156:159], v[180:183], v[54:57]
	v_mfma_f32_16x16x32_bf16 v[38:41], v[152:155], v[184:187], v[38:41]
	v_mfma_f32_16x16x32_bf16 v[38:41], v[156:159], v[188:191], v[38:41]
	v_mfma_f32_16x16x32_bf16 v[22:25], v[152:155], v[192:195], v[22:25]
	v_mfma_f32_16x16x32_bf16 v[22:25], v[156:159], v[196:199], v[22:25]
	v_mfma_f32_16x16x32_bf16 v[6:9], v[152:155], v[200:203], v[6:9]
	v_mfma_f32_16x16x32_bf16 v[6:9], v[156:159], v[204:207], v[6:9]
	v_mfma_f32_16x16x32_bf16 v[50:53], v[160:163], v[176:179], v[50:53]
	v_mfma_f32_16x16x32_bf16 v[50:53], v[172:175], v[180:183], v[50:53]
	v_mfma_f32_16x16x32_bf16 v[34:37], v[160:163], v[184:187], v[34:37]
	v_mfma_f32_16x16x32_bf16 v[34:37], v[172:175], v[188:191], v[34:37]
	v_mfma_f32_16x16x32_bf16 v[18:21], v[160:163], v[192:195], v[18:21]
	v_mfma_f32_16x16x32_bf16 v[18:21], v[172:175], v[196:199], v[18:21]
	v_mfma_f32_16x16x32_bf16 v[2:5], v[160:163], v[200:203], v[2:5]
	v_mfma_f32_16x16x32_bf16 v[2:5], v[172:175], v[204:207], v[2:5]
	s_barrier
	s_add_u32 s10, s10, 0x100
	s_addc_u32 s11, s11, 0
	v_readlane_b32 s31, v255, 41
	s_add_u32 s6, s6, s31
	s_addc_u32 s7, s7, 0
	s_cmp_ge_i32 s25, s13
	s_mov_b32 s8, s25
	s_cbranch_scc1 .LBB0_521
.LBB0_520:
	s_add_i32 s25, s8, 2
	v_readlane_b32 s27, v255, 40
	s_add_u32 s27, s6, s27
	s_addc_u32 s9, s7, 0
	s_add_i32 s31, 0, 0x10000
	s_cmp_eq_u32 s19, s8
	s_cselect_b32 s9, s43, s9
	s_cselect_b32 s8, s42, s27
	s_cselect_b32 s35, s93, s11
	s_cselect_b32 s34, s92, s10
	s_add_i32 s27, 0, 0x14000
	v_add_u32_e32 v148, s31, v229
	v_add_u32_e32 v164, s27, v229
	ds_read_b128 v[136:139], v148
	ds_read_b128 v[140:143], v148 offset:1024
	ds_read_b128 v[144:147], v148 offset:2048
	ds_read_b128 v[148:151], v148 offset:3072
	ds_read_b128 v[152:155], v164
	ds_read_b128 v[156:159], v164 offset:1024
	ds_read_b128 v[160:163], v164 offset:2048
	ds_read_b128 v[172:175], v164 offset:3072
	v_lshl_add_u64 v[164:165], s[6:7], 0, v[134:135]
	s_add_i32 m0, s2, 0xc000
	ds_read_b128 v[176:179], v231
	ds_read_b128 v[180:183], v231 offset:1024
	ds_read_b128 v[184:187], v231 offset:2048
	ds_read_b128 v[188:191], v231 offset:3072
	ds_read_b128 v[192:195], v231 offset:4096
	ds_read_b128 v[196:199], v231 offset:5120
	ds_read_b128 v[200:203], v231 offset:6144
	ds_read_b128 v[204:207], v231 offset:7168
	global_load_lds_dwordx4 v[164:165], off
	v_lshl_add_u64 v[164:165], s[6:7], 0, v[132:133]
	s_add_i32 m0, s2, 0xe000
	s_nop 0
	global_load_lds_dwordx4 v[164:165], off
	s_waitcnt vmcnt(8)
	s_waitcnt lgkmcnt(0)
	s_barrier
; #define PG8_STAGE(bufoff, gbase, voff) do { _Pragma("unroll") for (int _i = 0; _i < 2; ++_i) \
;         __builtin_amdgcn_global_load_lds((const unsigned*)((const char*)(gbase) + (voff)[_i]), (PG8_LAS unsigned*)(lds + (bufoff) + ldsw + _i * 8192), 16, 0, 0); } while (0)
; #define PG8_LDA(dst, b, h) do { _Pragma("unroll") for (int m = 0; m < 4; ++m) _Pragma("unroll") for (int k = 0; k < 2; ++k) dst[m][k] = *(const PG8_LAS bf16x8*)(lds + PG8_SA(b, h) + aoff + m * 2048 + k * 1024); } while (0)
; #define PG8_MMA(ai, bj, At, Bt) do { __builtin_amdgcn_s_setprio(1); _Pragma("unroll") for (int m = 0; m < 4; ++m) _Pragma("unroll") for (int n = 0; n < 2; ++n) _Pragma("unroll") for (int k = 0; k < 2; ++k) \
;         acc[ai][bj][m][n] = __builtin_amdgcn_mfma_f32_16x16x32_bf16(Bt[n][k], At[m][k], acc[ai][bj][m][n], 0, 0, 0); __builtin_amdgcn_s_setprio(0); } while (0)
; #define PG8_WAIT_V(n) asm volatile("s_waitcnt vmcnt(" #n ")" ::: "memory")
; #define PG8_WAIT_L(n) asm volatile("s_waitcnt lgkmcnt(" #n ")" ::: "memory")
; #define PG8_BAR __builtin_amdgcn_s_barrier()
; #define PG8_SCHED __builtin_amdgcn_sched_barrier(0)
;     ...
;             PG8_WAIT_V(8); PG8_WAIT_L(0); PG8_BAR; PG8_MMA(0, 0, At, B0); PG8_MMA(0, 1, At, B1); PG8_BAR; PG8_SCHED;
;             PG8_LDA(At, 0, 1); PG8_STAGE(PG8_SB(0, 0), b2, voffB); PG8_STAGE(PG8_SB(0, 1), b2 + hstepB, voffB); PG8_STAGE(PG8_SA(0, 0), a2, voffA);
;             PG8_WAIT_V(8); PG8_WAIT_L(0); PG8_BAR; PG8_MMA(1, 0, At, B0); PG8_MMA(1, 1, At, B1); PG8_BAR; PG8_SCHED;
	s_waitcnt lgkmcnt(0)
	v_mfma_f32_16x16x32_bf16 v[126:129], v[136:139], v[176:179], v[126:129]
	v_mfma_f32_16x16x32_bf16 v[126:129], v[140:143], v[180:183], v[126:129]
	v_mfma_f32_16x16x32_bf16 v[110:113], v[136:139], v[184:187], v[110:113]
	v_mfma_f32_16x16x32_bf16 v[110:113], v[140:143], v[188:191], v[110:113]
	v_mfma_f32_16x16x32_bf16 v[94:97], v[136:139], v[192:195], v[94:97]
	v_mfma_f32_16x16x32_bf16 v[94:97], v[140:143], v[196:199], v[94:97]
	v_mfma_f32_16x16x32_bf16 v[78:81], v[136:139], v[200:203], v[78:81]
	v_mfma_f32_16x16x32_bf16 v[78:81], v[140:143], v[204:207], v[78:81]
	v_mfma_f32_16x16x32_bf16 v[122:125], v[144:147], v[176:179], v[122:125]
	v_mfma_f32_16x16x32_bf16 v[122:125], v[148:151], v[180:183], v[122:125]
	v_mfma_f32_16x16x32_bf16 v[106:109], v[144:147], v[184:187], v[106:109]
	v_mfma_f32_16x16x32_bf16 v[106:109], v[148:151], v[188:191], v[106:109]
	v_mfma_f32_16x16x32_bf16 v[90:93], v[144:147], v[192:195], v[90:93]
	v_mfma_f32_16x16x32_bf16 v[90:93], v[148:151], v[196:199], v[90:93]
	v_mfma_f32_16x16x32_bf16 v[74:77], v[144:147], v[200:203], v[74:77]
	v_mfma_f32_16x16x32_bf16 v[74:77], v[148:151], v[204:207], v[74:77]
	v_mfma_f32_16x16x32_bf16 v[118:121], v[152:155], v[176:179], v[118:121]
	v_mfma_f32_16x16x32_bf16 v[118:121], v[156:159], v[180:183], v[118:121]
	v_mfma_f32_16x16x32_bf16 v[102:105], v[152:155], v[184:187], v[102:105]
	v_mfma_f32_16x16x32_bf16 v[102:105], v[156:159], v[188:191], v[102:105]
	v_mfma_f32_16x16x32_bf16 v[86:89], v[152:155], v[192:195], v[86:89]
	v_mfma_f32_16x16x32_bf16 v[86:89], v[156:159], v[196:199], v[86:89]
	v_mfma_f32_16x16x32_bf16 v[70:73], v[152:155], v[200:203], v[70:73]
	v_mfma_f32_16x16x32_bf16 v[70:73], v[156:159], v[204:207], v[70:73]
	v_mfma_f32_16x16x32_bf16 v[114:117], v[160:163], v[176:179], v[114:117]
	v_mfma_f32_16x16x32_bf16 v[114:117], v[172:175], v[180:183], v[114:117]
	v_mfma_f32_16x16x32_bf16 v[98:101], v[160:163], v[184:187], v[98:101]
	v_mfma_f32_16x16x32_bf16 v[98:101], v[172:175], v[188:191], v[98:101]
	v_mfma_f32_16x16x32_bf16 v[82:85], v[160:163], v[192:195], v[82:85]
	v_mfma_f32_16x16x32_bf16 v[82:85], v[172:175], v[196:199], v[82:85]
	v_mfma_f32_16x16x32_bf16 v[66:69], v[160:163], v[200:203], v[66:69]
	v_mfma_f32_16x16x32_bf16 v[66:69], v[172:175], v[204:207], v[66:69]
	s_barrier
	s_add_i32 s31, s31, s0
	v_lshl_add_u64 v[164:165], s[34:35], 0, v[166:167]
	s_mov_b32 m0, s31
	ds_read_b128 v[176:179], v231 offset:16384
	ds_read_b128 v[180:183], v231 offset:17408
	ds_read_b128 v[184:187], v231 offset:18432
	ds_read_b128 v[188:191], v231 offset:19456
	ds_read_b128 v[192:195], v231 offset:20480
	ds_read_b128 v[196:199], v231 offset:21504
	ds_read_b128 v[200:203], v231 offset:22528
	ds_read_b128 v[204:207], v231 offset:23552
	global_load_lds_dwordx4 v[164:165], off
	s_add_i32 m0, s31, 0x2000
	v_lshl_add_u64 v[168:169], s[34:35], 0, v[130:131]
	s_add_u32 s34, s34, s60
	s_addc_u32 s35, s35, s61
	s_add_i32 s27, s27, s0
	global_load_lds_dwordx4 v[168:169], off
	v_lshl_add_u64 v[170:171], s[34:35], 0, v[166:167]
	s_mov_b32 m0, s27
	v_lshl_add_u64 v[208:209], s[34:35], 0, v[130:131]
	global_load_lds_dwordx4 v[170:171], off
	s_add_i32 m0, s27, 0x2000
	v_lshl_add_u64 v[210:211], s[8:9], 0, v[246:247]
	global_load_lds_dwordx4 v[208:209], off
	s_mov_b32 m0, s2
	v_lshl_add_u64 v[212:213], s[8:9], 0, v[248:249]
	global_load_lds_dwordx4 v[210:211], off
	s_mov_b32 m0, s3
	s_nop 0
	global_load_lds_dwordx4 v[212:213], off
	s_waitcnt vmcnt(8)
	s_waitcnt lgkmcnt(0)
	s_barrier
	s_waitcnt lgkmcnt(0)
	v_mfma_f32_16x16x32_bf16 v[62:65], v[136:139], v[176:179], v[62:65]
	v_mfma_f32_16x16x32_bf16 v[62:65], v[140:143], v[180:183], v[62:65]
	v_mfma_f32_16x16x32_bf16 v[46:49], v[136:139], v[184:187], v[46:49]
	v_mfma_f32_16x16x32_bf16 v[46:49], v[140:143], v[188:191], v[46:49]
	v_mfma_f32_16x16x32_bf16 v[30:33], v[136:139], v[192:195], v[30:33]
	v_mfma_f32_16x16x32_bf16 v[30:33], v[140:143], v[196:199], v[30:33]
	v_mfma_f32_16x16x32_bf16 v[14:17], v[136:139], v[200:203], v[14:17]
	v_mfma_f32_16x16x32_bf16 v[14:17], v[140:143], v[204:207], v[14:17]
	v_mfma_f32_16x16x32_bf16 v[58:61], v[144:147], v[176:179], v[58:61]
	v_mfma_f32_16x16x32_bf16 v[58:61], v[148:151], v[180:183], v[58:61]
	v_mfma_f32_16x16x32_bf16 v[42:45], v[144:147], v[184:187], v[42:45]
	v_mfma_f32_16x16x32_bf16 v[42:45], v[148:151], v[188:191], v[42:45]
	v_mfma_f32_16x16x32_bf16 v[26:29], v[144:147], v[192:195], v[26:29]
	v_mfma_f32_16x16x32_bf16 v[26:29], v[148:151], v[196:199], v[26:29]
	v_mfma_f32_16x16x32_bf16 v[10:13], v[144:147], v[200:203], v[10:13]
	v_mfma_f32_16x16x32_bf16 v[10:13], v[148:151], v[204:207], v[10:13]
	v_mfma_f32_16x16x32_bf16 v[54:57], v[152:155], v[176:179], v[54:57]
	v_mfma_f32_16x16x32_bf16 v[54:57], v[156:159], v[180:183], v[54:57]
	v_mfma_f32_16x16x32_bf16 v[38:41], v[152:155], v[184:187], v[38:41]
	v_mfma_f32_16x16x32_bf16 v[38:41], v[156:159], v[188:191], v[38:41]
	v_mfma_f32_16x16x32_bf16 v[22:25], v[152:155], v[192:195], v[22:25]
	v_mfma_f32_16x16x32_bf16 v[22:25], v[156:159], v[196:199], v[22:25]
	v_mfma_f32_16x16x32_bf16 v[6:9], v[152:155], v[200:203], v[6:9]
	v_mfma_f32_16x16x32_bf16 v[6:9], v[156:159], v[204:207], v[6:9]
	v_mfma_f32_16x16x32_bf16 v[50:53], v[160:163], v[176:179], v[50:53]
	v_mfma_f32_16x16x32_bf16 v[50:53], v[172:175], v[180:183], v[50:53]
	v_mfma_f32_16x16x32_bf16 v[34:37], v[160:163], v[184:187], v[34:37]
	v_mfma_f32_16x16x32_bf16 v[34:37], v[172:175], v[188:191], v[34:37]
	v_mfma_f32_16x16x32_bf16 v[18:21], v[160:163], v[192:195], v[18:21]
	v_mfma_f32_16x16x32_bf16 v[18:21], v[172:175], v[196:199], v[18:21]
	v_mfma_f32_16x16x32_bf16 v[2:5], v[160:163], v[200:203], v[2:5]
	v_mfma_f32_16x16x32_bf16 v[2:5], v[172:175], v[204:207], v[2:5]
	s_barrier
; #define PG8_STAGE(bufoff, gbase, voff) do { _Pragma("unroll") for (int _i = 0; _i < 2; ++_i) \
;         __builtin_amdgcn_global_load_lds((const unsigned*)((const char*)(gbase) + (voff)[_i]), (PG8_LAS unsigned*)(lds + (bufoff) + ldsw + _i * 8192), 16, 0, 0); } while (0)
; #define PG8_LDA(dst, b, h) do { _Pragma("unroll") for (int m = 0; m < 4; ++m) _Pragma("unroll") for (int k = 0; k < 2; ++k) dst[m][k] = *(const PG8_LAS bf16x8*)(lds + PG8_SA(b, h) + aoff + m * 2048 + k * 1024); } while (0)
; #define PG8_LDB(dst, b, h) do { _Pragma("unroll") for (int n = 0; n < 2; ++n) _Pragma("unroll") for (int k = 0; k < 2; ++k) dst[n][k] = *(const PG8_LAS bf16x8*)(lds + PG8_SB(b, h) + boff + n * 2048 + k * 1024); } while (0)
; #define PG8_MMA(ai, bj, At, Bt) do { __builtin_amdgcn_s_setprio(1); _Pragma("unroll") for (int m = 0; m < 4; ++m) _Pragma("unroll") for (int n = 0; n < 2; ++n) _Pragma("unroll") for (int k = 0; k < 2; ++k) \
;         acc[ai][bj][m][n] = __builtin_amdgcn_mfma_f32_16x16x32_bf16(Bt[n][k], At[m][k], acc[ai][bj][m][n], 0, 0, 0); __builtin_amdgcn_s_setprio(0); } while (0)
; #define PG8_WAIT_V(n) asm volatile("s_waitcnt vmcnt(" #n ")" ::: "memory")
; #define PG8_WAIT_L(n) asm volatile("s_waitcnt lgkmcnt(" #n ")" ::: "memory")
; #define PG8_BAR __builtin_amdgcn_s_barrier()
; #define PG8_SCHED __builtin_amdgcn_sched_barrier(0)
;     ...
;             PG8_LDB(B0, 1, 0); PG8_LDB(B1, 1, 1); PG8_SCHED; PG8_LDA(At, 1, 0); PG8_STAGE(PG8_SA(0, 1), a2 + hstepA, voffA);
;             PG8_WAIT_V(8); PG8_WAIT_L(0); PG8_BAR; PG8_MMA(0, 0, At, B0); PG8_MMA(0, 1, At, B1); PG8_BAR; PG8_SCHED;
;             PG8_LDA(At, 1, 1); PG8_STAGE(PG8_SB(1, 0), b3, voffB); PG8_STAGE(PG8_SB(1, 1), b3 + hstepB, voffB); PG8_STAGE(PG8_SA(1, 0), a3, voffA);
;             PG8_WAIT_V(8); PG8_WAIT_L(0); PG8_BAR; PG8_MMA(1, 0, At, B0); PG8_MMA(1, 1, At, B1); PG8_BAR; PG8_SCHED;
	s_add_i32 s27, 0, 0x18000
	s_add_i32 s31, 0, 0x1c000
	v_add_u32_e32 v148, s27, v229
	v_add_u32_e32 v172, s31, v229
	ds_read_b128 v[136:139], v148
	ds_read_b128 v[140:143], v148 offset:1024
	ds_read_b128 v[144:147], v148 offset:2048
	ds_read_b128 v[148:151], v148 offset:3072
	ds_read_b128 v[152:155], v172
	ds_read_b128 v[156:159], v172 offset:1024
	ds_read_b128 v[160:163], v172 offset:2048
	ds_read_b128 v[172:175], v172 offset:3072
	s_add_u32 s8, s8, s101
	s_addc_u32 s9, s9, 0
	s_mov_b32 m0, s14
	v_lshl_add_u64 v[214:215], s[8:9], 0, v[246:247]
	ds_read_b128 v[176:179], v231 offset:32768
	ds_read_b128 v[180:183], v231 offset:33792
	ds_read_b128 v[184:187], v231 offset:34816
	ds_read_b128 v[188:191], v231 offset:35840
	ds_read_b128 v[192:195], v231 offset:36864
	ds_read_b128 v[196:199], v231 offset:37888
	ds_read_b128 v[200:203], v231 offset:38912
	ds_read_b128 v[204:207], v231 offset:39936
	global_load_lds_dwordx4 v[214:215], off
	v_lshl_add_u64 v[214:215], s[8:9], 0, v[248:249]
	s_mov_b32 m0, s15
	s_nop 0
	global_load_lds_dwordx4 v[214:215], off
	s_waitcnt vmcnt(8)
	s_waitcnt lgkmcnt(0)
	s_barrier
	s_waitcnt lgkmcnt(0)
	v_mfma_f32_16x16x32_bf16 v[126:129], v[136:139], v[176:179], v[126:129]
	v_mfma_f32_16x16x32_bf16 v[126:129], v[140:143], v[180:183], v[126:129]
	v_mfma_f32_16x16x32_bf16 v[110:113], v[136:139], v[184:187], v[110:113]
	v_mfma_f32_16x16x32_bf16 v[110:113], v[140:143], v[188:191], v[110:113]
	v_mfma_f32_16x16x32_bf16 v[94:97], v[136:139], v[192:195], v[94:97]
	v_mfma_f32_16x16x32_bf16 v[94:97], v[140:143], v[196:199], v[94:97]
	v_mfma_f32_16x16x32_bf16 v[78:81], v[136:139], v[200:203], v[78:81]
	v_mfma_f32_16x16x32_bf16 v[78:81], v[140:143], v[204:207], v[78:81]
	v_mfma_f32_16x16x32_bf16 v[122:125], v[144:147], v[176:179], v[122:125]
	v_mfma_f32_16x16x32_bf16 v[122:125], v[148:151], v[180:183], v[122:125]
	v_mfma_f32_16x16x32_bf16 v[106:109], v[144:147], v[184:187], v[106:109]
	v_mfma_f32_16x16x32_bf16 v[106:109], v[148:151], v[188:191], v[106:109]
	v_mfma_f32_16x16x32_bf16 v[90:93], v[144:147], v[192:195], v[90:93]
	v_mfma_f32_16x16x32_bf16 v[90:93], v[148:151], v[196:199], v[90:93]
	v_mfma_f32_16x16x32_bf16 v[74:77], v[144:147], v[200:203], v[74:77]
	v_mfma_f32_16x16x32_bf16 v[74:77], v[148:151], v[204:207], v[74:77]
	v_mfma_f32_16x16x32_bf16 v[118:121], v[152:155], v[176:179], v[118:121]
	v_mfma_f32_16x16x32_bf16 v[118:121], v[156:159], v[180:183], v[118:121]
	v_mfma_f32_16x16x32_bf16 v[102:105], v[152:155], v[184:187], v[102:105]
	v_mfma_f32_16x16x32_bf16 v[102:105], v[156:159], v[188:191], v[102:105]
	v_mfma_f32_16x16x32_bf16 v[86:89], v[152:155], v[192:195], v[86:89]
	v_mfma_f32_16x16x32_bf16 v[86:89], v[156:159], v[196:199], v[86:89]
	v_mfma_f32_16x16x32_bf16 v[70:73], v[152:155], v[200:203], v[70:73]
	v_mfma_f32_16x16x32_bf16 v[70:73], v[156:159], v[204:207], v[70:73]
	v_mfma_f32_16x16x32_bf16 v[114:117], v[160:163], v[176:179], v[114:117]
	v_mfma_f32_16x16x32_bf16 v[114:117], v[172:175], v[180:183], v[114:117]
	v_mfma_f32_16x16x32_bf16 v[98:101], v[160:163], v[184:187], v[98:101]
	v_mfma_f32_16x16x32_bf16 v[98:101], v[172:175], v[188:191], v[98:101]
	v_mfma_f32_16x16x32_bf16 v[82:85], v[160:163], v[192:195], v[82:85]
	v_mfma_f32_16x16x32_bf16 v[82:85], v[172:175], v[196:199], v[82:85]
	v_mfma_f32_16x16x32_bf16 v[66:69], v[160:163], v[200:203], v[66:69]
	v_mfma_f32_16x16x32_bf16 v[66:69], v[172:175], v[204:207], v[66:69]
	s_barrier
	s_add_i32 s8, s27, s0
	v_lshl_add_u64 v[164:165], v[164:165], 0, s[62:63]
	s_mov_b32 m0, s8
	ds_read_b128 v[176:179], v231 offset:49152
	ds_read_b128 v[180:183], v231 offset:50176
	ds_read_b128 v[184:187], v231 offset:51200
	ds_read_b128 v[188:191], v231 offset:52224
	ds_read_b128 v[192:195], v231 offset:53248
	ds_read_b128 v[196:199], v231 offset:54272
	ds_read_b128 v[200:203], v231 offset:55296
	ds_read_b128 v[204:207], v231 offset:56320
	global_load_lds_dwordx4 v[164:165], off
	v_lshl_add_u64 v[164:165], v[168:169], 0, s[62:63]
	s_add_i32 m0, s8, 0x2000
	s_add_i32 s8, s31, s0
	global_load_lds_dwordx4 v[164:165], off
	v_lshl_add_u64 v[164:165], v[170:171], 0, s[62:63]
	s_mov_b32 m0, s8
	s_nop 0
	global_load_lds_dwordx4 v[164:165], off
	v_lshl_add_u64 v[164:165], v[208:209], 0, s[62:63]
	s_add_i32 m0, s8, 0x2000
	s_nop 0
	global_load_lds_dwordx4 v[164:165], off
	v_lshl_add_u64 v[164:165], v[210:211], 0, v[244:245]
	s_mov_b32 m0, s17
	s_nop 0
	global_load_lds_dwordx4 v[164:165], off
	v_lshl_add_u64 v[164:165], v[212:213], 0, v[244:245]
	s_mov_b32 m0, s18
	s_nop 0
	global_load_lds_dwordx4 v[164:165], off
	s_waitcnt vmcnt(8)
	s_waitcnt lgkmcnt(0)
	s_barrier
	s_waitcnt lgkmcnt(0)
	v_mfma_f32_16x16x32_bf16 v[62:65], v[136:139], v[176:179], v[62:65]
	v_mfma_f32_16x16x32_bf16 v[62:65], v[140:143], v[180:183], v[62:65]
	v_mfma_f32_16x16x32_bf16 v[46:49], v[136:139], v[184:187], v[46:49]
	v_mfma_f32_16x16x32_bf16 v[46:49], v[140:143], v[188:191], v[46:49]
	v_mfma_f32_16x16x32_bf16 v[30:33], v[136:139], v[192:195], v[30:33]
	v_mfma_f32_16x16x32_bf16 v[30:33], v[140:143], v[196:199], v[30:33]
	v_mfma_f32_16x16x32_bf16 v[14:17], v[136:139], v[200:203], v[14:17]
	v_mfma_f32_16x16x32_bf16 v[14:17], v[140:143], v[204:207], v[14:17]
	v_mfma_f32_16x16x32_bf16 v[58:61], v[144:147], v[176:179], v[58:61]
	v_mfma_f32_16x16x32_bf16 v[58:61], v[148:151], v[180:183], v[58:61]
	v_mfma_f32_16x16x32_bf16 v[42:45], v[144:147], v[184:187], v[42:45]
	v_mfma_f32_16x16x32_bf16 v[42:45], v[148:151], v[188:191], v[42:45]
	v_mfma_f32_16x16x32_bf16 v[26:29], v[144:147], v[192:195], v[26:29]
	v_mfma_f32_16x16x32_bf16 v[26:29], v[148:151], v[196:199], v[26:29]
	v_mfma_f32_16x16x32_bf16 v[10:13], v[144:147], v[200:203], v[10:13]
	v_mfma_f32_16x16x32_bf16 v[10:13], v[148:151], v[204:207], v[10:13]
	v_mfma_f32_16x16x32_bf16 v[54:57], v[152:155], v[176:179], v[54:57]
	v_mfma_f32_16x16x32_bf16 v[54:57], v[156:159], v[180:183], v[54:57]
	v_mfma_f32_16x16x32_bf16 v[38:41], v[152:155], v[184:187], v[38:41]
	v_mfma_f32_16x16x32_bf16 v[38:41], v[156:159], v[188:191], v[38:41]
	v_mfma_f32_16x16x32_bf16 v[22:25], v[152:155], v[192:195], v[22:25]
	v_mfma_f32_16x16x32_bf16 v[22:25], v[156:159], v[196:199], v[22:25]
	v_mfma_f32_16x16x32_bf16 v[6:9], v[152:155], v[200:203], v[6:9]
	v_mfma_f32_16x16x32_bf16 v[6:9], v[156:159], v[204:207], v[6:9]
	v_mfma_f32_16x16x32_bf16 v[50:53], v[160:163], v[176:179], v[50:53]
	v_mfma_f32_16x16x32_bf16 v[50:53], v[172:175], v[180:183], v[50:53]
	v_mfma_f32_16x16x32_bf16 v[34:37], v[160:163], v[184:187], v[34:37]
	v_mfma_f32_16x16x32_bf16 v[34:37], v[172:175], v[188:191], v[34:37]
	v_mfma_f32_16x16x32_bf16 v[18:21], v[160:163], v[192:195], v[18:21]
	v_mfma_f32_16x16x32_bf16 v[18:21], v[172:175], v[196:199], v[18:21]
	v_mfma_f32_16x16x32_bf16 v[2:5], v[160:163], v[200:203], v[2:5]
	v_mfma_f32_16x16x32_bf16 v[2:5], v[172:175], v[204:207], v[2:5]
	s_barrier
	s_add_u32 s10, s10, 0x100
	s_addc_u32 s11, s11, 0
	v_readlane_b32 s31, v255, 41
	s_add_u32 s6, s6, s31
	s_addc_u32 s7, s7, 0
	s_cmp_ge_i32 s25, s13
	s_mov_b32 s8, s25
	s_cbranch_scc0 .LBB0_520

; #define PG8_STAGE(bufoff, gbase, voff) do { _Pragma("unroll") for (int _i = 0; _i < 2; ++_i) \
;         __builtin_amdgcn_global_load_lds((const unsigned*)((const char*)(gbase) + (voff)[_i]), (PG8_LAS unsigned*)(lds + (bufoff) + ldsw + _i * 8192), 16, 0, 0); } while (0)
; #define PG8_LDA(dst, b, h) do { _Pragma("unroll") for (int m = 0; m < 4; ++m) _Pragma("unroll") for (int k = 0; k < 2; ++k) dst[m][k] = *(const PG8_LAS bf16x8*)(lds + PG8_SA(b, h) + aoff + m * 2048 + k * 1024); } while (0)
; #define PG8_LDB(dst, b, h) do { _Pragma("unroll") for (int n = 0; n < 2; ++n) _Pragma("unroll") for (int k = 0; k < 2; ++k) dst[n][k] = *(const PG8_LAS bf16x8*)(lds + PG8_SB(b, h) + boff + n * 2048 + k * 1024); } while (0)
; #define PG8_MMA(ai, bj, At, Bt) do { __builtin_amdgcn_s_setprio(1); _Pragma("unroll") for (int m = 0; m < 4; ++m) _Pragma("unroll") for (int n = 0; n < 2; ++n) _Pragma("unroll") for (int k = 0; k < 2; ++k) \
;         acc[ai][bj][m][n] = __builtin_amdgcn_mfma_f32_16x16x32_bf16(Bt[n][k], At[m][k], acc[ai][bj][m][n], 0, 0, 0); __builtin_amdgcn_s_setprio(0); } while (0)
; #define PG8_WAIT_V(n) asm volatile("s_waitcnt vmcnt(" #n ")" ::: "memory")
; #define PG8_WAIT_L(n) asm volatile("s_waitcnt lgkmcnt(" #n ")" ::: "memory")
; #define PG8_BAR __builtin_amdgcn_s_barrier()
; #define PG8_SCHED __builtin_amdgcn_sched_barrier(0)
;     ...
;             const char* a1 = cA + (size_t)(t + 1) * kstep;
;             const char* a2 = last ? nA : cA + (size_t)(t + 2) * kstep; const char* b2 = last ? nB : cB + (size_t)(t + 2) * kstep;
;             const char* a3 = a2 + kstep; const char* b3 = b2 + kstep;
;             if (last && has_next) S.a_ready(nxt);
;             if constexpr (SP2) {
;             PG8_LDB(B0, 0, 0); PG8_LDB(B1, 0, 1); PG8_SCHED; PG8_LDA(At, 0, 0); PG8_STAGE(PG8_SA(1, 1), a1 + hstepA, voffA);
;             PG8_WAIT_V(8); PG8_WAIT_L(0); PG8_BAR; PG8_MMA(0, 0, At, B0); PG8_MMA(0, 1, At, B1); PG8_BAR; PG8_SCHED;
;             PG8_LDA(At, 0, 1); PG8_STAGE(PG8_SB(0, 0), b2, voffB); PG8_STAGE(PG8_SB(0, 1), b2 + hstepB, voffB); PG8_STAGE(PG8_SA(0, 0), a2, voffA);
.LBB0_611:
	s_andn2_b64 vcc, exec, s[86:87]
	s_cbranch_vccnz .LBB0_614
	s_and_b32 s24, s101, 3
	s_cbranch_scc1 .Lhalf_entry
	s_add_u32 s24, s8, 0x100
	s_addc_u32 s25, s9, 0
	s_add_u32 s6, s10, 0x80
	s_addc_u32 s7, s11, 0
	s_mov_b32 s8, 0
	s_add_i32 s10, s8, 2
	s_add_u32 s11, s6, 0x80
	s_addc_u32 s9, s7, 0
	s_add_i32 s27, 0, 0x10000
	s_cmp_eq_u32 s18, s8
	s_cselect_b32 s9, s41, s9
	s_cselect_b32 s8, s40, s11
	v_add_u32_e32 v140, s27, v151
	s_cselect_b32 s35, s91, s25
	s_cselect_b32 s34, s90, s24
	s_add_i32 s11, 0, 0x14000
	ds_read_b128 v[156:159], v140
	ds_read_b128 v[160:163], v140 offset:1024
	ds_read_b128 v[172:175], v140 offset:2048
	ds_read_b128 v[176:179], v140 offset:3072
	v_add_u32_e32 v140, s11, v151
	ds_read_b128 v[180:183], v140
	ds_read_b128 v[184:187], v140 offset:1024
	ds_read_b128 v[188:191], v140 offset:2048
	ds_read_b128 v[192:195], v140 offset:3072
	v_lshl_add_u64 v[164:165], s[6:7], 0, v[138:139]
	s_add_i32 m0, s3, 0xc000
	ds_read_b128 v[196:199], v154
	ds_read_b128 v[200:203], v154 offset:1024
	ds_read_b128 v[204:207], v154 offset:2048
	ds_read_b128 v[208:211], v154 offset:3072
	ds_read_b128 v[212:215], v154 offset:4096
	ds_read_b128 v[216:219], v154 offset:5120
	ds_read_b128 v[220:223], v154 offset:6144
	ds_read_b128 v[224:227], v154 offset:7168
	global_load_lds_dwordx4 v[164:165], off
	v_lshl_add_u64 v[164:165], s[6:7], 0, v[136:137]
	s_add_i32 m0, s3, 0xe000
	s_nop 0
	global_load_lds_dwordx4 v[164:165], off
	s_waitcnt vmcnt(8)
	s_waitcnt lgkmcnt(0)
	s_barrier
	s_waitcnt lgkmcnt(0)
	v_mfma_f32_16x16x32_bf16 v[126:129], v[156:159], v[196:199], 0
	v_mfma_f32_16x16x32_bf16 v[126:129], v[160:163], v[200:203], v[126:129]
	v_mfma_f32_16x16x32_bf16 v[110:113], v[156:159], v[204:207], 0
	v_mfma_f32_16x16x32_bf16 v[110:113], v[160:163], v[208:211], v[110:113]
	v_mfma_f32_16x16x32_bf16 v[94:97], v[156:159], v[212:215], 0
	v_mfma_f32_16x16x32_bf16 v[94:97], v[160:163], v[216:219], v[94:97]
	v_mfma_f32_16x16x32_bf16 v[78:81], v[156:159], v[220:223], 0
	v_mfma_f32_16x16x32_bf16 v[78:81], v[160:163], v[224:227], v[78:81]
	v_mfma_f32_16x16x32_bf16 v[122:125], v[172:175], v[196:199], 0
	v_mfma_f32_16x16x32_bf16 v[122:125], v[176:179], v[200:203], v[122:125]
	v_mfma_f32_16x16x32_bf16 v[106:109], v[172:175], v[204:207], 0
	v_mfma_f32_16x16x32_bf16 v[106:109], v[176:179], v[208:211], v[106:109]
	v_mfma_f32_16x16x32_bf16 v[90:93], v[172:175], v[212:215], 0
	v_mfma_f32_16x16x32_bf16 v[90:93], v[176:179], v[216:219], v[90:93]
	v_mfma_f32_16x16x32_bf16 v[74:77], v[172:175], v[220:223], 0
	v_mfma_f32_16x16x32_bf16 v[74:77], v[176:179], v[224:227], v[74:77]
	v_mfma_f32_16x16x32_bf16 v[118:121], v[180:183], v[196:199], 0
	v_mfma_f32_16x16x32_bf16 v[118:121], v[184:187], v[200:203], v[118:121]
	v_mfma_f32_16x16x32_bf16 v[102:105], v[180:183], v[204:207], 0
	v_mfma_f32_16x16x32_bf16 v[102:105], v[184:187], v[208:211], v[102:105]
	v_mfma_f32_16x16x32_bf16 v[86:89], v[180:183], v[212:215], 0
	v_mfma_f32_16x16x32_bf16 v[86:89], v[184:187], v[216:219], v[86:89]
	v_mfma_f32_16x16x32_bf16 v[70:73], v[180:183], v[220:223], 0
	v_mfma_f32_16x16x32_bf16 v[70:73], v[184:187], v[224:227], v[70:73]
	v_mfma_f32_16x16x32_bf16 v[114:117], v[188:191], v[196:199], 0
	v_mfma_f32_16x16x32_bf16 v[114:117], v[192:195], v[200:203], v[114:117]
	v_mfma_f32_16x16x32_bf16 v[98:101], v[188:191], v[204:207], 0
	v_mfma_f32_16x16x32_bf16 v[98:101], v[192:195], v[208:211], v[98:101]
	v_mfma_f32_16x16x32_bf16 v[82:85], v[188:191], v[212:215], 0
	v_mfma_f32_16x16x32_bf16 v[82:85], v[192:195], v[216:219], v[82:85]
	v_mfma_f32_16x16x32_bf16 v[66:69], v[188:191], v[220:223], 0
	v_mfma_f32_16x16x32_bf16 v[66:69], v[192:195], v[224:227], v[66:69]
	s_barrier
	s_add_i32 s27, s27, s0
	v_lshl_add_u64 v[164:165], s[34:35], 0, v[166:167]
	s_mov_b32 m0, s27
	ds_read_b128 v[196:199], v154 offset:16384
	ds_read_b128 v[200:203], v154 offset:17408
	ds_read_b128 v[204:207], v154 offset:18432
	ds_read_b128 v[208:211], v154 offset:19456
	ds_read_b128 v[212:215], v154 offset:20480
	ds_read_b128 v[216:219], v154 offset:21504
	ds_read_b128 v[220:223], v154 offset:22528
	ds_read_b128 v[224:227], v154 offset:23552
	global_load_lds_dwordx4 v[164:165], off
	s_add_i32 m0, s27, 0x2000
	v_lshl_add_u64 v[168:169], s[34:35], 0, v[130:131]
	s_add_u32 s34, s34, s58
	s_addc_u32 s35, s35, s59
	s_add_i32 s11, s11, s0
	global_load_lds_dwordx4 v[168:169], off
	v_lshl_add_u64 v[170:171], s[34:35], 0, v[166:167]
	s_mov_b32 m0, s11
	v_lshl_add_u64 v[228:229], s[34:35], 0, v[130:131]
	global_load_lds_dwordx4 v[170:171], off
	s_add_i32 m0, s11, 0x2000
	v_lshl_add_u64 v[230:231], s[8:9], 0, v[134:135]
	global_load_lds_dwordx4 v[228:229], off
	s_mov_b32 m0, s3
	v_lshl_add_u64 v[232:233], s[8:9], 0, v[132:133]
	global_load_lds_dwordx4 v[230:231], off
	s_mov_b32 m0, s12
	s_nop 0
	global_load_lds_dwordx4 v[232:233], off
	s_waitcnt vmcnt(8)
	s_waitcnt lgkmcnt(0)
	s_barrier
; #define PG8_STAGE(bufoff, gbase, voff) do { _Pragma("unroll") for (int _i = 0; _i < 2; ++_i) \
;         __builtin_amdgcn_global_load_lds((const unsigned*)((const char*)(gbase) + (voff)[_i]), (PG8_LAS unsigned*)(lds + (bufoff) + ldsw + _i * 8192), 16, 0, 0); } while (0)
; #define PG8_LDA(dst, b, h) do { _Pragma("unroll") for (int m = 0; m < 4; ++m) _Pragma("unroll") for (int k = 0; k < 2; ++k) dst[m][k] = *(const PG8_LAS bf16x8*)(lds + PG8_SA(b, h) + aoff + m * 2048 + k * 1024); } while (0)
; #define PG8_LDB(dst, b, h) do { _Pragma("unroll") for (int n = 0; n < 2; ++n) _Pragma("unroll") for (int k = 0; k < 2; ++k) dst[n][k] = *(const PG8_LAS bf16x8*)(lds + PG8_SB(b, h) + boff + n * 2048 + k * 1024); } while (0)
; #define PG8_MMA(ai, bj, At, Bt) do { __builtin_amdgcn_s_setprio(1); _Pragma("unroll") for (int m = 0; m < 4; ++m) _Pragma("unroll") for (int n = 0; n < 2; ++n) _Pragma("unroll") for (int k = 0; k < 2; ++k) \
;         acc[ai][bj][m][n] = __builtin_amdgcn_mfma_f32_16x16x32_bf16(Bt[n][k], At[m][k], acc[ai][bj][m][n], 0, 0, 0); __builtin_amdgcn_s_setprio(0); } while (0)
; #define PG8_WAIT_V(n) asm volatile("s_waitcnt vmcnt(" #n ")" ::: "memory")
; #define PG8_WAIT_L(n) asm volatile("s_waitcnt lgkmcnt(" #n ")" ::: "memory")
; #define PG8_BAR __builtin_amdgcn_s_barrier()
; #define PG8_SCHED __builtin_amdgcn_sched_barrier(0)
;     ...
;             PG8_WAIT_V(8); PG8_WAIT_L(0); PG8_BAR; PG8_MMA(1, 0, At, B0); PG8_MMA(1, 1, At, B1); PG8_BAR; PG8_SCHED;
;             PG8_LDB(B0, 1, 0); PG8_LDB(B1, 1, 1); PG8_SCHED; PG8_LDA(At, 1, 0); PG8_STAGE(PG8_SA(0, 1), a2 + hstepA, voffA);
;             PG8_WAIT_V(8); PG8_WAIT_L(0); PG8_BAR; PG8_MMA(0, 0, At, B0); PG8_MMA(0, 1, At, B1); PG8_BAR; PG8_SCHED;
	s_waitcnt lgkmcnt(0)
	v_mfma_f32_16x16x32_bf16 v[62:65], v[156:159], v[196:199], 0
	v_mfma_f32_16x16x32_bf16 v[62:65], v[160:163], v[200:203], v[62:65]
	v_mfma_f32_16x16x32_bf16 v[46:49], v[156:159], v[204:207], 0
	v_mfma_f32_16x16x32_bf16 v[46:49], v[160:163], v[208:211], v[46:49]
	v_mfma_f32_16x16x32_bf16 v[30:33], v[156:159], v[212:215], 0
	v_mfma_f32_16x16x32_bf16 v[30:33], v[160:163], v[216:219], v[30:33]
	v_mfma_f32_16x16x32_bf16 v[14:17], v[156:159], v[220:223], 0
	v_mfma_f32_16x16x32_bf16 v[14:17], v[160:163], v[224:227], v[14:17]
	v_mfma_f32_16x16x32_bf16 v[58:61], v[172:175], v[196:199], 0
	v_mfma_f32_16x16x32_bf16 v[58:61], v[176:179], v[200:203], v[58:61]
	v_mfma_f32_16x16x32_bf16 v[42:45], v[172:175], v[204:207], 0
	v_mfma_f32_16x16x32_bf16 v[42:45], v[176:179], v[208:211], v[42:45]
	v_mfma_f32_16x16x32_bf16 v[26:29], v[172:175], v[212:215], 0
	v_mfma_f32_16x16x32_bf16 v[26:29], v[176:179], v[216:219], v[26:29]
	v_mfma_f32_16x16x32_bf16 v[10:13], v[172:175], v[220:223], 0
	v_mfma_f32_16x16x32_bf16 v[10:13], v[176:179], v[224:227], v[10:13]
	v_mfma_f32_16x16x32_bf16 v[54:57], v[180:183], v[196:199], 0
	v_mfma_f32_16x16x32_bf16 v[54:57], v[184:187], v[200:203], v[54:57]
	v_mfma_f32_16x16x32_bf16 v[38:41], v[180:183], v[204:207], 0
	v_mfma_f32_16x16x32_bf16 v[38:41], v[184:187], v[208:211], v[38:41]
	v_mfma_f32_16x16x32_bf16 v[22:25], v[180:183], v[212:215], 0
	v_mfma_f32_16x16x32_bf16 v[22:25], v[184:187], v[216:219], v[22:25]
	v_mfma_f32_16x16x32_bf16 v[6:9], v[180:183], v[220:223], 0
	v_mfma_f32_16x16x32_bf16 v[6:9], v[184:187], v[224:227], v[6:9]
	v_mfma_f32_16x16x32_bf16 v[50:53], v[188:191], v[196:199], 0
	v_mfma_f32_16x16x32_bf16 v[50:53], v[192:195], v[200:203], v[50:53]
	v_mfma_f32_16x16x32_bf16 v[34:37], v[188:191], v[204:207], 0
	v_mfma_f32_16x16x32_bf16 v[34:37], v[192:195], v[208:211], v[34:37]
	v_mfma_f32_16x16x32_bf16 v[18:21], v[188:191], v[212:215], 0
	v_mfma_f32_16x16x32_bf16 v[18:21], v[192:195], v[216:219], v[18:21]
	v_mfma_f32_16x16x32_bf16 v[2:5], v[188:191], v[220:223], 0
	v_mfma_f32_16x16x32_bf16 v[2:5], v[192:195], v[224:227], v[2:5]
	s_barrier
	s_add_i32 s11, 0, 0x18000
	v_add_u32_e32 v140, s11, v151
	s_add_i32 s27, 0, 0x1c000
	ds_read_b128 v[156:159], v140
	ds_read_b128 v[160:163], v140 offset:1024
	ds_read_b128 v[172:175], v140 offset:2048
	ds_read_b128 v[176:179], v140 offset:3072
	v_add_u32_e32 v140, s27, v151
	ds_read_b128 v[180:183], v140
	ds_read_b128 v[184:187], v140 offset:1024
	ds_read_b128 v[188:191], v140 offset:2048
	ds_read_b128 v[192:195], v140 offset:3072
	s_add_u32 s8, s8, s58
	s_addc_u32 s9, s9, s59
	s_mov_b32 m0, s13
	v_lshl_add_u64 v[234:235], s[8:9], 0, v[134:135]
	ds_read_b128 v[196:199], v154 offset:32768
	ds_read_b128 v[200:203], v154 offset:33792
	ds_read_b128 v[204:207], v154 offset:34816
	ds_read_b128 v[208:211], v154 offset:35840
	ds_read_b128 v[212:215], v154 offset:36864
	ds_read_b128 v[216:219], v154 offset:37888
	ds_read_b128 v[220:223], v154 offset:38912
	ds_read_b128 v[224:227], v154 offset:39936
	global_load_lds_dwordx4 v[234:235], off
	v_lshl_add_u64 v[234:235], s[8:9], 0, v[132:133]
	s_mov_b32 m0, s14
	s_nop 0
	global_load_lds_dwordx4 v[234:235], off
	s_waitcnt vmcnt(8)
	s_waitcnt lgkmcnt(0)
	s_barrier
	s_waitcnt lgkmcnt(0)
	v_mfma_f32_16x16x32_bf16 v[126:129], v[156:159], v[196:199], v[126:129]
	v_mfma_f32_16x16x32_bf16 v[126:129], v[160:163], v[200:203], v[126:129]
	v_mfma_f32_16x16x32_bf16 v[110:113], v[156:159], v[204:207], v[110:113]
	v_mfma_f32_16x16x32_bf16 v[110:113], v[160:163], v[208:211], v[110:113]
	v_mfma_f32_16x16x32_bf16 v[94:97], v[156:159], v[212:215], v[94:97]
	v_mfma_f32_16x16x32_bf16 v[94:97], v[160:163], v[216:219], v[94:97]
	v_mfma_f32_16x16x32_bf16 v[78:81], v[156:159], v[220:223], v[78:81]
	v_mfma_f32_16x16x32_bf16 v[78:81], v[160:163], v[224:227], v[78:81]
	v_mfma_f32_16x16x32_bf16 v[122:125], v[172:175], v[196:199], v[122:125]
	v_mfma_f32_16x16x32_bf16 v[122:125], v[176:179], v[200:203], v[122:125]
	v_mfma_f32_16x16x32_bf16 v[106:109], v[172:175], v[204:207], v[106:109]
	v_mfma_f32_16x16x32_bf16 v[106:109], v[176:179], v[208:211], v[106:109]
	v_mfma_f32_16x16x32_bf16 v[90:93], v[172:175], v[212:215], v[90:93]
	v_mfma_f32_16x16x32_bf16 v[90:93], v[176:179], v[216:219], v[90:93]
	v_mfma_f32_16x16x32_bf16 v[74:77], v[172:175], v[220:223], v[74:77]
	v_mfma_f32_16x16x32_bf16 v[74:77], v[176:179], v[224:227], v[74:77]
	v_mfma_f32_16x16x32_bf16 v[118:121], v[180:183], v[196:199], v[118:121]
	v_mfma_f32_16x16x32_bf16 v[118:121], v[184:187], v[200:203], v[118:121]
	v_mfma_f32_16x16x32_bf16 v[102:105], v[180:183], v[204:207], v[102:105]
	v_mfma_f32_16x16x32_bf16 v[102:105], v[184:187], v[208:211], v[102:105]
	v_mfma_f32_16x16x32_bf16 v[86:89], v[180:183], v[212:215], v[86:89]
	v_mfma_f32_16x16x32_bf16 v[86:89], v[184:187], v[216:219], v[86:89]
	v_mfma_f32_16x16x32_bf16 v[70:73], v[180:183], v[220:223], v[70:73]
	v_mfma_f32_16x16x32_bf16 v[70:73], v[184:187], v[224:227], v[70:73]
	v_mfma_f32_16x16x32_bf16 v[114:117], v[188:191], v[196:199], v[114:117]
	v_mfma_f32_16x16x32_bf16 v[114:117], v[192:195], v[200:203], v[114:117]
	v_mfma_f32_16x16x32_bf16 v[98:101], v[188:191], v[204:207], v[98:101]
	v_mfma_f32_16x16x32_bf16 v[98:101], v[192:195], v[208:211], v[98:101]
	v_mfma_f32_16x16x32_bf16 v[82:85], v[188:191], v[212:215], v[82:85]
	v_mfma_f32_16x16x32_bf16 v[82:85], v[192:195], v[216:219], v[82:85]
	v_mfma_f32_16x16x32_bf16 v[66:69], v[188:191], v[220:223], v[66:69]
	v_mfma_f32_16x16x32_bf16 v[66:69], v[192:195], v[224:227], v[66:69]
	s_barrier
; #define PG8_STAGE(bufoff, gbase, voff) do { _Pragma("unroll") for (int _i = 0; _i < 2; ++_i) \
;         __builtin_amdgcn_global_load_lds((const unsigned*)((const char*)(gbase) + (voff)[_i]), (PG8_LAS unsigned*)(lds + (bufoff) + ldsw + _i * 8192), 16, 0, 0); } while (0)
; #define PG8_LDA(dst, b, h) do { _Pragma("unroll") for (int m = 0; m < 4; ++m) _Pragma("unroll") for (int k = 0; k < 2; ++k) dst[m][k] = *(const PG8_LAS bf16x8*)(lds + PG8_SA(b, h) + aoff + m * 2048 + k * 1024); } while (0)
; #define PG8_LDB(dst, b, h) do { _Pragma("unroll") for (int n = 0; n < 2; ++n) _Pragma("unroll") for (int k = 0; k < 2; ++k) dst[n][k] = *(const PG8_LAS bf16x8*)(lds + PG8_SB(b, h) + boff + n * 2048 + k * 1024); } while (0)
; #define PG8_MMA(ai, bj, At, Bt) do { __builtin_amdgcn_s_setprio(1); _Pragma("unroll") for (int m = 0; m < 4; ++m) _Pragma("unroll") for (int n = 0; n < 2; ++n) _Pragma("unroll") for (int k = 0; k < 2; ++k) \
;         acc[ai][bj][m][n] = __builtin_amdgcn_mfma_f32_16x16x32_bf16(Bt[n][k], At[m][k], acc[ai][bj][m][n], 0, 0, 0); __builtin_amdgcn_s_setprio(0); } while (0)
; #define PG8_WAIT_V(n) asm volatile("s_waitcnt vmcnt(" #n ")" ::: "memory")
; #define PG8_WAIT_L(n) asm volatile("s_waitcnt lgkmcnt(" #n ")" ::: "memory")
; #define PG8_BAR __builtin_amdgcn_s_barrier()
; #define PG8_SCHED __builtin_amdgcn_sched_barrier(0)
;     ...
;         for (int t = 0; t < nt; t += 2) {
;             const bool last = (t == nt - 2);
;             const char* a1 = cA + (size_t)(t + 1) * kstep;
;             const char* a2 = last ? nA : cA + (size_t)(t + 2) * kstep; const char* b2 = last ? nB : cB + (size_t)(t + 2) * kstep;
;             const char* a3 = a2 + kstep; const char* b3 = b2 + kstep;
;             if (last && has_next) S.a_ready(nxt);
;             if constexpr (SP2) {
;             PG8_LDB(B0, 0, 0); PG8_LDB(B1, 0, 1); PG8_SCHED; PG8_LDA(At, 0, 0); PG8_STAGE(PG8_SA(1, 1), a1 + hstepA, voffA);
;             PG8_WAIT_V(8); PG8_WAIT_L(0); PG8_BAR; PG8_MMA(0, 0, At, B0); PG8_MMA(0, 1, At, B1); PG8_BAR; PG8_SCHED;
;     ...
;             PG8_LDA(At, 1, 1); PG8_STAGE(PG8_SB(1, 0), b3, voffB); PG8_STAGE(PG8_SB(1, 1), b3 + hstepB, voffB); PG8_STAGE(PG8_SA(1, 0), a3, voffA);
;             PG8_WAIT_V(8); PG8_WAIT_L(0); PG8_BAR; PG8_MMA(1, 0, At, B0); PG8_MMA(1, 1, At, B1); PG8_BAR; PG8_SCHED;
	s_add_i32 s8, s11, s0
	v_lshl_add_u64 v[164:165], v[164:165], 0, s[62:63]
	s_mov_b32 m0, s8
	ds_read_b128 v[196:199], v154 offset:49152
	ds_read_b128 v[200:203], v154 offset:50176
	ds_read_b128 v[204:207], v154 offset:51200
	ds_read_b128 v[208:211], v154 offset:52224
	ds_read_b128 v[212:215], v154 offset:53248
	ds_read_b128 v[216:219], v154 offset:54272
	ds_read_b128 v[220:223], v154 offset:55296
	ds_read_b128 v[224:227], v154 offset:56320
	global_load_lds_dwordx4 v[164:165], off
	v_lshl_add_u64 v[164:165], v[168:169], 0, s[62:63]
	s_add_i32 m0, s8, 0x2000
	s_add_i32 s8, s27, s0
	global_load_lds_dwordx4 v[164:165], off
	v_lshl_add_u64 v[164:165], v[170:171], 0, s[62:63]
	s_mov_b32 m0, s8
	s_nop 0
	global_load_lds_dwordx4 v[164:165], off
	v_lshl_add_u64 v[164:165], v[228:229], 0, s[62:63]
	s_add_i32 m0, s8, 0x2000
	s_nop 0
	global_load_lds_dwordx4 v[164:165], off
	v_lshl_add_u64 v[164:165], v[230:231], 0, s[62:63]
	s_mov_b32 m0, s16
	s_nop 0
	global_load_lds_dwordx4 v[164:165], off
	v_lshl_add_u64 v[164:165], v[232:233], 0, s[62:63]
	s_mov_b32 m0, s17
	s_nop 0
	global_load_lds_dwordx4 v[164:165], off
	s_waitcnt vmcnt(8)
	s_waitcnt lgkmcnt(0)
	s_barrier
	s_waitcnt lgkmcnt(0)
	v_mfma_f32_16x16x32_bf16 v[62:65], v[156:159], v[196:199], v[62:65]
	v_mfma_f32_16x16x32_bf16 v[62:65], v[160:163], v[200:203], v[62:65]
	v_mfma_f32_16x16x32_bf16 v[46:49], v[156:159], v[204:207], v[46:49]
	v_mfma_f32_16x16x32_bf16 v[46:49], v[160:163], v[208:211], v[46:49]
	v_mfma_f32_16x16x32_bf16 v[30:33], v[156:159], v[212:215], v[30:33]
	v_mfma_f32_16x16x32_bf16 v[30:33], v[160:163], v[216:219], v[30:33]
	v_mfma_f32_16x16x32_bf16 v[14:17], v[156:159], v[220:223], v[14:17]
	v_mfma_f32_16x16x32_bf16 v[14:17], v[160:163], v[224:227], v[14:17]
	v_mfma_f32_16x16x32_bf16 v[58:61], v[172:175], v[196:199], v[58:61]
	v_mfma_f32_16x16x32_bf16 v[58:61], v[176:179], v[200:203], v[58:61]
	v_mfma_f32_16x16x32_bf16 v[42:45], v[172:175], v[204:207], v[42:45]
	v_mfma_f32_16x16x32_bf16 v[42:45], v[176:179], v[208:211], v[42:45]
	v_mfma_f32_16x16x32_bf16 v[26:29], v[172:175], v[212:215], v[26:29]
	v_mfma_f32_16x16x32_bf16 v[26:29], v[176:179], v[216:219], v[26:29]
	v_mfma_f32_16x16x32_bf16 v[10:13], v[172:175], v[220:223], v[10:13]
	v_mfma_f32_16x16x32_bf16 v[10:13], v[176:179], v[224:227], v[10:13]
	v_mfma_f32_16x16x32_bf16 v[54:57], v[180:183], v[196:199], v[54:57]
	v_mfma_f32_16x16x32_bf16 v[54:57], v[184:187], v[200:203], v[54:57]
	v_mfma_f32_16x16x32_bf16 v[38:41], v[180:183], v[204:207], v[38:41]
	v_mfma_f32_16x16x32_bf16 v[38:41], v[184:187], v[208:211], v[38:41]
	v_mfma_f32_16x16x32_bf16 v[22:25], v[180:183], v[212:215], v[22:25]
	v_mfma_f32_16x16x32_bf16 v[22:25], v[184:187], v[216:219], v[22:25]
	v_mfma_f32_16x16x32_bf16 v[6:9], v[180:183], v[220:223], v[6:9]
	v_mfma_f32_16x16x32_bf16 v[6:9], v[184:187], v[224:227], v[6:9]
	v_mfma_f32_16x16x32_bf16 v[50:53], v[188:191], v[196:199], v[50:53]
	v_mfma_f32_16x16x32_bf16 v[50:53], v[192:195], v[200:203], v[50:53]
	v_mfma_f32_16x16x32_bf16 v[34:37], v[188:191], v[204:207], v[34:37]
	v_mfma_f32_16x16x32_bf16 v[34:37], v[192:195], v[208:211], v[34:37]
	v_mfma_f32_16x16x32_bf16 v[18:21], v[188:191], v[212:215], v[18:21]
	v_mfma_f32_16x16x32_bf16 v[18:21], v[192:195], v[216:219], v[18:21]
	v_mfma_f32_16x16x32_bf16 v[2:5], v[188:191], v[220:223], v[2:5]
	v_mfma_f32_16x16x32_bf16 v[2:5], v[192:195], v[224:227], v[2:5]
	s_barrier
	s_add_u32 s24, s24, 0x100
	s_addc_u32 s25, s25, 0
	s_add_u32 s6, s6, 0x100
	s_addc_u32 s7, s7, 0
	s_cmp_ge_i32 s10, s15
	s_mov_b32 s8, s10
	s_cbranch_scc1 .LBB0_614
.LBB0_613:
	s_add_i32 s10, s8, 2
	s_add_u32 s11, s6, 0x80
	s_addc_u32 s9, s7, 0
	s_add_i32 s27, 0, 0x10000
	s_cmp_eq_u32 s18, s8
	s_cselect_b32 s9, s41, s9
	s_cselect_b32 s8, s40, s11
	v_add_u32_e32 v140, s27, v151
	s_cselect_b32 s35, s91, s25
	s_cselect_b32 s34, s90, s24
	s_add_i32 s11, 0, 0x14000
	ds_read_b128 v[156:159], v140
	ds_read_b128 v[160:163], v140 offset:1024
	ds_read_b128 v[172:175], v140 offset:2048
	ds_read_b128 v[176:179], v140 offset:3072
	v_add_u32_e32 v140, s11, v151
	ds_read_b128 v[180:183], v140
	ds_read_b128 v[184:187], v140 offset:1024
	ds_read_b128 v[188:191], v140 offset:2048
	ds_read_b128 v[192:195], v140 offset:3072
	v_lshl_add_u64 v[164:165], s[6:7], 0, v[138:139]
	s_add_i32 m0, s3, 0xc000
	ds_read_b128 v[196:199], v154
	ds_read_b128 v[200:203], v154 offset:1024
	ds_read_b128 v[204:207], v154 offset:2048
	ds_read_b128 v[208:211], v154 offset:3072
	ds_read_b128 v[212:215], v154 offset:4096
	ds_read_b128 v[216:219], v154 offset:5120
	ds_read_b128 v[220:223], v154 offset:6144
	ds_read_b128 v[224:227], v154 offset:7168
	global_load_lds_dwordx4 v[164:165], off
	v_lshl_add_u64 v[164:165], s[6:7], 0, v[136:137]
	s_add_i32 m0, s3, 0xe000
	s_nop 0
	global_load_lds_dwordx4 v[164:165], off
	s_waitcnt vmcnt(8)
	s_waitcnt lgkmcnt(0)
	s_barrier
; #define PG8_STAGE(bufoff, gbase, voff) do { _Pragma("unroll") for (int _i = 0; _i < 2; ++_i) \
;         __builtin_amdgcn_global_load_lds((const unsigned*)((const char*)(gbase) + (voff)[_i]), (PG8_LAS unsigned*)(lds + (bufoff) + ldsw + _i * 8192), 16, 0, 0); } while (0)
; #define PG8_LDA(dst, b, h) do { _Pragma("unroll") for (int m = 0; m < 4; ++m) _Pragma("unroll") for (int k = 0; k < 2; ++k) dst[m][k] = *(const PG8_LAS bf16x8*)(lds + PG8_SA(b, h) + aoff + m * 2048 + k * 1024); } while (0)
; #define PG8_MMA(ai, bj, At, Bt) do { __builtin_amdgcn_s_setprio(1); _Pragma("unroll") for (int m = 0; m < 4; ++m) _Pragma("unroll") for (int n = 0; n < 2; ++n) _Pragma("unroll") for (int k = 0; k < 2; ++k) \
;         acc[ai][bj][m][n] = __builtin_amdgcn_mfma_f32_16x16x32_bf16(Bt[n][k], At[m][k], acc[ai][bj][m][n], 0, 0, 0); __builtin_amdgcn_s_setprio(0); } while (0)
; #define PG8_WAIT_V(n) asm volatile("s_waitcnt vmcnt(" #n ")" ::: "memory")
; #define PG8_WAIT_L(n) asm volatile("s_waitcnt lgkmcnt(" #n ")" ::: "memory")
; #define PG8_BAR __builtin_amdgcn_s_barrier()
; #define PG8_SCHED __builtin_amdgcn_sched_barrier(0)
;     ...
;             PG8_WAIT_V(8); PG8_WAIT_L(0); PG8_BAR; PG8_MMA(0, 0, At, B0); PG8_MMA(0, 1, At, B1); PG8_BAR; PG8_SCHED;
;             PG8_LDA(At, 0, 1); PG8_STAGE(PG8_SB(0, 0), b2, voffB); PG8_STAGE(PG8_SB(0, 1), b2 + hstepB, voffB); PG8_STAGE(PG8_SA(0, 0), a2, voffA);
;             PG8_WAIT_V(8); PG8_WAIT_L(0); PG8_BAR; PG8_MMA(1, 0, At, B0); PG8_MMA(1, 1, At, B1); PG8_BAR; PG8_SCHED;
	s_waitcnt lgkmcnt(0)
	v_mfma_f32_16x16x32_bf16 v[126:129], v[156:159], v[196:199], v[126:129]
	v_mfma_f32_16x16x32_bf16 v[126:129], v[160:163], v[200:203], v[126:129]
	v_mfma_f32_16x16x32_bf16 v[110:113], v[156:159], v[204:207], v[110:113]
	v_mfma_f32_16x16x32_bf16 v[110:113], v[160:163], v[208:211], v[110:113]
	v_mfma_f32_16x16x32_bf16 v[94:97], v[156:159], v[212:215], v[94:97]
	v_mfma_f32_16x16x32_bf16 v[94:97], v[160:163], v[216:219], v[94:97]
	v_mfma_f32_16x16x32_bf16 v[78:81], v[156:159], v[220:223], v[78:81]
	v_mfma_f32_16x16x32_bf16 v[78:81], v[160:163], v[224:227], v[78:81]
	v_mfma_f32_16x16x32_bf16 v[122:125], v[172:175], v[196:199], v[122:125]
	v_mfma_f32_16x16x32_bf16 v[122:125], v[176:179], v[200:203], v[122:125]
	v_mfma_f32_16x16x32_bf16 v[106:109], v[172:175], v[204:207], v[106:109]
	v_mfma_f32_16x16x32_bf16 v[106:109], v[176:179], v[208:211], v[106:109]
	v_mfma_f32_16x16x32_bf16 v[90:93], v[172:175], v[212:215], v[90:93]
	v_mfma_f32_16x16x32_bf16 v[90:93], v[176:179], v[216:219], v[90:93]
	v_mfma_f32_16x16x32_bf16 v[74:77], v[172:175], v[220:223], v[74:77]
	v_mfma_f32_16x16x32_bf16 v[74:77], v[176:179], v[224:227], v[74:77]
	v_mfma_f32_16x16x32_bf16 v[118:121], v[180:183], v[196:199], v[118:121]
	v_mfma_f32_16x16x32_bf16 v[118:121], v[184:187], v[200:203], v[118:121]
	v_mfma_f32_16x16x32_bf16 v[102:105], v[180:183], v[204:207], v[102:105]
	v_mfma_f32_16x16x32_bf16 v[102:105], v[184:187], v[208:211], v[102:105]
	v_mfma_f32_16x16x32_bf16 v[86:89], v[180:183], v[212:215], v[86:89]
	v_mfma_f32_16x16x32_bf16 v[86:89], v[184:187], v[216:219], v[86:89]
	v_mfma_f32_16x16x32_bf16 v[70:73], v[180:183], v[220:223], v[70:73]
	v_mfma_f32_16x16x32_bf16 v[70:73], v[184:187], v[224:227], v[70:73]
	v_mfma_f32_16x16x32_bf16 v[114:117], v[188:191], v[196:199], v[114:117]
	v_mfma_f32_16x16x32_bf16 v[114:117], v[192:195], v[200:203], v[114:117]
	v_mfma_f32_16x16x32_bf16 v[98:101], v[188:191], v[204:207], v[98:101]
	v_mfma_f32_16x16x32_bf16 v[98:101], v[192:195], v[208:211], v[98:101]
	v_mfma_f32_16x16x32_bf16 v[82:85], v[188:191], v[212:215], v[82:85]
	v_mfma_f32_16x16x32_bf16 v[82:85], v[192:195], v[216:219], v[82:85]
	v_mfma_f32_16x16x32_bf16 v[66:69], v[188:191], v[220:223], v[66:69]
	v_mfma_f32_16x16x32_bf16 v[66:69], v[192:195], v[224:227], v[66:69]
	s_barrier
	s_add_i32 s27, s27, s0
	v_lshl_add_u64 v[164:165], s[34:35], 0, v[166:167]
	s_mov_b32 m0, s27
	ds_read_b128 v[196:199], v154 offset:16384
	ds_read_b128 v[200:203], v154 offset:17408
	ds_read_b128 v[204:207], v154 offset:18432
	ds_read_b128 v[208:211], v154 offset:19456
	ds_read_b128 v[212:215], v154 offset:20480
	ds_read_b128 v[216:219], v154 offset:21504
	ds_read_b128 v[220:223], v154 offset:22528
	ds_read_b128 v[224:227], v154 offset:23552
	global_load_lds_dwordx4 v[164:165], off
	s_add_i32 m0, s27, 0x2000
	v_lshl_add_u64 v[168:169], s[34:35], 0, v[130:131]
	s_add_u32 s34, s34, s58
	s_addc_u32 s35, s35, s59
	s_add_i32 s11, s11, s0
	global_load_lds_dwordx4 v[168:169], off
	v_lshl_add_u64 v[170:171], s[34:35], 0, v[166:167]
	s_mov_b32 m0, s11
	v_lshl_add_u64 v[228:229], s[34:35], 0, v[130:131]
	global_load_lds_dwordx4 v[170:171], off
	s_add_i32 m0, s11, 0x2000
	v_lshl_add_u64 v[230:231], s[8:9], 0, v[134:135]
	global_load_lds_dwordx4 v[228:229], off
	s_mov_b32 m0, s3
	v_lshl_add_u64 v[232:233], s[8:9], 0, v[132:133]
	global_load_lds_dwordx4 v[230:231], off
	s_mov_b32 m0, s12
	s_nop 0
	global_load_lds_dwordx4 v[232:233], off
	s_waitcnt vmcnt(8)
	s_waitcnt lgkmcnt(0)
	s_barrier
	s_waitcnt lgkmcnt(0)
	v_mfma_f32_16x16x32_bf16 v[62:65], v[156:159], v[196:199], v[62:65]
	v_mfma_f32_16x16x32_bf16 v[62:65], v[160:163], v[200:203], v[62:65]
	v_mfma_f32_16x16x32_bf16 v[46:49], v[156:159], v[204:207], v[46:49]
	v_mfma_f32_16x16x32_bf16 v[46:49], v[160:163], v[208:211], v[46:49]
	v_mfma_f32_16x16x32_bf16 v[30:33], v[156:159], v[212:215], v[30:33]
	v_mfma_f32_16x16x32_bf16 v[30:33], v[160:163], v[216:219], v[30:33]
	v_mfma_f32_16x16x32_bf16 v[14:17], v[156:159], v[220:223], v[14:17]
	v_mfma_f32_16x16x32_bf16 v[14:17], v[160:163], v[224:227], v[14:17]
	v_mfma_f32_16x16x32_bf16 v[58:61], v[172:175], v[196:199], v[58:61]
	v_mfma_f32_16x16x32_bf16 v[58:61], v[176:179], v[200:203], v[58:61]
	v_mfma_f32_16x16x32_bf16 v[42:45], v[172:175], v[204:207], v[42:45]
	v_mfma_f32_16x16x32_bf16 v[42:45], v[176:179], v[208:211], v[42:45]
	v_mfma_f32_16x16x32_bf16 v[26:29], v[172:175], v[212:215], v[26:29]
	v_mfma_f32_16x16x32_bf16 v[26:29], v[176:179], v[216:219], v[26:29]
	v_mfma_f32_16x16x32_bf16 v[10:13], v[172:175], v[220:223], v[10:13]
	v_mfma_f32_16x16x32_bf16 v[10:13], v[176:179], v[224:227], v[10:13]
	v_mfma_f32_16x16x32_bf16 v[54:57], v[180:183], v[196:199], v[54:57]
	v_mfma_f32_16x16x32_bf16 v[54:57], v[184:187], v[200:203], v[54:57]
	v_mfma_f32_16x16x32_bf16 v[38:41], v[180:183], v[204:207], v[38:41]
	v_mfma_f32_16x16x32_bf16 v[38:41], v[184:187], v[208:211], v[38:41]
	v_mfma_f32_16x16x32_bf16 v[22:25], v[180:183], v[212:215], v[22:25]
	v_mfma_f32_16x16x32_bf16 v[22:25], v[184:187], v[216:219], v[22:25]
	v_mfma_f32_16x16x32_bf16 v[6:9], v[180:183], v[220:223], v[6:9]
	v_mfma_f32_16x16x32_bf16 v[6:9], v[184:187], v[224:227], v[6:9]
	v_mfma_f32_16x16x32_bf16 v[50:53], v[188:191], v[196:199], v[50:53]
	v_mfma_f32_16x16x32_bf16 v[50:53], v[192:195], v[200:203], v[50:53]
	v_mfma_f32_16x16x32_bf16 v[34:37], v[188:191], v[204:207], v[34:37]
	v_mfma_f32_16x16x32_bf16 v[34:37], v[192:195], v[208:211], v[34:37]
	v_mfma_f32_16x16x32_bf16 v[18:21], v[188:191], v[212:215], v[18:21]
	v_mfma_f32_16x16x32_bf16 v[18:21], v[192:195], v[216:219], v[18:21]
	v_mfma_f32_16x16x32_bf16 v[2:5], v[188:191], v[220:223], v[2:5]
	v_mfma_f32_16x16x32_bf16 v[2:5], v[192:195], v[224:227], v[2:5]
	s_barrier
; #define PG8_STAGE(bufoff, gbase, voff) do { _Pragma("unroll") for (int _i = 0; _i < 2; ++_i) \
;         __builtin_amdgcn_global_load_lds((const unsigned*)((const char*)(gbase) + (voff)[_i]), (PG8_LAS unsigned*)(lds + (bufoff) + ldsw + _i * 8192), 16, 0, 0); } while (0)
; #define PG8_LDA(dst, b, h) do { _Pragma("unroll") for (int m = 0; m < 4; ++m) _Pragma("unroll") for (int k = 0; k < 2; ++k) dst[m][k] = *(const PG8_LAS bf16x8*)(lds + PG8_SA(b, h) + aoff + m * 2048 + k * 1024); } while (0)
; #define PG8_LDB(dst, b, h) do { _Pragma("unroll") for (int n = 0; n < 2; ++n) _Pragma("unroll") for (int k = 0; k < 2; ++k) dst[n][k] = *(const PG8_LAS bf16x8*)(lds + PG8_SB(b, h) + boff + n * 2048 + k * 1024); } while (0)
; #define PG8_MMA(ai, bj, At, Bt) do { __builtin_amdgcn_s_setprio(1); _Pragma("unroll") for (int m = 0; m < 4; ++m) _Pragma("unroll") for (int n = 0; n < 2; ++n) _Pragma("unroll") for (int k = 0; k < 2; ++k) \
;         acc[ai][bj][m][n] = __builtin_amdgcn_mfma_f32_16x16x32_bf16(Bt[n][k], At[m][k], acc[ai][bj][m][n], 0, 0, 0); __builtin_amdgcn_s_setprio(0); } while (0)
; #define PG8_WAIT_V(n) asm volatile("s_waitcnt vmcnt(" #n ")" ::: "memory")
; #define PG8_WAIT_L(n) asm volatile("s_waitcnt lgkmcnt(" #n ")" ::: "memory")
; #define PG8_BAR __builtin_amdgcn_s_barrier()
; #define PG8_SCHED __builtin_amdgcn_sched_barrier(0)
;     ...
;             PG8_LDB(B0, 1, 0); PG8_LDB(B1, 1, 1); PG8_SCHED; PG8_LDA(At, 1, 0); PG8_STAGE(PG8_SA(0, 1), a2 + hstepA, voffA);
;             PG8_WAIT_V(8); PG8_WAIT_L(0); PG8_BAR; PG8_MMA(0, 0, At, B0); PG8_MMA(0, 1, At, B1); PG8_BAR; PG8_SCHED;
;             PG8_LDA(At, 1, 1); PG8_STAGE(PG8_SB(1, 0), b3, voffB); PG8_STAGE(PG8_SB(1, 1), b3 + hstepB, voffB); PG8_STAGE(PG8_SA(1, 0), a3, voffA);
;             PG8_WAIT_V(8); PG8_WAIT_L(0); PG8_BAR; PG8_MMA(1, 0, At, B0); PG8_MMA(1, 1, At, B1); PG8_BAR; PG8_SCHED;
	s_add_i32 s11, 0, 0x18000
	v_add_u32_e32 v140, s11, v151
	s_add_i32 s27, 0, 0x1c000
	ds_read_b128 v[156:159], v140
	ds_read_b128 v[160:163], v140 offset:1024
	ds_read_b128 v[172:175], v140 offset:2048
	ds_read_b128 v[176:179], v140 offset:3072
	v_add_u32_e32 v140, s27, v151
	ds_read_b128 v[180:183], v140
	ds_read_b128 v[184:187], v140 offset:1024
	ds_read_b128 v[188:191], v140 offset:2048
	ds_read_b128 v[192:195], v140 offset:3072
	s_add_u32 s8, s8, s58
	s_addc_u32 s9, s9, s59
	s_mov_b32 m0, s13
	v_lshl_add_u64 v[234:235], s[8:9], 0, v[134:135]
	ds_read_b128 v[196:199], v154 offset:32768
	ds_read_b128 v[200:203], v154 offset:33792
	ds_read_b128 v[204:207], v154 offset:34816
	ds_read_b128 v[208:211], v154 offset:35840
	ds_read_b128 v[212:215], v154 offset:36864
	ds_read_b128 v[216:219], v154 offset:37888
	ds_read_b128 v[220:223], v154 offset:38912
	ds_read_b128 v[224:227], v154 offset:39936
	global_load_lds_dwordx4 v[234:235], off
	v_lshl_add_u64 v[234:235], s[8:9], 0, v[132:133]
	s_mov_b32 m0, s14
	s_nop 0
	global_load_lds_dwordx4 v[234:235], off
	s_waitcnt vmcnt(8)
	s_waitcnt lgkmcnt(0)
	s_barrier
	s_waitcnt lgkmcnt(0)
	v_mfma_f32_16x16x32_bf16 v[126:129], v[156:159], v[196:199], v[126:129]
	v_mfma_f32_16x16x32_bf16 v[126:129], v[160:163], v[200:203], v[126:129]
	v_mfma_f32_16x16x32_bf16 v[110:113], v[156:159], v[204:207], v[110:113]
	v_mfma_f32_16x16x32_bf16 v[110:113], v[160:163], v[208:211], v[110:113]
	v_mfma_f32_16x16x32_bf16 v[94:97], v[156:159], v[212:215], v[94:97]
	v_mfma_f32_16x16x32_bf16 v[94:97], v[160:163], v[216:219], v[94:97]
	v_mfma_f32_16x16x32_bf16 v[78:81], v[156:159], v[220:223], v[78:81]
	v_mfma_f32_16x16x32_bf16 v[78:81], v[160:163], v[224:227], v[78:81]
	v_mfma_f32_16x16x32_bf16 v[122:125], v[172:175], v[196:199], v[122:125]
	v_mfma_f32_16x16x32_bf16 v[122:125], v[176:179], v[200:203], v[122:125]
	v_mfma_f32_16x16x32_bf16 v[106:109], v[172:175], v[204:207], v[106:109]
	v_mfma_f32_16x16x32_bf16 v[106:109], v[176:179], v[208:211], v[106:109]
	v_mfma_f32_16x16x32_bf16 v[90:93], v[172:175], v[212:215], v[90:93]
	v_mfma_f32_16x16x32_bf16 v[90:93], v[176:179], v[216:219], v[90:93]
	v_mfma_f32_16x16x32_bf16 v[74:77], v[172:175], v[220:223], v[74:77]
	v_mfma_f32_16x16x32_bf16 v[74:77], v[176:179], v[224:227], v[74:77]
	v_mfma_f32_16x16x32_bf16 v[118:121], v[180:183], v[196:199], v[118:121]
	v_mfma_f32_16x16x32_bf16 v[118:121], v[184:187], v[200:203], v[118:121]
	v_mfma_f32_16x16x32_bf16 v[102:105], v[180:183], v[204:207], v[102:105]
	v_mfma_f32_16x16x32_bf16 v[102:105], v[184:187], v[208:211], v[102:105]
	v_mfma_f32_16x16x32_bf16 v[86:89], v[180:183], v[212:215], v[86:89]
	v_mfma_f32_16x16x32_bf16 v[86:89], v[184:187], v[216:219], v[86:89]
	v_mfma_f32_16x16x32_bf16 v[70:73], v[180:183], v[220:223], v[70:73]
	v_mfma_f32_16x16x32_bf16 v[70:73], v[184:187], v[224:227], v[70:73]
	v_mfma_f32_16x16x32_bf16 v[114:117], v[188:191], v[196:199], v[114:117]
	v_mfma_f32_16x16x32_bf16 v[114:117], v[192:195], v[200:203], v[114:117]
	v_mfma_f32_16x16x32_bf16 v[98:101], v[188:191], v[204:207], v[98:101]
	v_mfma_f32_16x16x32_bf16 v[98:101], v[192:195], v[208:211], v[98:101]
	v_mfma_f32_16x16x32_bf16 v[82:85], v[188:191], v[212:215], v[82:85]
	v_mfma_f32_16x16x32_bf16 v[82:85], v[192:195], v[216:219], v[82:85]
	v_mfma_f32_16x16x32_bf16 v[66:69], v[188:191], v[220:223], v[66:69]
	v_mfma_f32_16x16x32_bf16 v[66:69], v[192:195], v[224:227], v[66:69]
	s_barrier
	s_add_i32 s8, s11, s0
	v_lshl_add_u64 v[164:165], v[164:165], 0, s[62:63]
	s_mov_b32 m0, s8
	ds_read_b128 v[196:199], v154 offset:49152
	ds_read_b128 v[200:203], v154 offset:50176
	ds_read_b128 v[204:207], v154 offset:51200
	ds_read_b128 v[208:211], v154 offset:52224
	ds_read_b128 v[212:215], v154 offset:53248
	ds_read_b128 v[216:219], v154 offset:54272
	ds_read_b128 v[220:223], v154 offset:55296
	ds_read_b128 v[224:227], v154 offset:56320
	global_load_lds_dwordx4 v[164:165], off
	v_lshl_add_u64 v[164:165], v[168:169], 0, s[62:63]
	s_add_i32 m0, s8, 0x2000
	s_add_i32 s8, s27, s0
	global_load_lds_dwordx4 v[164:165], off
	v_lshl_add_u64 v[164:165], v[170:171], 0, s[62:63]
	s_mov_b32 m0, s8
	s_nop 0
	global_load_lds_dwordx4 v[164:165], off
	v_lshl_add_u64 v[164:165], v[228:229], 0, s[62:63]
	s_add_i32 m0, s8, 0x2000
	s_nop 0
	global_load_lds_dwordx4 v[164:165], off
	v_lshl_add_u64 v[164:165], v[230:231], 0, s[62:63]
	s_mov_b32 m0, s16
	s_nop 0
	global_load_lds_dwordx4 v[164:165], off
	v_lshl_add_u64 v[164:165], v[232:233], 0, s[62:63]
	s_mov_b32 m0, s17
	s_nop 0
	global_load_lds_dwordx4 v[164:165], off
	s_waitcnt vmcnt(8)
	s_waitcnt lgkmcnt(0)
	s_barrier
	s_waitcnt lgkmcnt(0)
	v_mfma_f32_16x16x32_bf16 v[62:65], v[156:159], v[196:199], v[62:65]
	v_mfma_f32_16x16x32_bf16 v[62:65], v[160:163], v[200:203], v[62:65]
	v_mfma_f32_16x16x32_bf16 v[46:49], v[156:159], v[204:207], v[46:49]
	v_mfma_f32_16x16x32_bf16 v[46:49], v[160:163], v[208:211], v[46:49]
	v_mfma_f32_16x16x32_bf16 v[30:33], v[156:159], v[212:215], v[30:33]
	v_mfma_f32_16x16x32_bf16 v[30:33], v[160:163], v[216:219], v[30:33]
	v_mfma_f32_16x16x32_bf16 v[14:17], v[156:159], v[220:223], v[14:17]
	v_mfma_f32_16x16x32_bf16 v[14:17], v[160:163], v[224:227], v[14:17]
	v_mfma_f32_16x16x32_bf16 v[58:61], v[172:175], v[196:199], v[58:61]
	v_mfma_f32_16x16x32_bf16 v[58:61], v[176:179], v[200:203], v[58:61]
	v_mfma_f32_16x16x32_bf16 v[42:45], v[172:175], v[204:207], v[42:45]
	v_mfma_f32_16x16x32_bf16 v[42:45], v[176:179], v[208:211], v[42:45]
	v_mfma_f32_16x16x32_bf16 v[26:29], v[172:175], v[212:215], v[26:29]
	v_mfma_f32_16x16x32_bf16 v[26:29], v[176:179], v[216:219], v[26:29]
	v_mfma_f32_16x16x32_bf16 v[10:13], v[172:175], v[220:223], v[10:13]
	v_mfma_f32_16x16x32_bf16 v[10:13], v[176:179], v[224:227], v[10:13]
	v_mfma_f32_16x16x32_bf16 v[54:57], v[180:183], v[196:199], v[54:57]
	v_mfma_f32_16x16x32_bf16 v[54:57], v[184:187], v[200:203], v[54:57]
	v_mfma_f32_16x16x32_bf16 v[38:41], v[180:183], v[204:207], v[38:41]
	v_mfma_f32_16x16x32_bf16 v[38:41], v[184:187], v[208:211], v[38:41]
	v_mfma_f32_16x16x32_bf16 v[22:25], v[180:183], v[212:215], v[22:25]
	v_mfma_f32_16x16x32_bf16 v[22:25], v[184:187], v[216:219], v[22:25]
	v_mfma_f32_16x16x32_bf16 v[6:9], v[180:183], v[220:223], v[6:9]
	v_mfma_f32_16x16x32_bf16 v[6:9], v[184:187], v[224:227], v[6:9]
	v_mfma_f32_16x16x32_bf16 v[50:53], v[188:191], v[196:199], v[50:53]
	v_mfma_f32_16x16x32_bf16 v[50:53], v[192:195], v[200:203], v[50:53]
	v_mfma_f32_16x16x32_bf16 v[34:37], v[188:191], v[204:207], v[34:37]
	v_mfma_f32_16x16x32_bf16 v[34:37], v[192:195], v[208:211], v[34:37]
	v_mfma_f32_16x16x32_bf16 v[18:21], v[188:191], v[212:215], v[18:21]
	v_mfma_f32_16x16x32_bf16 v[18:21], v[192:195], v[216:219], v[18:21]
	v_mfma_f32_16x16x32_bf16 v[2:5], v[188:191], v[220:223], v[2:5]
	v_mfma_f32_16x16x32_bf16 v[2:5], v[192:195], v[224:227], v[2:5]
	s_barrier
	s_add_u32 s24, s24, 0x100
	s_addc_u32 s25, s25, 0
	s_add_u32 s6, s6, 0x100
	s_addc_u32 s7, s7, 0
	s_cmp_ge_i32 s10, s15
	s_mov_b32 s8, s10
	s_cbranch_scc0 .LBB0_613

; #define PG8_STAGE(bufoff, gbase, voff) do { _Pragma("unroll") for (int _i = 0; _i < 2; ++_i) \
;         __builtin_amdgcn_global_load_lds((const unsigned*)((const char*)(gbase) + (voff)[_i]), (PG8_LAS unsigned*)(lds + (bufoff) + ldsw + _i * 8192), 16, 0, 0); } while (0)
; #define PG8_LDA(dst, b, h) do { _Pragma("unroll") for (int m = 0; m < 4; ++m) _Pragma("unroll") for (int k = 0; k < 2; ++k) dst[m][k] = *(const PG8_LAS bf16x8*)(lds + PG8_SA(b, h) + aoff + m * 2048 + k * 1024); } while (0)
; #define PG8_LDB(dst, b, h) do { _Pragma("unroll") for (int n = 0; n < 2; ++n) _Pragma("unroll") for (int k = 0; k < 2; ++k) dst[n][k] = *(const PG8_LAS bf16x8*)(lds + PG8_SB(b, h) + boff + n * 2048 + k * 1024); } while (0)
; #define PG8_MMA(ai, bj, At, Bt) do { __builtin_amdgcn_s_setprio(1); _Pragma("unroll") for (int m = 0; m < 4; ++m) _Pragma("unroll") for (int n = 0; n < 2; ++n) _Pragma("unroll") for (int k = 0; k < 2; ++k) \
;         acc[ai][bj][m][n] = __builtin_amdgcn_mfma_f32_16x16x32_bf16(Bt[n][k], At[m][k], acc[ai][bj][m][n], 0, 0, 0); __builtin_amdgcn_s_setprio(0); } while (0)
; #define PG8_WAIT_V(n) asm volatile("s_waitcnt vmcnt(" #n ")" ::: "memory")
;     ...
;         const bool has_next = S.next(ui + 1, nxt);
;         const char* nA = has_next ? (const char*)gA + (size_t)nxt.pm * tstepA + (size_t)nxt.pn * acolB : cA; const char* nB = has_next ? (const char*)gB + (size_t)nxt.pn * tstepB : cB;
;         for (int t = 0; t < nt; t += 2) {
;             const bool last = (t == nt - 2);
;             const char* a1 = cA + (size_t)(t + 1) * kstep;
;             const char* a2 = last ? nA : cA + (size_t)(t + 2) * kstep; const char* b2 = last ? nB : cB + (size_t)(t + 2) * kstep;
;             const char* a3 = a2 + kstep; const char* b3 = b2 + kstep;
;             if (last && has_next) S.a_ready(nxt);
;             if constexpr (SP2) {
;             PG8_LDB(B0, 0, 0); PG8_LDB(B1, 0, 1); PG8_SCHED; PG8_LDA(At, 0, 0); PG8_STAGE(PG8_SA(1, 1), a1 + hstepA, voffA);
;             PG8_WAIT_V(8); PG8_WAIT_L(0); PG8_BAR; PG8_MMA(0, 0, At, B0); PG8_MMA(0, 1, At, B1); PG8_BAR; PG8_SCHED;
;             PG8_LDA(At, 0, 1); PG8_STAGE(PG8_SB(0, 0), b2, voffB); PG8_STAGE(PG8_SB(0, 1), b2 + hstepB, voffB); PG8_STAGE(PG8_SA(0, 0), a2, voffA);
;             PG8_WAIT_V(8); PG8_WAIT_L(0); PG8_BAR; PG8_MMA(1, 0, At, B0); PG8_MMA(1, 1, At, B1); PG8_BAR; PG8_SCHED;
.Lhalf_entry:
	s_add_u32 s24, s8, 0x100
	s_addc_u32 s25, s9, 0
	s_add_u32 s6, s10, 0x80
	s_addc_u32 s7, s11, 0
	s_mov_b32 s8, 0
	s_add_i32 s10, s8, 2
	s_add_u32 s11, s6, 0x80
	s_addc_u32 s9, s7, 0
	s_add_i32 s27, 0, 0x10000
	s_cmp_eq_u32 s18, s8
	s_cselect_b32 s9, s41, s9
	s_cselect_b32 s8, s40, s11
	v_add_u32_e32 v140, s27, v151
	s_cselect_b32 s35, s91, s25
	s_cselect_b32 s34, s90, s24
	s_add_i32 s11, 0, 0x14000
	ds_read_b128 v[156:159], v140
	ds_read_b128 v[160:163], v140 offset:1024
	ds_read_b128 v[172:175], v140 offset:2048
	ds_read_b128 v[176:179], v140 offset:3072
	v_add_u32_e32 v140, s11, v151
	ds_read_b128 v[180:183], v140
	ds_read_b128 v[184:187], v140 offset:1024
	ds_read_b128 v[188:191], v140 offset:2048
	ds_read_b128 v[192:195], v140 offset:3072
	v_lshl_add_u64 v[164:165], s[6:7], 0, v[138:139]
	s_add_i32 m0, s3, 0xc000
	ds_read_b128 v[196:199], v154
	ds_read_b128 v[200:203], v154 offset:1024
	ds_read_b128 v[204:207], v154 offset:2048
	ds_read_b128 v[208:211], v154 offset:3072
	ds_read_b128 v[212:215], v154 offset:4096
	ds_read_b128 v[216:219], v154 offset:5120
	ds_read_b128 v[220:223], v154 offset:6144
	ds_read_b128 v[224:227], v154 offset:7168
	global_load_lds_dwordx4 v[164:165], off
	v_lshl_add_u64 v[164:165], s[6:7], 0, v[136:137]
	s_add_i32 m0, s3, 0xe000
	s_nop 0
	global_load_lds_dwordx4 v[164:165], off
	s_waitcnt vmcnt(8)
	s_waitcnt lgkmcnt(0)
	s_barrier
	s_waitcnt lgkmcnt(0)
	s_bitcmp1_b32 s101, 1
	s_cbranch_scc1 .Lmfskip0
	v_mfma_f32_16x16x32_bf16 v[126:129], v[156:159], v[196:199], 0
	v_mfma_f32_16x16x32_bf16 v[126:129], v[160:163], v[200:203], v[126:129]
	v_mfma_f32_16x16x32_bf16 v[110:113], v[156:159], v[204:207], 0
	v_mfma_f32_16x16x32_bf16 v[110:113], v[160:163], v[208:211], v[110:113]
	v_mfma_f32_16x16x32_bf16 v[94:97], v[156:159], v[212:215], 0
	v_mfma_f32_16x16x32_bf16 v[94:97], v[160:163], v[216:219], v[94:97]
	v_mfma_f32_16x16x32_bf16 v[78:81], v[156:159], v[220:223], 0
	v_mfma_f32_16x16x32_bf16 v[78:81], v[160:163], v[224:227], v[78:81]
	v_mfma_f32_16x16x32_bf16 v[122:125], v[172:175], v[196:199], 0
	v_mfma_f32_16x16x32_bf16 v[122:125], v[176:179], v[200:203], v[122:125]
	v_mfma_f32_16x16x32_bf16 v[106:109], v[172:175], v[204:207], 0
	v_mfma_f32_16x16x32_bf16 v[106:109], v[176:179], v[208:211], v[106:109]
	v_mfma_f32_16x16x32_bf16 v[90:93], v[172:175], v[212:215], 0
	v_mfma_f32_16x16x32_bf16 v[90:93], v[176:179], v[216:219], v[90:93]
	v_mfma_f32_16x16x32_bf16 v[74:77], v[172:175], v[220:223], 0
	v_mfma_f32_16x16x32_bf16 v[74:77], v[176:179], v[224:227], v[74:77]
	v_mfma_f32_16x16x32_bf16 v[118:121], v[180:183], v[196:199], 0
	v_mfma_f32_16x16x32_bf16 v[118:121], v[184:187], v[200:203], v[118:121]
	v_mfma_f32_16x16x32_bf16 v[102:105], v[180:183], v[204:207], 0
	v_mfma_f32_16x16x32_bf16 v[102:105], v[184:187], v[208:211], v[102:105]
	v_mfma_f32_16x16x32_bf16 v[86:89], v[180:183], v[212:215], 0
	v_mfma_f32_16x16x32_bf16 v[86:89], v[184:187], v[216:219], v[86:89]
	v_mfma_f32_16x16x32_bf16 v[70:73], v[180:183], v[220:223], 0
	v_mfma_f32_16x16x32_bf16 v[70:73], v[184:187], v[224:227], v[70:73]
	v_mfma_f32_16x16x32_bf16 v[114:117], v[188:191], v[196:199], 0
	v_mfma_f32_16x16x32_bf16 v[114:117], v[192:195], v[200:203], v[114:117]
	v_mfma_f32_16x16x32_bf16 v[98:101], v[188:191], v[204:207], 0
	v_mfma_f32_16x16x32_bf16 v[98:101], v[192:195], v[208:211], v[98:101]
	v_mfma_f32_16x16x32_bf16 v[82:85], v[188:191], v[212:215], 0
	v_mfma_f32_16x16x32_bf16 v[82:85], v[192:195], v[216:219], v[82:85]
	v_mfma_f32_16x16x32_bf16 v[66:69], v[188:191], v[220:223], 0
	v_mfma_f32_16x16x32_bf16 v[66:69], v[192:195], v[224:227], v[66:69]
.Lmfskip0:
	s_barrier
	s_add_i32 s27, s27, s0
	v_lshl_add_u64 v[164:165], s[34:35], 0, v[166:167]
	s_mov_b32 m0, s27
	ds_read_b128 v[196:199], v154 offset:16384
	ds_read_b128 v[200:203], v154 offset:17408
	ds_read_b128 v[204:207], v154 offset:18432
	ds_read_b128 v[208:211], v154 offset:19456
	ds_read_b128 v[212:215], v154 offset:20480
	ds_read_b128 v[216:219], v154 offset:21504
	ds_read_b128 v[220:223], v154 offset:22528
	ds_read_b128 v[224:227], v154 offset:23552
	global_load_lds_dwordx4 v[164:165], off
	s_add_i32 m0, s27, 0x2000
	v_lshl_add_u64 v[168:169], s[34:35], 0, v[130:131]
	s_add_u32 s34, s34, s58
	s_addc_u32 s35, s35, s59
	s_add_i32 s11, s11, s0
	global_load_lds_dwordx4 v[168:169], off
	v_lshl_add_u64 v[170:171], s[34:35], 0, v[166:167]
	s_mov_b32 m0, s11
	v_lshl_add_u64 v[228:229], s[34:35], 0, v[130:131]
	global_load_lds_dwordx4 v[170:171], off
	s_add_i32 m0, s11, 0x2000
	v_lshl_add_u64 v[230:231], s[8:9], 0, v[134:135]
	global_load_lds_dwordx4 v[228:229], off
	s_mov_b32 m0, s3
	v_lshl_add_u64 v[232:233], s[8:9], 0, v[132:133]
	global_load_lds_dwordx4 v[230:231], off
	s_mov_b32 m0, s12
	s_nop 0
	global_load_lds_dwordx4 v[232:233], off
	s_waitcnt vmcnt(8)
	s_waitcnt lgkmcnt(0)
	s_barrier
	s_waitcnt lgkmcnt(0)
	s_bitcmp1_b32 s101, 0
	s_cbranch_scc1 .Lmfskip1
	v_mfma_f32_16x16x32_bf16 v[62:65], v[156:159], v[196:199], 0
	v_mfma_f32_16x16x32_bf16 v[62:65], v[160:163], v[200:203], v[62:65]
	v_mfma_f32_16x16x32_bf16 v[46:49], v[156:159], v[204:207], 0
	v_mfma_f32_16x16x32_bf16 v[46:49], v[160:163], v[208:211], v[46:49]
	v_mfma_f32_16x16x32_bf16 v[30:33], v[156:159], v[212:215], 0
	v_mfma_f32_16x16x32_bf16 v[30:33], v[160:163], v[216:219], v[30:33]
	v_mfma_f32_16x16x32_bf16 v[14:17], v[156:159], v[220:223], 0
	v_mfma_f32_16x16x32_bf16 v[14:17], v[160:163], v[224:227], v[14:17]
	v_mfma_f32_16x16x32_bf16 v[58:61], v[172:175], v[196:199], 0
	v_mfma_f32_16x16x32_bf16 v[58:61], v[176:179], v[200:203], v[58:61]
	v_mfma_f32_16x16x32_bf16 v[42:45], v[172:175], v[204:207], 0
	v_mfma_f32_16x16x32_bf16 v[42:45], v[176:179], v[208:211], v[42:45]
	v_mfma_f32_16x16x32_bf16 v[26:29], v[172:175], v[212:215], 0
	v_mfma_f32_16x16x32_bf16 v[26:29], v[176:179], v[216:219], v[26:29]
	v_mfma_f32_16x16x32_bf16 v[10:13], v[172:175], v[220:223], 0
	v_mfma_f32_16x16x32_bf16 v[10:13], v[176:179], v[224:227], v[10:13]
	v_mfma_f32_16x16x32_bf16 v[54:57], v[180:183], v[196:199], 0
	v_mfma_f32_16x16x32_bf16 v[54:57], v[184:187], v[200:203], v[54:57]
	v_mfma_f32_16x16x32_bf16 v[38:41], v[180:183], v[204:207], 0
	v_mfma_f32_16x16x32_bf16 v[38:41], v[184:187], v[208:211], v[38:41]
	v_mfma_f32_16x16x32_bf16 v[22:25], v[180:183], v[212:215], 0
	v_mfma_f32_16x16x32_bf16 v[22:25], v[184:187], v[216:219], v[22:25]
	v_mfma_f32_16x16x32_bf16 v[6:9], v[180:183], v[220:223], 0
	v_mfma_f32_16x16x32_bf16 v[6:9], v[184:187], v[224:227], v[6:9]
	v_mfma_f32_16x16x32_bf16 v[50:53], v[188:191], v[196:199], 0
	v_mfma_f32_16x16x32_bf16 v[50:53], v[192:195], v[200:203], v[50:53]
	v_mfma_f32_16x16x32_bf16 v[34:37], v[188:191], v[204:207], 0
	v_mfma_f32_16x16x32_bf16 v[34:37], v[192:195], v[208:211], v[34:37]
	v_mfma_f32_16x16x32_bf16 v[18:21], v[188:191], v[212:215], 0
	v_mfma_f32_16x16x32_bf16 v[18:21], v[192:195], v[216:219], v[18:21]
	v_mfma_f32_16x16x32_bf16 v[2:5], v[188:191], v[220:223], 0
	v_mfma_f32_16x16x32_bf16 v[2:5], v[192:195], v[224:227], v[2:5]
; #define PG8_STAGE(bufoff, gbase, voff) do { _Pragma("unroll") for (int _i = 0; _i < 2; ++_i) \
;         __builtin_amdgcn_global_load_lds((const unsigned*)((const char*)(gbase) + (voff)[_i]), (PG8_LAS unsigned*)(lds + (bufoff) + ldsw + _i * 8192), 16, 0, 0); } while (0)
; #define PG8_LDA(dst, b, h) do { _Pragma("unroll") for (int m = 0; m < 4; ++m) _Pragma("unroll") for (int k = 0; k < 2; ++k) dst[m][k] = *(const PG8_LAS bf16x8*)(lds + PG8_SA(b, h) + aoff + m * 2048 + k * 1024); } while (0)
; #define PG8_LDB(dst, b, h) do { _Pragma("unroll") for (int n = 0; n < 2; ++n) _Pragma("unroll") for (int k = 0; k < 2; ++k) dst[n][k] = *(const PG8_LAS bf16x8*)(lds + PG8_SB(b, h) + boff + n * 2048 + k * 1024); } while (0)
; #define PG8_MMA(ai, bj, At, Bt) do { __builtin_amdgcn_s_setprio(1); _Pragma("unroll") for (int m = 0; m < 4; ++m) _Pragma("unroll") for (int n = 0; n < 2; ++n) _Pragma("unroll") for (int k = 0; k < 2; ++k) \
;         acc[ai][bj][m][n] = __builtin_amdgcn_mfma_f32_16x16x32_bf16(Bt[n][k], At[m][k], acc[ai][bj][m][n], 0, 0, 0); __builtin_amdgcn_s_setprio(0); } while (0)
; #define PG8_WAIT_V(n) asm volatile("s_waitcnt vmcnt(" #n ")" ::: "memory")
; #define PG8_WAIT_L(n) asm volatile("s_waitcnt lgkmcnt(" #n ")" ::: "memory")
; #define PG8_BAR __builtin_amdgcn_s_barrier()
; #define PG8_SCHED __builtin_amdgcn_sched_barrier(0)
;     ...
;             PG8_WAIT_V(8); PG8_WAIT_L(0); PG8_BAR; PG8_MMA(1, 0, At, B0); PG8_MMA(1, 1, At, B1); PG8_BAR; PG8_SCHED;
;             PG8_LDB(B0, 1, 0); PG8_LDB(B1, 1, 1); PG8_SCHED; PG8_LDA(At, 1, 0); PG8_STAGE(PG8_SA(0, 1), a2 + hstepA, voffA);
;             PG8_WAIT_V(8); PG8_WAIT_L(0); PG8_BAR; PG8_MMA(0, 0, At, B0); PG8_MMA(0, 1, At, B1); PG8_BAR; PG8_SCHED;
;             PG8_LDA(At, 1, 1); PG8_STAGE(PG8_SB(1, 0), b3, voffB); PG8_STAGE(PG8_SB(1, 1), b3 + hstepB, voffB); PG8_STAGE(PG8_SA(1, 0), a3, voffA);
;             PG8_WAIT_V(8); PG8_WAIT_L(0); PG8_BAR; PG8_MMA(1, 0, At, B0); PG8_MMA(1, 1, At, B1); PG8_BAR; PG8_SCHED;
.Lmfskip1:
	s_barrier
	s_add_i32 s11, 0, 0x18000
	v_add_u32_e32 v140, s11, v151
	s_add_i32 s27, 0, 0x1c000
	ds_read_b128 v[156:159], v140
	ds_read_b128 v[160:163], v140 offset:1024
	ds_read_b128 v[172:175], v140 offset:2048
	ds_read_b128 v[176:179], v140 offset:3072
	v_add_u32_e32 v140, s27, v151
	ds_read_b128 v[180:183], v140
	ds_read_b128 v[184:187], v140 offset:1024
	ds_read_b128 v[188:191], v140 offset:2048
	ds_read_b128 v[192:195], v140 offset:3072
	s_add_u32 s8, s8, s58
	s_addc_u32 s9, s9, s59
	s_mov_b32 m0, s13
	v_lshl_add_u64 v[234:235], s[8:9], 0, v[134:135]
	ds_read_b128 v[196:199], v154 offset:32768
	ds_read_b128 v[200:203], v154 offset:33792
	ds_read_b128 v[204:207], v154 offset:34816
	ds_read_b128 v[208:211], v154 offset:35840
	ds_read_b128 v[212:215], v154 offset:36864
	ds_read_b128 v[216:219], v154 offset:37888
	ds_read_b128 v[220:223], v154 offset:38912
	ds_read_b128 v[224:227], v154 offset:39936
	global_load_lds_dwordx4 v[234:235], off
	v_lshl_add_u64 v[234:235], s[8:9], 0, v[132:133]
	s_mov_b32 m0, s14
	s_nop 0
	global_load_lds_dwordx4 v[234:235], off
	s_waitcnt vmcnt(8)
	s_waitcnt lgkmcnt(0)
	s_barrier
	s_waitcnt lgkmcnt(0)
	s_bitcmp1_b32 s101, 1
	s_cbranch_scc1 .Lmfskip2
	v_mfma_f32_16x16x32_bf16 v[126:129], v[156:159], v[196:199], v[126:129]
	v_mfma_f32_16x16x32_bf16 v[126:129], v[160:163], v[200:203], v[126:129]
	v_mfma_f32_16x16x32_bf16 v[110:113], v[156:159], v[204:207], v[110:113]
	v_mfma_f32_16x16x32_bf16 v[110:113], v[160:163], v[208:211], v[110:113]
	v_mfma_f32_16x16x32_bf16 v[94:97], v[156:159], v[212:215], v[94:97]
	v_mfma_f32_16x16x32_bf16 v[94:97], v[160:163], v[216:219], v[94:97]
	v_mfma_f32_16x16x32_bf16 v[78:81], v[156:159], v[220:223], v[78:81]
	v_mfma_f32_16x16x32_bf16 v[78:81], v[160:163], v[224:227], v[78:81]
	v_mfma_f32_16x16x32_bf16 v[122:125], v[172:175], v[196:199], v[122:125]
	v_mfma_f32_16x16x32_bf16 v[122:125], v[176:179], v[200:203], v[122:125]
	v_mfma_f32_16x16x32_bf16 v[106:109], v[172:175], v[204:207], v[106:109]
	v_mfma_f32_16x16x32_bf16 v[106:109], v[176:179], v[208:211], v[106:109]
	v_mfma_f32_16x16x32_bf16 v[90:93], v[172:175], v[212:215], v[90:93]
	v_mfma_f32_16x16x32_bf16 v[90:93], v[176:179], v[216:219], v[90:93]
	v_mfma_f32_16x16x32_bf16 v[74:77], v[172:175], v[220:223], v[74:77]
	v_mfma_f32_16x16x32_bf16 v[74:77], v[176:179], v[224:227], v[74:77]
	v_mfma_f32_16x16x32_bf16 v[118:121], v[180:183], v[196:199], v[118:121]
	v_mfma_f32_16x16x32_bf16 v[118:121], v[184:187], v[200:203], v[118:121]
	v_mfma_f32_16x16x32_bf16 v[102:105], v[180:183], v[204:207], v[102:105]
	v_mfma_f32_16x16x32_bf16 v[102:105], v[184:187], v[208:211], v[102:105]
	v_mfma_f32_16x16x32_bf16 v[86:89], v[180:183], v[212:215], v[86:89]
	v_mfma_f32_16x16x32_bf16 v[86:89], v[184:187], v[216:219], v[86:89]
	v_mfma_f32_16x16x32_bf16 v[70:73], v[180:183], v[220:223], v[70:73]
	v_mfma_f32_16x16x32_bf16 v[70:73], v[184:187], v[224:227], v[70:73]
	v_mfma_f32_16x16x32_bf16 v[114:117], v[188:191], v[196:199], v[114:117]
	v_mfma_f32_16x16x32_bf16 v[114:117], v[192:195], v[200:203], v[114:117]
	v_mfma_f32_16x16x32_bf16 v[98:101], v[188:191], v[204:207], v[98:101]
	v_mfma_f32_16x16x32_bf16 v[98:101], v[192:195], v[208:211], v[98:101]
	v_mfma_f32_16x16x32_bf16 v[82:85], v[188:191], v[212:215], v[82:85]
	v_mfma_f32_16x16x32_bf16 v[82:85], v[192:195], v[216:219], v[82:85]
	v_mfma_f32_16x16x32_bf16 v[66:69], v[188:191], v[220:223], v[66:69]
	v_mfma_f32_16x16x32_bf16 v[66:69], v[192:195], v[224:227], v[66:69]
.Lmfskip2:
	s_barrier
	s_add_i32 s8, s11, s0
	v_lshl_add_u64 v[164:165], v[164:165], 0, s[62:63]
	s_mov_b32 m0, s8
	ds_read_b128 v[196:199], v154 offset:49152
	ds_read_b128 v[200:203], v154 offset:50176
	ds_read_b128 v[204:207], v154 offset:51200
	ds_read_b128 v[208:211], v154 offset:52224
	ds_read_b128 v[212:215], v154 offset:53248
	ds_read_b128 v[216:219], v154 offset:54272
	ds_read_b128 v[220:223], v154 offset:55296
	ds_read_b128 v[224:227], v154 offset:56320
	global_load_lds_dwordx4 v[164:165], off
	v_lshl_add_u64 v[164:165], v[168:169], 0, s[62:63]
	s_add_i32 m0, s8, 0x2000
	s_add_i32 s8, s27, s0
	global_load_lds_dwordx4 v[164:165], off
	v_lshl_add_u64 v[164:165], v[170:171], 0, s[62:63]
	s_mov_b32 m0, s8
	s_nop 0
	global_load_lds_dwordx4 v[164:165], off
	v_lshl_add_u64 v[164:165], v[228:229], 0, s[62:63]
	s_add_i32 m0, s8, 0x2000
	s_nop 0
	global_load_lds_dwordx4 v[164:165], off
	v_lshl_add_u64 v[164:165], v[230:231], 0, s[62:63]
	s_mov_b32 m0, s16
	s_nop 0
	global_load_lds_dwordx4 v[164:165], off
	v_lshl_add_u64 v[164:165], v[232:233], 0, s[62:63]
	s_mov_b32 m0, s17
	s_nop 0
	global_load_lds_dwordx4 v[164:165], off
	s_waitcnt vmcnt(8)
	s_waitcnt lgkmcnt(0)
	s_barrier
	s_waitcnt lgkmcnt(0)
	s_bitcmp1_b32 s101, 0
	s_cbranch_scc1 .Lmfskip3
	v_mfma_f32_16x16x32_bf16 v[62:65], v[156:159], v[196:199], v[62:65]
	v_mfma_f32_16x16x32_bf16 v[62:65], v[160:163], v[200:203], v[62:65]
	v_mfma_f32_16x16x32_bf16 v[46:49], v[156:159], v[204:207], v[46:49]
	v_mfma_f32_16x16x32_bf16 v[46:49], v[160:163], v[208:211], v[46:49]
	v_mfma_f32_16x16x32_bf16 v[30:33], v[156:159], v[212:215], v[30:33]
	v_mfma_f32_16x16x32_bf16 v[30:33], v[160:163], v[216:219], v[30:33]
	v_mfma_f32_16x16x32_bf16 v[14:17], v[156:159], v[220:223], v[14:17]
	v_mfma_f32_16x16x32_bf16 v[14:17], v[160:163], v[224:227], v[14:17]
	v_mfma_f32_16x16x32_bf16 v[58:61], v[172:175], v[196:199], v[58:61]
	v_mfma_f32_16x16x32_bf16 v[58:61], v[176:179], v[200:203], v[58:61]
	v_mfma_f32_16x16x32_bf16 v[42:45], v[172:175], v[204:207], v[42:45]
	v_mfma_f32_16x16x32_bf16 v[42:45], v[176:179], v[208:211], v[42:45]
	v_mfma_f32_16x16x32_bf16 v[26:29], v[172:175], v[212:215], v[26:29]
	v_mfma_f32_16x16x32_bf16 v[26:29], v[176:179], v[216:219], v[26:29]
	v_mfma_f32_16x16x32_bf16 v[10:13], v[172:175], v[220:223], v[10:13]
	v_mfma_f32_16x16x32_bf16 v[10:13], v[176:179], v[224:227], v[10:13]
	v_mfma_f32_16x16x32_bf16 v[54:57], v[180:183], v[196:199], v[54:57]
	v_mfma_f32_16x16x32_bf16 v[54:57], v[184:187], v[200:203], v[54:57]
	v_mfma_f32_16x16x32_bf16 v[38:41], v[180:183], v[204:207], v[38:41]
	v_mfma_f32_16x16x32_bf16 v[38:41], v[184:187], v[208:211], v[38:41]
	v_mfma_f32_16x16x32_bf16 v[22:25], v[180:183], v[212:215], v[22:25]
	v_mfma_f32_16x16x32_bf16 v[22:25], v[184:187], v[216:219], v[22:25]
	v_mfma_f32_16x16x32_bf16 v[6:9], v[180:183], v[220:223], v[6:9]
	v_mfma_f32_16x16x32_bf16 v[6:9], v[184:187], v[224:227], v[6:9]
	v_mfma_f32_16x16x32_bf16 v[50:53], v[188:191], v[196:199], v[50:53]
	v_mfma_f32_16x16x32_bf16 v[50:53], v[192:195], v[200:203], v[50:53]
	v_mfma_f32_16x16x32_bf16 v[34:37], v[188:191], v[204:207], v[34:37]
	v_mfma_f32_16x16x32_bf16 v[34:37], v[192:195], v[208:211], v[34:37]
	v_mfma_f32_16x16x32_bf16 v[18:21], v[188:191], v[212:215], v[18:21]
	v_mfma_f32_16x16x32_bf16 v[18:21], v[192:195], v[216:219], v[18:21]
	v_mfma_f32_16x16x32_bf16 v[2:5], v[188:191], v[220:223], v[2:5]
	v_mfma_f32_16x16x32_bf16 v[2:5], v[192:195], v[224:227], v[2:5]

; #define PG8_STAGE(bufoff, gbase, voff) do { _Pragma("unroll") for (int _i = 0; _i < 2; ++_i) \
;         __builtin_amdgcn_global_load_lds((const unsigned*)((const char*)(gbase) + (voff)[_i]), (PG8_LAS unsigned*)(lds + (bufoff) + ldsw + _i * 8192), 16, 0, 0); } while (0)
; #define PG8_LDA(dst, b, h) do { _Pragma("unroll") for (int m = 0; m < 4; ++m) _Pragma("unroll") for (int k = 0; k < 2; ++k) dst[m][k] = *(const PG8_LAS bf16x8*)(lds + PG8_SA(b, h) + aoff + m * 2048 + k * 1024); } while (0)
; #define PG8_LDB(dst, b, h) do { _Pragma("unroll") for (int n = 0; n < 2; ++n) _Pragma("unroll") for (int k = 0; k < 2; ++k) dst[n][k] = *(const PG8_LAS bf16x8*)(lds + PG8_SB(b, h) + boff + n * 2048 + k * 1024); } while (0)
; #define PG8_MMA(ai, bj, At, Bt) do { __builtin_amdgcn_s_setprio(1); _Pragma("unroll") for (int m = 0; m < 4; ++m) _Pragma("unroll") for (int n = 0; n < 2; ++n) _Pragma("unroll") for (int k = 0; k < 2; ++k) \
;         acc[ai][bj][m][n] = __builtin_amdgcn_mfma_f32_16x16x32_bf16(Bt[n][k], At[m][k], acc[ai][bj][m][n], 0, 0, 0); __builtin_amdgcn_s_setprio(0); } while (0)
; #define PG8_WAIT_V(n) asm volatile("s_waitcnt vmcnt(" #n ")" ::: "memory")
; #define PG8_WAIT_L(n) asm volatile("s_waitcnt lgkmcnt(" #n ")" ::: "memory")
; #define PG8_BAR __builtin_amdgcn_s_barrier()
; #define PG8_SCHED __builtin_amdgcn_sched_barrier(0)
;     ...
;         for (int t = 0; t < nt; t += 2) {
;             const bool last = (t == nt - 2);
;             const char* a1 = cA + (size_t)(t + 1) * kstep;
;             const char* a2 = last ? nA : cA + (size_t)(t + 2) * kstep; const char* b2 = last ? nB : cB + (size_t)(t + 2) * kstep;
;             const char* a3 = a2 + kstep; const char* b3 = b2 + kstep;
;             if (last && has_next) S.a_ready(nxt);
;             if constexpr (SP2) {
;             PG8_LDB(B0, 0, 0); PG8_LDB(B1, 0, 1); PG8_SCHED; PG8_LDA(At, 0, 0); PG8_STAGE(PG8_SA(1, 1), a1 + hstepA, voffA);
;             PG8_WAIT_V(8); PG8_WAIT_L(0); PG8_BAR; PG8_MMA(0, 0, At, B0); PG8_MMA(0, 1, At, B1); PG8_BAR; PG8_SCHED;
.Lhalf_613:
	s_add_i32 s10, s8, 2
	s_add_u32 s11, s6, 0x80
	s_addc_u32 s9, s7, 0
	s_add_i32 s27, 0, 0x10000
	s_cmp_eq_u32 s18, s8
	s_cselect_b32 s9, s41, s9
	s_cselect_b32 s8, s40, s11
	v_add_u32_e32 v140, s27, v151
	s_cselect_b32 s35, s91, s25
	s_cselect_b32 s34, s90, s24
	s_add_i32 s11, 0, 0x14000
	ds_read_b128 v[156:159], v140
	ds_read_b128 v[160:163], v140 offset:1024
	ds_read_b128 v[172:175], v140 offset:2048
	ds_read_b128 v[176:179], v140 offset:3072
	v_add_u32_e32 v140, s11, v151
	ds_read_b128 v[180:183], v140
	ds_read_b128 v[184:187], v140 offset:1024
	ds_read_b128 v[188:191], v140 offset:2048
	ds_read_b128 v[192:195], v140 offset:3072
	v_lshl_add_u64 v[164:165], s[6:7], 0, v[138:139]
	s_add_i32 m0, s3, 0xc000
	ds_read_b128 v[196:199], v154
	ds_read_b128 v[200:203], v154 offset:1024
	ds_read_b128 v[204:207], v154 offset:2048
	ds_read_b128 v[208:211], v154 offset:3072
	ds_read_b128 v[212:215], v154 offset:4096
	ds_read_b128 v[216:219], v154 offset:5120
	ds_read_b128 v[220:223], v154 offset:6144
	ds_read_b128 v[224:227], v154 offset:7168
	global_load_lds_dwordx4 v[164:165], off
	v_lshl_add_u64 v[164:165], s[6:7], 0, v[136:137]
	s_add_i32 m0, s3, 0xe000
	s_nop 0
	global_load_lds_dwordx4 v[164:165], off
	s_waitcnt vmcnt(8)
	s_waitcnt lgkmcnt(0)
	s_barrier
	s_waitcnt lgkmcnt(0)
	s_bitcmp1_b32 s101, 1
	s_cbranch_scc1 .Lmfskip4
	v_mfma_f32_16x16x32_bf16 v[126:129], v[156:159], v[196:199], v[126:129]
	v_mfma_f32_16x16x32_bf16 v[126:129], v[160:163], v[200:203], v[126:129]
	v_mfma_f32_16x16x32_bf16 v[110:113], v[156:159], v[204:207], v[110:113]
	v_mfma_f32_16x16x32_bf16 v[110:113], v[160:163], v[208:211], v[110:113]
	v_mfma_f32_16x16x32_bf16 v[94:97], v[156:159], v[212:215], v[94:97]
	v_mfma_f32_16x16x32_bf16 v[94:97], v[160:163], v[216:219], v[94:97]
	v_mfma_f32_16x16x32_bf16 v[78:81], v[156:159], v[220:223], v[78:81]
	v_mfma_f32_16x16x32_bf16 v[78:81], v[160:163], v[224:227], v[78:81]
	v_mfma_f32_16x16x32_bf16 v[122:125], v[172:175], v[196:199], v[122:125]
	v_mfma_f32_16x16x32_bf16 v[122:125], v[176:179], v[200:203], v[122:125]
	v_mfma_f32_16x16x32_bf16 v[106:109], v[172:175], v[204:207], v[106:109]
	v_mfma_f32_16x16x32_bf16 v[106:109], v[176:179], v[208:211], v[106:109]
	v_mfma_f32_16x16x32_bf16 v[90:93], v[172:175], v[212:215], v[90:93]
	v_mfma_f32_16x16x32_bf16 v[90:93], v[176:179], v[216:219], v[90:93]
	v_mfma_f32_16x16x32_bf16 v[74:77], v[172:175], v[220:223], v[74:77]
	v_mfma_f32_16x16x32_bf16 v[74:77], v[176:179], v[224:227], v[74:77]
	v_mfma_f32_16x16x32_bf16 v[118:121], v[180:183], v[196:199], v[118:121]
	v_mfma_f32_16x16x32_bf16 v[118:121], v[184:187], v[200:203], v[118:121]
	v_mfma_f32_16x16x32_bf16 v[102:105], v[180:183], v[204:207], v[102:105]
	v_mfma_f32_16x16x32_bf16 v[102:105], v[184:187], v[208:211], v[102:105]
	v_mfma_f32_16x16x32_bf16 v[86:89], v[180:183], v[212:215], v[86:89]
	v_mfma_f32_16x16x32_bf16 v[86:89], v[184:187], v[216:219], v[86:89]
	v_mfma_f32_16x16x32_bf16 v[70:73], v[180:183], v[220:223], v[70:73]
	v_mfma_f32_16x16x32_bf16 v[70:73], v[184:187], v[224:227], v[70:73]
	v_mfma_f32_16x16x32_bf16 v[114:117], v[188:191], v[196:199], v[114:117]
	v_mfma_f32_16x16x32_bf16 v[114:117], v[192:195], v[200:203], v[114:117]
	v_mfma_f32_16x16x32_bf16 v[98:101], v[188:191], v[204:207], v[98:101]
	v_mfma_f32_16x16x32_bf16 v[98:101], v[192:195], v[208:211], v[98:101]
	v_mfma_f32_16x16x32_bf16 v[82:85], v[188:191], v[212:215], v[82:85]
	v_mfma_f32_16x16x32_bf16 v[82:85], v[192:195], v[216:219], v[82:85]
	v_mfma_f32_16x16x32_bf16 v[66:69], v[188:191], v[220:223], v[66:69]
	v_mfma_f32_16x16x32_bf16 v[66:69], v[192:195], v[224:227], v[66:69]
; #define PG8_STAGE(bufoff, gbase, voff) do { _Pragma("unroll") for (int _i = 0; _i < 2; ++_i) \
;         __builtin_amdgcn_global_load_lds((const unsigned*)((const char*)(gbase) + (voff)[_i]), (PG8_LAS unsigned*)(lds + (bufoff) + ldsw + _i * 8192), 16, 0, 0); } while (0)
; #define PG8_LDA(dst, b, h) do { _Pragma("unroll") for (int m = 0; m < 4; ++m) _Pragma("unroll") for (int k = 0; k < 2; ++k) dst[m][k] = *(const PG8_LAS bf16x8*)(lds + PG8_SA(b, h) + aoff + m * 2048 + k * 1024); } while (0)
; #define PG8_MMA(ai, bj, At, Bt) do { __builtin_amdgcn_s_setprio(1); _Pragma("unroll") for (int m = 0; m < 4; ++m) _Pragma("unroll") for (int n = 0; n < 2; ++n) _Pragma("unroll") for (int k = 0; k < 2; ++k) \
;         acc[ai][bj][m][n] = __builtin_amdgcn_mfma_f32_16x16x32_bf16(Bt[n][k], At[m][k], acc[ai][bj][m][n], 0, 0, 0); __builtin_amdgcn_s_setprio(0); } while (0)
; #define PG8_WAIT_V(n) asm volatile("s_waitcnt vmcnt(" #n ")" ::: "memory")
; #define PG8_WAIT_L(n) asm volatile("s_waitcnt lgkmcnt(" #n ")" ::: "memory")
; #define PG8_BAR __builtin_amdgcn_s_barrier()
; #define PG8_SCHED __builtin_amdgcn_sched_barrier(0)
;     ...
;             PG8_WAIT_V(8); PG8_WAIT_L(0); PG8_BAR; PG8_MMA(0, 0, At, B0); PG8_MMA(0, 1, At, B1); PG8_BAR; PG8_SCHED;
;             PG8_LDA(At, 0, 1); PG8_STAGE(PG8_SB(0, 0), b2, voffB); PG8_STAGE(PG8_SB(0, 1), b2 + hstepB, voffB); PG8_STAGE(PG8_SA(0, 0), a2, voffA);
;             PG8_WAIT_V(8); PG8_WAIT_L(0); PG8_BAR; PG8_MMA(1, 0, At, B0); PG8_MMA(1, 1, At, B1); PG8_BAR; PG8_SCHED;
.Lmfskip4:
	s_barrier
	s_add_i32 s27, s27, s0
	v_lshl_add_u64 v[164:165], s[34:35], 0, v[166:167]
	s_mov_b32 m0, s27
	ds_read_b128 v[196:199], v154 offset:16384
	ds_read_b128 v[200:203], v154 offset:17408
	ds_read_b128 v[204:207], v154 offset:18432
	ds_read_b128 v[208:211], v154 offset:19456
	ds_read_b128 v[212:215], v154 offset:20480
	ds_read_b128 v[216:219], v154 offset:21504
	ds_read_b128 v[220:223], v154 offset:22528
	ds_read_b128 v[224:227], v154 offset:23552
	global_load_lds_dwordx4 v[164:165], off
	s_add_i32 m0, s27, 0x2000
	v_lshl_add_u64 v[168:169], s[34:35], 0, v[130:131]
	s_add_u32 s34, s34, s58
	s_addc_u32 s35, s35, s59
	s_add_i32 s11, s11, s0
	global_load_lds_dwordx4 v[168:169], off
	v_lshl_add_u64 v[170:171], s[34:35], 0, v[166:167]
	s_mov_b32 m0, s11
	v_lshl_add_u64 v[228:229], s[34:35], 0, v[130:131]
	global_load_lds_dwordx4 v[170:171], off
	s_add_i32 m0, s11, 0x2000
	v_lshl_add_u64 v[230:231], s[8:9], 0, v[134:135]
	global_load_lds_dwordx4 v[228:229], off
	s_mov_b32 m0, s3
	v_lshl_add_u64 v[232:233], s[8:9], 0, v[132:133]
	global_load_lds_dwordx4 v[230:231], off
	s_mov_b32 m0, s12
	s_nop 0
	global_load_lds_dwordx4 v[232:233], off
	s_waitcnt vmcnt(8)
	s_waitcnt lgkmcnt(0)
	s_barrier
	s_waitcnt lgkmcnt(0)
	s_bitcmp1_b32 s101, 0
	s_cbranch_scc1 .Lmfskip5
	v_mfma_f32_16x16x32_bf16 v[62:65], v[156:159], v[196:199], v[62:65]
	v_mfma_f32_16x16x32_bf16 v[62:65], v[160:163], v[200:203], v[62:65]
	v_mfma_f32_16x16x32_bf16 v[46:49], v[156:159], v[204:207], v[46:49]
	v_mfma_f32_16x16x32_bf16 v[46:49], v[160:163], v[208:211], v[46:49]
	v_mfma_f32_16x16x32_bf16 v[30:33], v[156:159], v[212:215], v[30:33]
	v_mfma_f32_16x16x32_bf16 v[30:33], v[160:163], v[216:219], v[30:33]
	v_mfma_f32_16x16x32_bf16 v[14:17], v[156:159], v[220:223], v[14:17]
	v_mfma_f32_16x16x32_bf16 v[14:17], v[160:163], v[224:227], v[14:17]
	v_mfma_f32_16x16x32_bf16 v[58:61], v[172:175], v[196:199], v[58:61]
	v_mfma_f32_16x16x32_bf16 v[58:61], v[176:179], v[200:203], v[58:61]
	v_mfma_f32_16x16x32_bf16 v[42:45], v[172:175], v[204:207], v[42:45]
	v_mfma_f32_16x16x32_bf16 v[42:45], v[176:179], v[208:211], v[42:45]
	v_mfma_f32_16x16x32_bf16 v[26:29], v[172:175], v[212:215], v[26:29]
	v_mfma_f32_16x16x32_bf16 v[26:29], v[176:179], v[216:219], v[26:29]
	v_mfma_f32_16x16x32_bf16 v[10:13], v[172:175], v[220:223], v[10:13]
	v_mfma_f32_16x16x32_bf16 v[10:13], v[176:179], v[224:227], v[10:13]
	v_mfma_f32_16x16x32_bf16 v[54:57], v[180:183], v[196:199], v[54:57]
	v_mfma_f32_16x16x32_bf16 v[54:57], v[184:187], v[200:203], v[54:57]
	v_mfma_f32_16x16x32_bf16 v[38:41], v[180:183], v[204:207], v[38:41]
	v_mfma_f32_16x16x32_bf16 v[38:41], v[184:187], v[208:211], v[38:41]
	v_mfma_f32_16x16x32_bf16 v[22:25], v[180:183], v[212:215], v[22:25]
	v_mfma_f32_16x16x32_bf16 v[22:25], v[184:187], v[216:219], v[22:25]
	v_mfma_f32_16x16x32_bf16 v[6:9], v[180:183], v[220:223], v[6:9]
	v_mfma_f32_16x16x32_bf16 v[6:9], v[184:187], v[224:227], v[6:9]
	v_mfma_f32_16x16x32_bf16 v[50:53], v[188:191], v[196:199], v[50:53]
	v_mfma_f32_16x16x32_bf16 v[50:53], v[192:195], v[200:203], v[50:53]
	v_mfma_f32_16x16x32_bf16 v[34:37], v[188:191], v[204:207], v[34:37]
	v_mfma_f32_16x16x32_bf16 v[34:37], v[192:195], v[208:211], v[34:37]
	v_mfma_f32_16x16x32_bf16 v[18:21], v[188:191], v[212:215], v[18:21]
	v_mfma_f32_16x16x32_bf16 v[18:21], v[192:195], v[216:219], v[18:21]
	v_mfma_f32_16x16x32_bf16 v[2:5], v[188:191], v[220:223], v[2:5]
	v_mfma_f32_16x16x32_bf16 v[2:5], v[192:195], v[224:227], v[2:5]

; #define PG8_STAGE(bufoff, gbase, voff) do { _Pragma("unroll") for (int _i = 0; _i < 2; ++_i) \
;         __builtin_amdgcn_global_load_lds((const unsigned*)((const char*)(gbase) + (voff)[_i]), (PG8_LAS unsigned*)(lds + (bufoff) + ldsw + _i * 8192), 16, 0, 0); } while (0)
; #define PG8_LDA(dst, b, h) do { _Pragma("unroll") for (int m = 0; m < 4; ++m) _Pragma("unroll") for (int k = 0; k < 2; ++k) dst[m][k] = *(const PG8_LAS bf16x8*)(lds + PG8_SA(b, h) + aoff + m * 2048 + k * 1024); } while (0)
; #define PG8_LDB(dst, b, h) do { _Pragma("unroll") for (int n = 0; n < 2; ++n) _Pragma("unroll") for (int k = 0; k < 2; ++k) dst[n][k] = *(const PG8_LAS bf16x8*)(lds + PG8_SB(b, h) + boff + n * 2048 + k * 1024); } while (0)
; #define PG8_MMA(ai, bj, At, Bt) do { __builtin_amdgcn_s_setprio(1); _Pragma("unroll") for (int m = 0; m < 4; ++m) _Pragma("unroll") for (int n = 0; n < 2; ++n) _Pragma("unroll") for (int k = 0; k < 2; ++k) \
;         acc[ai][bj][m][n] = __builtin_amdgcn_mfma_f32_16x16x32_bf16(Bt[n][k], At[m][k], acc[ai][bj][m][n], 0, 0, 0); __builtin_amdgcn_s_setprio(0); } while (0)
; #define PG8_WAIT_V(n) asm volatile("s_waitcnt vmcnt(" #n ")" ::: "memory")
; #define PG8_WAIT_L(n) asm volatile("s_waitcnt lgkmcnt(" #n ")" ::: "memory")
; #define PG8_BAR __builtin_amdgcn_s_barrier()
; #define PG8_SCHED __builtin_amdgcn_sched_barrier(0)
;     ...
;         for (int t = 0; t < nt; t += 2) {
;             const bool last = (t == nt - 2);
;             const char* a1 = cA + (size_t)(t + 1) * kstep;
;             const char* a2 = last ? nA : cA + (size_t)(t + 2) * kstep; const char* b2 = last ? nB : cB + (size_t)(t + 2) * kstep;
;             const char* a3 = a2 + kstep; const char* b3 = b2 + kstep;
;             if (last && has_next) S.a_ready(nxt);
;             if constexpr (SP2) {
;             PG8_LDB(B0, 0, 0); PG8_LDB(B1, 0, 1); PG8_SCHED; PG8_LDA(At, 0, 0); PG8_STAGE(PG8_SA(1, 1), a1 + hstepA, voffA);
;             PG8_WAIT_V(8); PG8_WAIT_L(0); PG8_BAR; PG8_MMA(0, 0, At, B0); PG8_MMA(0, 1, At, B1); PG8_BAR; PG8_SCHED;
;             PG8_LDA(At, 0, 1); PG8_STAGE(PG8_SB(0, 0), b2, voffB); PG8_STAGE(PG8_SB(0, 1), b2 + hstepB, voffB); PG8_STAGE(PG8_SA(0, 0), a2, voffA);
;             PG8_WAIT_V(8); PG8_WAIT_L(0); PG8_BAR; PG8_MMA(1, 0, At, B0); PG8_MMA(1, 1, At, B1); PG8_BAR; PG8_SCHED;
.LBB0_750:
	s_andn2_b64 vcc, exec, s[86:87]
	s_waitcnt lgkmcnt(0)
	s_cbranch_vccnz .LBB0_753
	s_add_u32 s10, s6, 0x100
	s_addc_u32 s11, s7, 0
	s_add_u32 s6, s8, 0x200000
	s_addc_u32 s7, s9, 0
	s_mov_b32 s8, 0
	s_add_i32 s25, s8, 2
	s_add_u32 s27, s6, 0x200000
	s_addc_u32 s9, s7, 0
	s_add_i32 s31, 0, 0x10000
	s_cmp_eq_u32 s19, s8
	s_cselect_b32 s9, s43, s9
	s_cselect_b32 s8, s42, s27
	s_cselect_b32 s35, s91, s11
	s_cselect_b32 s34, s90, s10
	s_add_i32 s27, 0, 0x14000
	v_add_u32_e32 v148, s31, v229
	v_add_u32_e32 v164, s27, v229
	ds_read_b128 v[136:139], v148
	ds_read_b128 v[140:143], v148 offset:1024
	ds_read_b128 v[144:147], v148 offset:2048
	ds_read_b128 v[148:151], v148 offset:3072
	ds_read_b128 v[152:155], v164
	ds_read_b128 v[156:159], v164 offset:1024
	ds_read_b128 v[160:163], v164 offset:2048
	ds_read_b128 v[172:175], v164 offset:3072
	v_lshl_add_u64 v[164:165], s[6:7], 0, v[134:135]
	s_add_i32 m0, s2, 0xc000
	ds_read_b128 v[176:179], v231
	ds_read_b128 v[180:183], v231 offset:1024
	ds_read_b128 v[184:187], v231 offset:2048
	ds_read_b128 v[188:191], v231 offset:3072
	ds_read_b128 v[192:195], v231 offset:4096
	ds_read_b128 v[196:199], v231 offset:5120
	ds_read_b128 v[200:203], v231 offset:6144
	ds_read_b128 v[204:207], v231 offset:7168
	global_load_lds_dwordx4 v[164:165], off
	v_lshl_add_u64 v[164:165], s[6:7], 0, v[132:133]
	s_add_i32 m0, s2, 0xe000
	s_nop 0
	global_load_lds_dwordx4 v[164:165], off
	s_waitcnt vmcnt(8)
	s_waitcnt lgkmcnt(0)
	s_barrier
	s_waitcnt lgkmcnt(0)
	v_mfma_f32_16x16x32_bf16 v[126:129], v[136:139], v[176:179], 0
	v_mfma_f32_16x16x32_bf16 v[126:129], v[140:143], v[180:183], v[126:129]
	v_mfma_f32_16x16x32_bf16 v[110:113], v[136:139], v[184:187], 0
	v_mfma_f32_16x16x32_bf16 v[110:113], v[140:143], v[188:191], v[110:113]
	v_mfma_f32_16x16x32_bf16 v[94:97], v[136:139], v[192:195], 0
	v_mfma_f32_16x16x32_bf16 v[94:97], v[140:143], v[196:199], v[94:97]
	v_mfma_f32_16x16x32_bf16 v[78:81], v[136:139], v[200:203], 0
	v_mfma_f32_16x16x32_bf16 v[78:81], v[140:143], v[204:207], v[78:81]
	v_mfma_f32_16x16x32_bf16 v[122:125], v[144:147], v[176:179], 0
	v_mfma_f32_16x16x32_bf16 v[122:125], v[148:151], v[180:183], v[122:125]
	v_mfma_f32_16x16x32_bf16 v[106:109], v[144:147], v[184:187], 0
	v_mfma_f32_16x16x32_bf16 v[106:109], v[148:151], v[188:191], v[106:109]
	v_mfma_f32_16x16x32_bf16 v[90:93], v[144:147], v[192:195], 0
	v_mfma_f32_16x16x32_bf16 v[90:93], v[148:151], v[196:199], v[90:93]
	v_mfma_f32_16x16x32_bf16 v[74:77], v[144:147], v[200:203], 0
	v_mfma_f32_16x16x32_bf16 v[74:77], v[148:151], v[204:207], v[74:77]
	v_mfma_f32_16x16x32_bf16 v[118:121], v[152:155], v[176:179], 0
	v_mfma_f32_16x16x32_bf16 v[118:121], v[156:159], v[180:183], v[118:121]
	v_mfma_f32_16x16x32_bf16 v[102:105], v[152:155], v[184:187], 0
	v_mfma_f32_16x16x32_bf16 v[102:105], v[156:159], v[188:191], v[102:105]
	v_mfma_f32_16x16x32_bf16 v[86:89], v[152:155], v[192:195], 0
	v_mfma_f32_16x16x32_bf16 v[86:89], v[156:159], v[196:199], v[86:89]
	v_mfma_f32_16x16x32_bf16 v[70:73], v[152:155], v[200:203], 0
	v_mfma_f32_16x16x32_bf16 v[70:73], v[156:159], v[204:207], v[70:73]
	v_mfma_f32_16x16x32_bf16 v[114:117], v[160:163], v[176:179], 0
	v_mfma_f32_16x16x32_bf16 v[114:117], v[172:175], v[180:183], v[114:117]
	v_mfma_f32_16x16x32_bf16 v[98:101], v[160:163], v[184:187], 0
	v_mfma_f32_16x16x32_bf16 v[98:101], v[172:175], v[188:191], v[98:101]
	v_mfma_f32_16x16x32_bf16 v[82:85], v[160:163], v[192:195], 0
	v_mfma_f32_16x16x32_bf16 v[82:85], v[172:175], v[196:199], v[82:85]
	v_mfma_f32_16x16x32_bf16 v[66:69], v[160:163], v[200:203], 0
	v_mfma_f32_16x16x32_bf16 v[66:69], v[172:175], v[204:207], v[66:69]
	s_barrier
	s_add_i32 s31, s31, s0
	v_lshl_add_u64 v[164:165], s[34:35], 0, v[166:167]
	s_mov_b32 m0, s31
	ds_read_b128 v[176:179], v231 offset:16384
	ds_read_b128 v[180:183], v231 offset:17408
	ds_read_b128 v[184:187], v231 offset:18432
	ds_read_b128 v[188:191], v231 offset:19456
	ds_read_b128 v[192:195], v231 offset:20480
	ds_read_b128 v[196:199], v231 offset:21504
	ds_read_b128 v[200:203], v231 offset:22528
	ds_read_b128 v[204:207], v231 offset:23552
	global_load_lds_dwordx4 v[164:165], off
	s_add_i32 m0, s31, 0x2000
	v_lshl_add_u64 v[168:169], s[34:35], 0, v[130:131]
	s_add_u32 s34, s34, s58
	s_addc_u32 s35, s35, s59
	s_add_i32 s27, s27, s0
	global_load_lds_dwordx4 v[168:169], off
	v_lshl_add_u64 v[170:171], s[34:35], 0, v[166:167]
	s_mov_b32 m0, s27
	v_lshl_add_u64 v[208:209], s[34:35], 0, v[130:131]
	global_load_lds_dwordx4 v[170:171], off
	s_add_i32 m0, s27, 0x2000
	v_lshl_add_u64 v[210:211], s[8:9], 0, v[246:247]
	global_load_lds_dwordx4 v[208:209], off
	s_mov_b32 m0, s2
	v_lshl_add_u64 v[212:213], s[8:9], 0, v[248:249]
	global_load_lds_dwordx4 v[210:211], off
	s_mov_b32 m0, s3
	s_nop 0
	global_load_lds_dwordx4 v[212:213], off
	s_waitcnt vmcnt(8)
	s_waitcnt lgkmcnt(0)
	s_barrier
; #define PG8_STAGE(bufoff, gbase, voff) do { _Pragma("unroll") for (int _i = 0; _i < 2; ++_i) \
;         __builtin_amdgcn_global_load_lds((const unsigned*)((const char*)(gbase) + (voff)[_i]), (PG8_LAS unsigned*)(lds + (bufoff) + ldsw + _i * 8192), 16, 0, 0); } while (0)
; #define PG8_LDA(dst, b, h) do { _Pragma("unroll") for (int m = 0; m < 4; ++m) _Pragma("unroll") for (int k = 0; k < 2; ++k) dst[m][k] = *(const PG8_LAS bf16x8*)(lds + PG8_SA(b, h) + aoff + m * 2048 + k * 1024); } while (0)
; #define PG8_LDB(dst, b, h) do { _Pragma("unroll") for (int n = 0; n < 2; ++n) _Pragma("unroll") for (int k = 0; k < 2; ++k) dst[n][k] = *(const PG8_LAS bf16x8*)(lds + PG8_SB(b, h) + boff + n * 2048 + k * 1024); } while (0)
; #define PG8_MMA(ai, bj, At, Bt) do { __builtin_amdgcn_s_setprio(1); _Pragma("unroll") for (int m = 0; m < 4; ++m) _Pragma("unroll") for (int n = 0; n < 2; ++n) _Pragma("unroll") for (int k = 0; k < 2; ++k) \
;         acc[ai][bj][m][n] = __builtin_amdgcn_mfma_f32_16x16x32_bf16(Bt[n][k], At[m][k], acc[ai][bj][m][n], 0, 0, 0); __builtin_amdgcn_s_setprio(0); } while (0)
; #define PG8_WAIT_V(n) asm volatile("s_waitcnt vmcnt(" #n ")" ::: "memory")
; #define PG8_WAIT_L(n) asm volatile("s_waitcnt lgkmcnt(" #n ")" ::: "memory")
; #define PG8_BAR __builtin_amdgcn_s_barrier()
; #define PG8_SCHED __builtin_amdgcn_sched_barrier(0)
;     ...
;             PG8_WAIT_V(8); PG8_WAIT_L(0); PG8_BAR; PG8_MMA(1, 0, At, B0); PG8_MMA(1, 1, At, B1); PG8_BAR; PG8_SCHED;
;             PG8_LDB(B0, 1, 0); PG8_LDB(B1, 1, 1); PG8_SCHED; PG8_LDA(At, 1, 0); PG8_STAGE(PG8_SA(0, 1), a2 + hstepA, voffA);
;             PG8_WAIT_V(8); PG8_WAIT_L(0); PG8_BAR; PG8_MMA(0, 0, At, B0); PG8_MMA(0, 1, At, B1); PG8_BAR; PG8_SCHED;
	s_waitcnt lgkmcnt(0)
	v_mfma_f32_16x16x32_bf16 v[62:65], v[136:139], v[176:179], 0
	v_mfma_f32_16x16x32_bf16 v[62:65], v[140:143], v[180:183], v[62:65]
	v_mfma_f32_16x16x32_bf16 v[46:49], v[136:139], v[184:187], 0
	v_mfma_f32_16x16x32_bf16 v[46:49], v[140:143], v[188:191], v[46:49]
	v_mfma_f32_16x16x32_bf16 v[30:33], v[136:139], v[192:195], 0
	v_mfma_f32_16x16x32_bf16 v[30:33], v[140:143], v[196:199], v[30:33]
	v_mfma_f32_16x16x32_bf16 v[14:17], v[136:139], v[200:203], 0
	v_mfma_f32_16x16x32_bf16 v[14:17], v[140:143], v[204:207], v[14:17]
	v_mfma_f32_16x16x32_bf16 v[58:61], v[144:147], v[176:179], 0
	v_mfma_f32_16x16x32_bf16 v[58:61], v[148:151], v[180:183], v[58:61]
	v_mfma_f32_16x16x32_bf16 v[42:45], v[144:147], v[184:187], 0
	v_mfma_f32_16x16x32_bf16 v[42:45], v[148:151], v[188:191], v[42:45]
	v_mfma_f32_16x16x32_bf16 v[26:29], v[144:147], v[192:195], 0
	v_mfma_f32_16x16x32_bf16 v[26:29], v[148:151], v[196:199], v[26:29]
	v_mfma_f32_16x16x32_bf16 v[10:13], v[144:147], v[200:203], 0
	v_mfma_f32_16x16x32_bf16 v[10:13], v[148:151], v[204:207], v[10:13]
	v_mfma_f32_16x16x32_bf16 v[54:57], v[152:155], v[176:179], 0
	v_mfma_f32_16x16x32_bf16 v[54:57], v[156:159], v[180:183], v[54:57]
	v_mfma_f32_16x16x32_bf16 v[38:41], v[152:155], v[184:187], 0
	v_mfma_f32_16x16x32_bf16 v[38:41], v[156:159], v[188:191], v[38:41]
	v_mfma_f32_16x16x32_bf16 v[22:25], v[152:155], v[192:195], 0
	v_mfma_f32_16x16x32_bf16 v[22:25], v[156:159], v[196:199], v[22:25]
	v_mfma_f32_16x16x32_bf16 v[6:9], v[152:155], v[200:203], 0
	v_mfma_f32_16x16x32_bf16 v[6:9], v[156:159], v[204:207], v[6:9]
	v_mfma_f32_16x16x32_bf16 v[50:53], v[160:163], v[176:179], 0
	v_mfma_f32_16x16x32_bf16 v[50:53], v[172:175], v[180:183], v[50:53]
	v_mfma_f32_16x16x32_bf16 v[34:37], v[160:163], v[184:187], 0
	v_mfma_f32_16x16x32_bf16 v[34:37], v[172:175], v[188:191], v[34:37]
	v_mfma_f32_16x16x32_bf16 v[18:21], v[160:163], v[192:195], 0
	v_mfma_f32_16x16x32_bf16 v[18:21], v[172:175], v[196:199], v[18:21]
	v_mfma_f32_16x16x32_bf16 v[2:5], v[160:163], v[200:203], 0
	v_mfma_f32_16x16x32_bf16 v[2:5], v[172:175], v[204:207], v[2:5]
	s_barrier
	s_add_i32 s27, 0, 0x18000
	s_add_i32 s31, 0, 0x1c000
	v_add_u32_e32 v148, s27, v229
	v_add_u32_e32 v172, s31, v229
	ds_read_b128 v[136:139], v148
	ds_read_b128 v[140:143], v148 offset:1024
	ds_read_b128 v[144:147], v148 offset:2048
	ds_read_b128 v[148:151], v148 offset:3072
	ds_read_b128 v[152:155], v172
	ds_read_b128 v[156:159], v172 offset:1024
	ds_read_b128 v[160:163], v172 offset:2048
	ds_read_b128 v[172:175], v172 offset:3072
	s_add_u32 s8, s8, 0x800
	s_addc_u32 s9, s9, 0
	s_mov_b32 m0, s14
	v_lshl_add_u64 v[214:215], s[8:9], 0, v[246:247]
	ds_read_b128 v[176:179], v231 offset:32768
	ds_read_b128 v[180:183], v231 offset:33792
	ds_read_b128 v[184:187], v231 offset:34816
	ds_read_b128 v[188:191], v231 offset:35840
	ds_read_b128 v[192:195], v231 offset:36864
	ds_read_b128 v[196:199], v231 offset:37888
	ds_read_b128 v[200:203], v231 offset:38912
	ds_read_b128 v[204:207], v231 offset:39936
	global_load_lds_dwordx4 v[214:215], off
	v_lshl_add_u64 v[214:215], s[8:9], 0, v[248:249]
	s_mov_b32 m0, s15
	s_nop 0
	global_load_lds_dwordx4 v[214:215], off
	s_waitcnt vmcnt(8)
	s_waitcnt lgkmcnt(0)
	s_barrier
	s_waitcnt lgkmcnt(0)
	v_mfma_f32_16x16x32_bf16 v[126:129], v[136:139], v[176:179], v[126:129]
	v_mfma_f32_16x16x32_bf16 v[126:129], v[140:143], v[180:183], v[126:129]
	v_mfma_f32_16x16x32_bf16 v[110:113], v[136:139], v[184:187], v[110:113]
	v_mfma_f32_16x16x32_bf16 v[110:113], v[140:143], v[188:191], v[110:113]
	v_mfma_f32_16x16x32_bf16 v[94:97], v[136:139], v[192:195], v[94:97]
	v_mfma_f32_16x16x32_bf16 v[94:97], v[140:143], v[196:199], v[94:97]
	v_mfma_f32_16x16x32_bf16 v[78:81], v[136:139], v[200:203], v[78:81]
	v_mfma_f32_16x16x32_bf16 v[78:81], v[140:143], v[204:207], v[78:81]
	v_mfma_f32_16x16x32_bf16 v[122:125], v[144:147], v[176:179], v[122:125]
	v_mfma_f32_16x16x32_bf16 v[122:125], v[148:151], v[180:183], v[122:125]
	v_mfma_f32_16x16x32_bf16 v[106:109], v[144:147], v[184:187], v[106:109]
	v_mfma_f32_16x16x32_bf16 v[106:109], v[148:151], v[188:191], v[106:109]
	v_mfma_f32_16x16x32_bf16 v[90:93], v[144:147], v[192:195], v[90:93]
	v_mfma_f32_16x16x32_bf16 v[90:93], v[148:151], v[196:199], v[90:93]
	v_mfma_f32_16x16x32_bf16 v[74:77], v[144:147], v[200:203], v[74:77]
	v_mfma_f32_16x16x32_bf16 v[74:77], v[148:151], v[204:207], v[74:77]
	v_mfma_f32_16x16x32_bf16 v[118:121], v[152:155], v[176:179], v[118:121]
	v_mfma_f32_16x16x32_bf16 v[118:121], v[156:159], v[180:183], v[118:121]
	v_mfma_f32_16x16x32_bf16 v[102:105], v[152:155], v[184:187], v[102:105]
	v_mfma_f32_16x16x32_bf16 v[102:105], v[156:159], v[188:191], v[102:105]
	v_mfma_f32_16x16x32_bf16 v[86:89], v[152:155], v[192:195], v[86:89]
	v_mfma_f32_16x16x32_bf16 v[86:89], v[156:159], v[196:199], v[86:89]
	v_mfma_f32_16x16x32_bf16 v[70:73], v[152:155], v[200:203], v[70:73]
	v_mfma_f32_16x16x32_bf16 v[70:73], v[156:159], v[204:207], v[70:73]
	v_mfma_f32_16x16x32_bf16 v[114:117], v[160:163], v[176:179], v[114:117]
	v_mfma_f32_16x16x32_bf16 v[114:117], v[172:175], v[180:183], v[114:117]
	v_mfma_f32_16x16x32_bf16 v[98:101], v[160:163], v[184:187], v[98:101]
	v_mfma_f32_16x16x32_bf16 v[98:101], v[172:175], v[188:191], v[98:101]
	v_mfma_f32_16x16x32_bf16 v[82:85], v[160:163], v[192:195], v[82:85]
	v_mfma_f32_16x16x32_bf16 v[82:85], v[172:175], v[196:199], v[82:85]
	v_mfma_f32_16x16x32_bf16 v[66:69], v[160:163], v[200:203], v[66:69]
	v_mfma_f32_16x16x32_bf16 v[66:69], v[172:175], v[204:207], v[66:69]
	s_barrier
; #define PG8_STAGE(bufoff, gbase, voff) do { _Pragma("unroll") for (int _i = 0; _i < 2; ++_i) \
;         __builtin_amdgcn_global_load_lds((const unsigned*)((const char*)(gbase) + (voff)[_i]), (PG8_LAS unsigned*)(lds + (bufoff) + ldsw + _i * 8192), 16, 0, 0); } while (0)
; #define PG8_LDA(dst, b, h) do { _Pragma("unroll") for (int m = 0; m < 4; ++m) _Pragma("unroll") for (int k = 0; k < 2; ++k) dst[m][k] = *(const PG8_LAS bf16x8*)(lds + PG8_SA(b, h) + aoff + m * 2048 + k * 1024); } while (0)
; #define PG8_LDB(dst, b, h) do { _Pragma("unroll") for (int n = 0; n < 2; ++n) _Pragma("unroll") for (int k = 0; k < 2; ++k) dst[n][k] = *(const PG8_LAS bf16x8*)(lds + PG8_SB(b, h) + boff + n * 2048 + k * 1024); } while (0)
; #define PG8_MMA(ai, bj, At, Bt) do { __builtin_amdgcn_s_setprio(1); _Pragma("unroll") for (int m = 0; m < 4; ++m) _Pragma("unroll") for (int n = 0; n < 2; ++n) _Pragma("unroll") for (int k = 0; k < 2; ++k) \
;         acc[ai][bj][m][n] = __builtin_amdgcn_mfma_f32_16x16x32_bf16(Bt[n][k], At[m][k], acc[ai][bj][m][n], 0, 0, 0); __builtin_amdgcn_s_setprio(0); } while (0)
; #define PG8_WAIT_V(n) asm volatile("s_waitcnt vmcnt(" #n ")" ::: "memory")
; #define PG8_WAIT_L(n) asm volatile("s_waitcnt lgkmcnt(" #n ")" ::: "memory")
; #define PG8_BAR __builtin_amdgcn_s_barrier()
; #define PG8_SCHED __builtin_amdgcn_sched_barrier(0)
;     ...
;         for (int t = 0; t < nt; t += 2) {
;             const bool last = (t == nt - 2);
;             const char* a1 = cA + (size_t)(t + 1) * kstep;
;             const char* a2 = last ? nA : cA + (size_t)(t + 2) * kstep; const char* b2 = last ? nB : cB + (size_t)(t + 2) * kstep;
;             const char* a3 = a2 + kstep; const char* b3 = b2 + kstep;
;             if (last && has_next) S.a_ready(nxt);
;             if constexpr (SP2) {
;             PG8_LDB(B0, 0, 0); PG8_LDB(B1, 0, 1); PG8_SCHED; PG8_LDA(At, 0, 0); PG8_STAGE(PG8_SA(1, 1), a1 + hstepA, voffA);
;     ...
;             PG8_LDA(At, 1, 1); PG8_STAGE(PG8_SB(1, 0), b3, voffB); PG8_STAGE(PG8_SB(1, 1), b3 + hstepB, voffB); PG8_STAGE(PG8_SA(1, 0), a3, voffA);
;             PG8_WAIT_V(8); PG8_WAIT_L(0); PG8_BAR; PG8_MMA(1, 0, At, B0); PG8_MMA(1, 1, At, B1); PG8_BAR; PG8_SCHED;
	s_add_i32 s8, s27, s0
	v_lshl_add_u64 v[164:165], v[164:165], 0, s[62:63]
	s_mov_b32 m0, s8
	ds_read_b128 v[176:179], v231 offset:49152
	ds_read_b128 v[180:183], v231 offset:50176
	ds_read_b128 v[184:187], v231 offset:51200
	ds_read_b128 v[188:191], v231 offset:52224
	ds_read_b128 v[192:195], v231 offset:53248
	ds_read_b128 v[196:199], v231 offset:54272
	ds_read_b128 v[200:203], v231 offset:55296
	ds_read_b128 v[204:207], v231 offset:56320
	global_load_lds_dwordx4 v[164:165], off
	v_lshl_add_u64 v[164:165], v[168:169], 0, s[62:63]
	s_add_i32 m0, s8, 0x2000
	s_add_i32 s8, s31, s0
	global_load_lds_dwordx4 v[164:165], off
	v_lshl_add_u64 v[164:165], v[170:171], 0, s[62:63]
	s_mov_b32 m0, s8
	s_nop 0
	global_load_lds_dwordx4 v[164:165], off
	v_lshl_add_u64 v[164:165], v[208:209], 0, s[62:63]
	s_add_i32 m0, s8, 0x2000
	s_nop 0
	global_load_lds_dwordx4 v[164:165], off
	v_lshl_add_u64 v[164:165], v[210:211], 0, v[244:245]
	s_mov_b32 m0, s17
	s_nop 0
	global_load_lds_dwordx4 v[164:165], off
	v_lshl_add_u64 v[164:165], v[212:213], 0, v[244:245]
	s_mov_b32 m0, s18
	s_nop 0
	global_load_lds_dwordx4 v[164:165], off
	s_waitcnt vmcnt(8)
	s_waitcnt lgkmcnt(0)
	s_barrier
	s_waitcnt lgkmcnt(0)
	v_mfma_f32_16x16x32_bf16 v[62:65], v[136:139], v[176:179], v[62:65]
	v_mfma_f32_16x16x32_bf16 v[62:65], v[140:143], v[180:183], v[62:65]
	v_mfma_f32_16x16x32_bf16 v[46:49], v[136:139], v[184:187], v[46:49]
	v_mfma_f32_16x16x32_bf16 v[46:49], v[140:143], v[188:191], v[46:49]
	v_mfma_f32_16x16x32_bf16 v[30:33], v[136:139], v[192:195], v[30:33]
	v_mfma_f32_16x16x32_bf16 v[30:33], v[140:143], v[196:199], v[30:33]
	v_mfma_f32_16x16x32_bf16 v[14:17], v[136:139], v[200:203], v[14:17]
	v_mfma_f32_16x16x32_bf16 v[14:17], v[140:143], v[204:207], v[14:17]
	v_mfma_f32_16x16x32_bf16 v[58:61], v[144:147], v[176:179], v[58:61]
	v_mfma_f32_16x16x32_bf16 v[58:61], v[148:151], v[180:183], v[58:61]
	v_mfma_f32_16x16x32_bf16 v[42:45], v[144:147], v[184:187], v[42:45]
	v_mfma_f32_16x16x32_bf16 v[42:45], v[148:151], v[188:191], v[42:45]
	v_mfma_f32_16x16x32_bf16 v[26:29], v[144:147], v[192:195], v[26:29]
	v_mfma_f32_16x16x32_bf16 v[26:29], v[148:151], v[196:199], v[26:29]
	v_mfma_f32_16x16x32_bf16 v[10:13], v[144:147], v[200:203], v[10:13]
	v_mfma_f32_16x16x32_bf16 v[10:13], v[148:151], v[204:207], v[10:13]
	v_mfma_f32_16x16x32_bf16 v[54:57], v[152:155], v[176:179], v[54:57]
	v_mfma_f32_16x16x32_bf16 v[54:57], v[156:159], v[180:183], v[54:57]
	v_mfma_f32_16x16x32_bf16 v[38:41], v[152:155], v[184:187], v[38:41]
	v_mfma_f32_16x16x32_bf16 v[38:41], v[156:159], v[188:191], v[38:41]
	v_mfma_f32_16x16x32_bf16 v[22:25], v[152:155], v[192:195], v[22:25]
	v_mfma_f32_16x16x32_bf16 v[22:25], v[156:159], v[196:199], v[22:25]
	v_mfma_f32_16x16x32_bf16 v[6:9], v[152:155], v[200:203], v[6:9]
	v_mfma_f32_16x16x32_bf16 v[6:9], v[156:159], v[204:207], v[6:9]
	v_mfma_f32_16x16x32_bf16 v[50:53], v[160:163], v[176:179], v[50:53]
	v_mfma_f32_16x16x32_bf16 v[50:53], v[172:175], v[180:183], v[50:53]
	v_mfma_f32_16x16x32_bf16 v[34:37], v[160:163], v[184:187], v[34:37]
	v_mfma_f32_16x16x32_bf16 v[34:37], v[172:175], v[188:191], v[34:37]
	v_mfma_f32_16x16x32_bf16 v[18:21], v[160:163], v[192:195], v[18:21]
	v_mfma_f32_16x16x32_bf16 v[18:21], v[172:175], v[196:199], v[18:21]
	v_mfma_f32_16x16x32_bf16 v[2:5], v[160:163], v[200:203], v[2:5]
	v_mfma_f32_16x16x32_bf16 v[2:5], v[172:175], v[204:207], v[2:5]
	s_barrier
	s_add_u32 s10, s10, 0x100
	s_addc_u32 s11, s11, 0
	s_add_u32 s6, s6, 0x400000
	s_addc_u32 s7, s7, 0
	s_cmp_ge_i32 s25, s13
	s_mov_b32 s8, s25
	s_cbranch_scc1 .LBB0_753
.LBB0_752:
	s_add_i32 s25, s8, 2
	s_add_u32 s27, s6, 0x200000
	s_addc_u32 s9, s7, 0
	s_add_i32 s31, 0, 0x10000
	s_cmp_eq_u32 s19, s8
	s_cselect_b32 s9, s43, s9
	s_cselect_b32 s8, s42, s27
	s_cselect_b32 s35, s91, s11
	s_cselect_b32 s34, s90, s10
	s_add_i32 s27, 0, 0x14000
	v_add_u32_e32 v148, s31, v229
	v_add_u32_e32 v164, s27, v229
	ds_read_b128 v[136:139], v148
	ds_read_b128 v[140:143], v148 offset:1024
	ds_read_b128 v[144:147], v148 offset:2048
	ds_read_b128 v[148:151], v148 offset:3072
	ds_read_b128 v[152:155], v164
	ds_read_b128 v[156:159], v164 offset:1024
	ds_read_b128 v[160:163], v164 offset:2048
	ds_read_b128 v[172:175], v164 offset:3072
	v_lshl_add_u64 v[164:165], s[6:7], 0, v[134:135]
	s_add_i32 m0, s2, 0xc000
	ds_read_b128 v[176:179], v231
	ds_read_b128 v[180:183], v231 offset:1024
	ds_read_b128 v[184:187], v231 offset:2048
	ds_read_b128 v[188:191], v231 offset:3072
	ds_read_b128 v[192:195], v231 offset:4096
	ds_read_b128 v[196:199], v231 offset:5120
	ds_read_b128 v[200:203], v231 offset:6144
	ds_read_b128 v[204:207], v231 offset:7168
	global_load_lds_dwordx4 v[164:165], off
	v_lshl_add_u64 v[164:165], s[6:7], 0, v[132:133]
	s_add_i32 m0, s2, 0xe000
	s_nop 0
	global_load_lds_dwordx4 v[164:165], off
	s_waitcnt vmcnt(8)
	s_waitcnt lgkmcnt(0)
	s_barrier
; #define PG8_STAGE(bufoff, gbase, voff) do { _Pragma("unroll") for (int _i = 0; _i < 2; ++_i) \
;         __builtin_amdgcn_global_load_lds((const unsigned*)((const char*)(gbase) + (voff)[_i]), (PG8_LAS unsigned*)(lds + (bufoff) + ldsw + _i * 8192), 16, 0, 0); } while (0)
; #define PG8_LDA(dst, b, h) do { _Pragma("unroll") for (int m = 0; m < 4; ++m) _Pragma("unroll") for (int k = 0; k < 2; ++k) dst[m][k] = *(const PG8_LAS bf16x8*)(lds + PG8_SA(b, h) + aoff + m * 2048 + k * 1024); } while (0)
; #define PG8_MMA(ai, bj, At, Bt) do { __builtin_amdgcn_s_setprio(1); _Pragma("unroll") for (int m = 0; m < 4; ++m) _Pragma("unroll") for (int n = 0; n < 2; ++n) _Pragma("unroll") for (int k = 0; k < 2; ++k) \
;         acc[ai][bj][m][n] = __builtin_amdgcn_mfma_f32_16x16x32_bf16(Bt[n][k], At[m][k], acc[ai][bj][m][n], 0, 0, 0); __builtin_amdgcn_s_setprio(0); } while (0)
; #define PG8_WAIT_V(n) asm volatile("s_waitcnt vmcnt(" #n ")" ::: "memory")
; #define PG8_WAIT_L(n) asm volatile("s_waitcnt lgkmcnt(" #n ")" ::: "memory")
; #define PG8_BAR __builtin_amdgcn_s_barrier()
; #define PG8_SCHED __builtin_amdgcn_sched_barrier(0)
;     ...
;             PG8_WAIT_V(8); PG8_WAIT_L(0); PG8_BAR; PG8_MMA(0, 0, At, B0); PG8_MMA(0, 1, At, B1); PG8_BAR; PG8_SCHED;
;             PG8_LDA(At, 0, 1); PG8_STAGE(PG8_SB(0, 0), b2, voffB); PG8_STAGE(PG8_SB(0, 1), b2 + hstepB, voffB); PG8_STAGE(PG8_SA(0, 0), a2, voffA);
;             PG8_WAIT_V(8); PG8_WAIT_L(0); PG8_BAR; PG8_MMA(1, 0, At, B0); PG8_MMA(1, 1, At, B1); PG8_BAR; PG8_SCHED;
	s_waitcnt lgkmcnt(0)
	v_mfma_f32_16x16x32_bf16 v[126:129], v[136:139], v[176:179], v[126:129]
	v_mfma_f32_16x16x32_bf16 v[126:129], v[140:143], v[180:183], v[126:129]
	v_mfma_f32_16x16x32_bf16 v[110:113], v[136:139], v[184:187], v[110:113]
	v_mfma_f32_16x16x32_bf16 v[110:113], v[140:143], v[188:191], v[110:113]
	v_mfma_f32_16x16x32_bf16 v[94:97], v[136:139], v[192:195], v[94:97]
	v_mfma_f32_16x16x32_bf16 v[94:97], v[140:143], v[196:199], v[94:97]
	v_mfma_f32_16x16x32_bf16 v[78:81], v[136:139], v[200:203], v[78:81]
	v_mfma_f32_16x16x32_bf16 v[78:81], v[140:143], v[204:207], v[78:81]
	v_mfma_f32_16x16x32_bf16 v[122:125], v[144:147], v[176:179], v[122:125]
	v_mfma_f32_16x16x32_bf16 v[122:125], v[148:151], v[180:183], v[122:125]
	v_mfma_f32_16x16x32_bf16 v[106:109], v[144:147], v[184:187], v[106:109]
	v_mfma_f32_16x16x32_bf16 v[106:109], v[148:151], v[188:191], v[106:109]
	v_mfma_f32_16x16x32_bf16 v[90:93], v[144:147], v[192:195], v[90:93]
	v_mfma_f32_16x16x32_bf16 v[90:93], v[148:151], v[196:199], v[90:93]
	v_mfma_f32_16x16x32_bf16 v[74:77], v[144:147], v[200:203], v[74:77]
	v_mfma_f32_16x16x32_bf16 v[74:77], v[148:151], v[204:207], v[74:77]
	v_mfma_f32_16x16x32_bf16 v[118:121], v[152:155], v[176:179], v[118:121]
	v_mfma_f32_16x16x32_bf16 v[118:121], v[156:159], v[180:183], v[118:121]
	v_mfma_f32_16x16x32_bf16 v[102:105], v[152:155], v[184:187], v[102:105]
	v_mfma_f32_16x16x32_bf16 v[102:105], v[156:159], v[188:191], v[102:105]
	v_mfma_f32_16x16x32_bf16 v[86:89], v[152:155], v[192:195], v[86:89]
	v_mfma_f32_16x16x32_bf16 v[86:89], v[156:159], v[196:199], v[86:89]
	v_mfma_f32_16x16x32_bf16 v[70:73], v[152:155], v[200:203], v[70:73]
	v_mfma_f32_16x16x32_bf16 v[70:73], v[156:159], v[204:207], v[70:73]
	v_mfma_f32_16x16x32_bf16 v[114:117], v[160:163], v[176:179], v[114:117]
	v_mfma_f32_16x16x32_bf16 v[114:117], v[172:175], v[180:183], v[114:117]
	v_mfma_f32_16x16x32_bf16 v[98:101], v[160:163], v[184:187], v[98:101]
	v_mfma_f32_16x16x32_bf16 v[98:101], v[172:175], v[188:191], v[98:101]
	v_mfma_f32_16x16x32_bf16 v[82:85], v[160:163], v[192:195], v[82:85]
	v_mfma_f32_16x16x32_bf16 v[82:85], v[172:175], v[196:199], v[82:85]
	v_mfma_f32_16x16x32_bf16 v[66:69], v[160:163], v[200:203], v[66:69]
	v_mfma_f32_16x16x32_bf16 v[66:69], v[172:175], v[204:207], v[66:69]
	s_barrier
	s_add_i32 s31, s31, s0
	v_lshl_add_u64 v[164:165], s[34:35], 0, v[166:167]
	s_mov_b32 m0, s31
	ds_read_b128 v[176:179], v231 offset:16384
	ds_read_b128 v[180:183], v231 offset:17408
	ds_read_b128 v[184:187], v231 offset:18432
	ds_read_b128 v[188:191], v231 offset:19456
	ds_read_b128 v[192:195], v231 offset:20480
	ds_read_b128 v[196:199], v231 offset:21504
	ds_read_b128 v[200:203], v231 offset:22528
	ds_read_b128 v[204:207], v231 offset:23552
	global_load_lds_dwordx4 v[164:165], off
	s_add_i32 m0, s31, 0x2000
	v_lshl_add_u64 v[168:169], s[34:35], 0, v[130:131]
	s_add_u32 s34, s34, s58
	s_addc_u32 s35, s35, s59
	s_add_i32 s27, s27, s0
	global_load_lds_dwordx4 v[168:169], off
	v_lshl_add_u64 v[170:171], s[34:35], 0, v[166:167]
	s_mov_b32 m0, s27
	v_lshl_add_u64 v[208:209], s[34:35], 0, v[130:131]
	global_load_lds_dwordx4 v[170:171], off
	s_add_i32 m0, s27, 0x2000
	v_lshl_add_u64 v[210:211], s[8:9], 0, v[246:247]
	global_load_lds_dwordx4 v[208:209], off
	s_mov_b32 m0, s2
	v_lshl_add_u64 v[212:213], s[8:9], 0, v[248:249]
	global_load_lds_dwordx4 v[210:211], off
	s_mov_b32 m0, s3
	s_nop 0
	global_load_lds_dwordx4 v[212:213], off
	s_waitcnt vmcnt(8)
	s_waitcnt lgkmcnt(0)
	s_barrier
	s_waitcnt lgkmcnt(0)
	v_mfma_f32_16x16x32_bf16 v[62:65], v[136:139], v[176:179], v[62:65]
	v_mfma_f32_16x16x32_bf16 v[62:65], v[140:143], v[180:183], v[62:65]
	v_mfma_f32_16x16x32_bf16 v[46:49], v[136:139], v[184:187], v[46:49]
	v_mfma_f32_16x16x32_bf16 v[46:49], v[140:143], v[188:191], v[46:49]
	v_mfma_f32_16x16x32_bf16 v[30:33], v[136:139], v[192:195], v[30:33]
	v_mfma_f32_16x16x32_bf16 v[30:33], v[140:143], v[196:199], v[30:33]
	v_mfma_f32_16x16x32_bf16 v[14:17], v[136:139], v[200:203], v[14:17]
	v_mfma_f32_16x16x32_bf16 v[14:17], v[140:143], v[204:207], v[14:17]
	v_mfma_f32_16x16x32_bf16 v[58:61], v[144:147], v[176:179], v[58:61]
	v_mfma_f32_16x16x32_bf16 v[58:61], v[148:151], v[180:183], v[58:61]
	v_mfma_f32_16x16x32_bf16 v[42:45], v[144:147], v[184:187], v[42:45]
	v_mfma_f32_16x16x32_bf16 v[42:45], v[148:151], v[188:191], v[42:45]
	v_mfma_f32_16x16x32_bf16 v[26:29], v[144:147], v[192:195], v[26:29]
	v_mfma_f32_16x16x32_bf16 v[26:29], v[148:151], v[196:199], v[26:29]
	v_mfma_f32_16x16x32_bf16 v[10:13], v[144:147], v[200:203], v[10:13]
	v_mfma_f32_16x16x32_bf16 v[10:13], v[148:151], v[204:207], v[10:13]
	v_mfma_f32_16x16x32_bf16 v[54:57], v[152:155], v[176:179], v[54:57]
	v_mfma_f32_16x16x32_bf16 v[54:57], v[156:159], v[180:183], v[54:57]
	v_mfma_f32_16x16x32_bf16 v[38:41], v[152:155], v[184:187], v[38:41]
	v_mfma_f32_16x16x32_bf16 v[38:41], v[156:159], v[188:191], v[38:41]
	v_mfma_f32_16x16x32_bf16 v[22:25], v[152:155], v[192:195], v[22:25]
	v_mfma_f32_16x16x32_bf16 v[22:25], v[156:159], v[196:199], v[22:25]
	v_mfma_f32_16x16x32_bf16 v[6:9], v[152:155], v[200:203], v[6:9]
	v_mfma_f32_16x16x32_bf16 v[6:9], v[156:159], v[204:207], v[6:9]
	v_mfma_f32_16x16x32_bf16 v[50:53], v[160:163], v[176:179], v[50:53]
	v_mfma_f32_16x16x32_bf16 v[50:53], v[172:175], v[180:183], v[50:53]
	v_mfma_f32_16x16x32_bf16 v[34:37], v[160:163], v[184:187], v[34:37]
	v_mfma_f32_16x16x32_bf16 v[34:37], v[172:175], v[188:191], v[34:37]
	v_mfma_f32_16x16x32_bf16 v[18:21], v[160:163], v[192:195], v[18:21]
	v_mfma_f32_16x16x32_bf16 v[18:21], v[172:175], v[196:199], v[18:21]
	v_mfma_f32_16x16x32_bf16 v[2:5], v[160:163], v[200:203], v[2:5]
	v_mfma_f32_16x16x32_bf16 v[2:5], v[172:175], v[204:207], v[2:5]
	s_barrier
; #define PG8_STAGE(bufoff, gbase, voff) do { _Pragma("unroll") for (int _i = 0; _i < 2; ++_i) \
;         __builtin_amdgcn_global_load_lds((const unsigned*)((const char*)(gbase) + (voff)[_i]), (PG8_LAS unsigned*)(lds + (bufoff) + ldsw + _i * 8192), 16, 0, 0); } while (0)
; #define PG8_LDA(dst, b, h) do { _Pragma("unroll") for (int m = 0; m < 4; ++m) _Pragma("unroll") for (int k = 0; k < 2; ++k) dst[m][k] = *(const PG8_LAS bf16x8*)(lds + PG8_SA(b, h) + aoff + m * 2048 + k * 1024); } while (0)
; #define PG8_LDB(dst, b, h) do { _Pragma("unroll") for (int n = 0; n < 2; ++n) _Pragma("unroll") for (int k = 0; k < 2; ++k) dst[n][k] = *(const PG8_LAS bf16x8*)(lds + PG8_SB(b, h) + boff + n * 2048 + k * 1024); } while (0)
; #define PG8_MMA(ai, bj, At, Bt) do { __builtin_amdgcn_s_setprio(1); _Pragma("unroll") for (int m = 0; m < 4; ++m) _Pragma("unroll") for (int n = 0; n < 2; ++n) _Pragma("unroll") for (int k = 0; k < 2; ++k) \
;         acc[ai][bj][m][n] = __builtin_amdgcn_mfma_f32_16x16x32_bf16(Bt[n][k], At[m][k], acc[ai][bj][m][n], 0, 0, 0); __builtin_amdgcn_s_setprio(0); } while (0)
; #define PG8_WAIT_V(n) asm volatile("s_waitcnt vmcnt(" #n ")" ::: "memory")
; #define PG8_WAIT_L(n) asm volatile("s_waitcnt lgkmcnt(" #n ")" ::: "memory")
; #define PG8_BAR __builtin_amdgcn_s_barrier()
; #define PG8_SCHED __builtin_amdgcn_sched_barrier(0)
;     ...
;             PG8_LDB(B0, 1, 0); PG8_LDB(B1, 1, 1); PG8_SCHED; PG8_LDA(At, 1, 0); PG8_STAGE(PG8_SA(0, 1), a2 + hstepA, voffA);
;             PG8_WAIT_V(8); PG8_WAIT_L(0); PG8_BAR; PG8_MMA(0, 0, At, B0); PG8_MMA(0, 1, At, B1); PG8_BAR; PG8_SCHED;
;             PG8_LDA(At, 1, 1); PG8_STAGE(PG8_SB(1, 0), b3, voffB); PG8_STAGE(PG8_SB(1, 1), b3 + hstepB, voffB); PG8_STAGE(PG8_SA(1, 0), a3, voffA);
;             PG8_WAIT_V(8); PG8_WAIT_L(0); PG8_BAR; PG8_MMA(1, 0, At, B0); PG8_MMA(1, 1, At, B1); PG8_BAR; PG8_SCHED;
	s_add_i32 s27, 0, 0x18000
	s_add_i32 s31, 0, 0x1c000
	v_add_u32_e32 v148, s27, v229
	v_add_u32_e32 v172, s31, v229
	ds_read_b128 v[136:139], v148
	ds_read_b128 v[140:143], v148 offset:1024
	ds_read_b128 v[144:147], v148 offset:2048
	ds_read_b128 v[148:151], v148 offset:3072
	ds_read_b128 v[152:155], v172
	ds_read_b128 v[156:159], v172 offset:1024
	ds_read_b128 v[160:163], v172 offset:2048
	ds_read_b128 v[172:175], v172 offset:3072
	s_add_u32 s8, s8, 0x800
	s_addc_u32 s9, s9, 0
	s_mov_b32 m0, s14
	v_lshl_add_u64 v[214:215], s[8:9], 0, v[246:247]
	ds_read_b128 v[176:179], v231 offset:32768
	ds_read_b128 v[180:183], v231 offset:33792
	ds_read_b128 v[184:187], v231 offset:34816
	ds_read_b128 v[188:191], v231 offset:35840
	ds_read_b128 v[192:195], v231 offset:36864
	ds_read_b128 v[196:199], v231 offset:37888
	ds_read_b128 v[200:203], v231 offset:38912
	ds_read_b128 v[204:207], v231 offset:39936
	global_load_lds_dwordx4 v[214:215], off
	v_lshl_add_u64 v[214:215], s[8:9], 0, v[248:249]
	s_mov_b32 m0, s15
	s_nop 0
	global_load_lds_dwordx4 v[214:215], off
	s_waitcnt vmcnt(8)
	s_waitcnt lgkmcnt(0)
	s_barrier
	s_waitcnt lgkmcnt(0)
	v_mfma_f32_16x16x32_bf16 v[126:129], v[136:139], v[176:179], v[126:129]
	v_mfma_f32_16x16x32_bf16 v[126:129], v[140:143], v[180:183], v[126:129]
	v_mfma_f32_16x16x32_bf16 v[110:113], v[136:139], v[184:187], v[110:113]
	v_mfma_f32_16x16x32_bf16 v[110:113], v[140:143], v[188:191], v[110:113]
	v_mfma_f32_16x16x32_bf16 v[94:97], v[136:139], v[192:195], v[94:97]
	v_mfma_f32_16x16x32_bf16 v[94:97], v[140:143], v[196:199], v[94:97]
	v_mfma_f32_16x16x32_bf16 v[78:81], v[136:139], v[200:203], v[78:81]
	v_mfma_f32_16x16x32_bf16 v[78:81], v[140:143], v[204:207], v[78:81]
	v_mfma_f32_16x16x32_bf16 v[122:125], v[144:147], v[176:179], v[122:125]
	v_mfma_f32_16x16x32_bf16 v[122:125], v[148:151], v[180:183], v[122:125]
	v_mfma_f32_16x16x32_bf16 v[106:109], v[144:147], v[184:187], v[106:109]
	v_mfma_f32_16x16x32_bf16 v[106:109], v[148:151], v[188:191], v[106:109]
	v_mfma_f32_16x16x32_bf16 v[90:93], v[144:147], v[192:195], v[90:93]
	v_mfma_f32_16x16x32_bf16 v[90:93], v[148:151], v[196:199], v[90:93]
	v_mfma_f32_16x16x32_bf16 v[74:77], v[144:147], v[200:203], v[74:77]
	v_mfma_f32_16x16x32_bf16 v[74:77], v[148:151], v[204:207], v[74:77]
	v_mfma_f32_16x16x32_bf16 v[118:121], v[152:155], v[176:179], v[118:121]
	v_mfma_f32_16x16x32_bf16 v[118:121], v[156:159], v[180:183], v[118:121]
	v_mfma_f32_16x16x32_bf16 v[102:105], v[152:155], v[184:187], v[102:105]
	v_mfma_f32_16x16x32_bf16 v[102:105], v[156:159], v[188:191], v[102:105]
	v_mfma_f32_16x16x32_bf16 v[86:89], v[152:155], v[192:195], v[86:89]
	v_mfma_f32_16x16x32_bf16 v[86:89], v[156:159], v[196:199], v[86:89]
	v_mfma_f32_16x16x32_bf16 v[70:73], v[152:155], v[200:203], v[70:73]
	v_mfma_f32_16x16x32_bf16 v[70:73], v[156:159], v[204:207], v[70:73]
	v_mfma_f32_16x16x32_bf16 v[114:117], v[160:163], v[176:179], v[114:117]
	v_mfma_f32_16x16x32_bf16 v[114:117], v[172:175], v[180:183], v[114:117]
	v_mfma_f32_16x16x32_bf16 v[98:101], v[160:163], v[184:187], v[98:101]
	v_mfma_f32_16x16x32_bf16 v[98:101], v[172:175], v[188:191], v[98:101]
	v_mfma_f32_16x16x32_bf16 v[82:85], v[160:163], v[192:195], v[82:85]
	v_mfma_f32_16x16x32_bf16 v[82:85], v[172:175], v[196:199], v[82:85]
	v_mfma_f32_16x16x32_bf16 v[66:69], v[160:163], v[200:203], v[66:69]
	v_mfma_f32_16x16x32_bf16 v[66:69], v[172:175], v[204:207], v[66:69]
	s_barrier
	s_add_i32 s8, s27, s0
	v_lshl_add_u64 v[164:165], v[164:165], 0, s[62:63]
	s_mov_b32 m0, s8
	ds_read_b128 v[176:179], v231 offset:49152
	ds_read_b128 v[180:183], v231 offset:50176
	ds_read_b128 v[184:187], v231 offset:51200
	ds_read_b128 v[188:191], v231 offset:52224
	ds_read_b128 v[192:195], v231 offset:53248
	ds_read_b128 v[196:199], v231 offset:54272
	ds_read_b128 v[200:203], v231 offset:55296
	ds_read_b128 v[204:207], v231 offset:56320
	global_load_lds_dwordx4 v[164:165], off
	v_lshl_add_u64 v[164:165], v[168:169], 0, s[62:63]
	s_add_i32 m0, s8, 0x2000
	s_add_i32 s8, s31, s0
	global_load_lds_dwordx4 v[164:165], off
	v_lshl_add_u64 v[164:165], v[170:171], 0, s[62:63]
	s_mov_b32 m0, s8
	s_nop 0
	global_load_lds_dwordx4 v[164:165], off
	v_lshl_add_u64 v[164:165], v[208:209], 0, s[62:63]
	s_add_i32 m0, s8, 0x2000
	s_nop 0
	global_load_lds_dwordx4 v[164:165], off
	v_lshl_add_u64 v[164:165], v[210:211], 0, v[244:245]
	s_mov_b32 m0, s17
	s_nop 0
	global_load_lds_dwordx4 v[164:165], off
	v_lshl_add_u64 v[164:165], v[212:213], 0, v[244:245]
	s_mov_b32 m0, s18
	s_nop 0
	global_load_lds_dwordx4 v[164:165], off
	s_waitcnt vmcnt(8)
	s_waitcnt lgkmcnt(0)
	s_barrier
	s_waitcnt lgkmcnt(0)
	v_mfma_f32_16x16x32_bf16 v[62:65], v[136:139], v[176:179], v[62:65]
	v_mfma_f32_16x16x32_bf16 v[62:65], v[140:143], v[180:183], v[62:65]
	v_mfma_f32_16x16x32_bf16 v[46:49], v[136:139], v[184:187], v[46:49]
	v_mfma_f32_16x16x32_bf16 v[46:49], v[140:143], v[188:191], v[46:49]
	v_mfma_f32_16x16x32_bf16 v[30:33], v[136:139], v[192:195], v[30:33]
	v_mfma_f32_16x16x32_bf16 v[30:33], v[140:143], v[196:199], v[30:33]
	v_mfma_f32_16x16x32_bf16 v[14:17], v[136:139], v[200:203], v[14:17]
	v_mfma_f32_16x16x32_bf16 v[14:17], v[140:143], v[204:207], v[14:17]
	v_mfma_f32_16x16x32_bf16 v[58:61], v[144:147], v[176:179], v[58:61]
	v_mfma_f32_16x16x32_bf16 v[58:61], v[148:151], v[180:183], v[58:61]
	v_mfma_f32_16x16x32_bf16 v[42:45], v[144:147], v[184:187], v[42:45]
	v_mfma_f32_16x16x32_bf16 v[42:45], v[148:151], v[188:191], v[42:45]
	v_mfma_f32_16x16x32_bf16 v[26:29], v[144:147], v[192:195], v[26:29]
	v_mfma_f32_16x16x32_bf16 v[26:29], v[148:151], v[196:199], v[26:29]
	v_mfma_f32_16x16x32_bf16 v[10:13], v[144:147], v[200:203], v[10:13]
	v_mfma_f32_16x16x32_bf16 v[10:13], v[148:151], v[204:207], v[10:13]
	v_mfma_f32_16x16x32_bf16 v[54:57], v[152:155], v[176:179], v[54:57]
	v_mfma_f32_16x16x32_bf16 v[54:57], v[156:159], v[180:183], v[54:57]
	v_mfma_f32_16x16x32_bf16 v[38:41], v[152:155], v[184:187], v[38:41]
	v_mfma_f32_16x16x32_bf16 v[38:41], v[156:159], v[188:191], v[38:41]
	v_mfma_f32_16x16x32_bf16 v[22:25], v[152:155], v[192:195], v[22:25]
	v_mfma_f32_16x16x32_bf16 v[22:25], v[156:159], v[196:199], v[22:25]
	v_mfma_f32_16x16x32_bf16 v[6:9], v[152:155], v[200:203], v[6:9]
	v_mfma_f32_16x16x32_bf16 v[6:9], v[156:159], v[204:207], v[6:9]
	v_mfma_f32_16x16x32_bf16 v[50:53], v[160:163], v[176:179], v[50:53]
	v_mfma_f32_16x16x32_bf16 v[50:53], v[172:175], v[180:183], v[50:53]
	v_mfma_f32_16x16x32_bf16 v[34:37], v[160:163], v[184:187], v[34:37]
	v_mfma_f32_16x16x32_bf16 v[34:37], v[172:175], v[188:191], v[34:37]
	v_mfma_f32_16x16x32_bf16 v[18:21], v[160:163], v[192:195], v[18:21]
	v_mfma_f32_16x16x32_bf16 v[18:21], v[172:175], v[196:199], v[18:21]
	v_mfma_f32_16x16x32_bf16 v[2:5], v[160:163], v[200:203], v[2:5]
	v_mfma_f32_16x16x32_bf16 v[2:5], v[172:175], v[204:207], v[2:5]
	s_barrier
	s_add_u32 s10, s10, 0x100
	s_addc_u32 s11, s11, 0
	s_add_u32 s6, s6, 0x400000
	s_addc_u32 s7, s7, 0
	s_cmp_ge_i32 s25, s13
	s_mov_b32 s8, s25
	s_cbranch_scc0 .LBB0_752
